# dense attention loop v4: conflict-free K swizzle, K prefetch across barrier, loads and LDS writes spread over MFMA gaps
# speedup vs baseline: 1.0580x; 1.0194x over previous
;     ...
;     const int sq = qs0 + wid * QBLK + r32;
; #pragma unroll
;     for (int aa = 0; aa < 2; ++aa) { const float pos = (float)(aa == 0 ? (sq >> 6) : (sq & 63));
; #pragma unroll
;       for (int dd = 0; dd < 2; ++dd) { const int d0 = aa * 4 + dd;
; #pragma unroll
;         for (int j = 0; j < 8; ++j) { const int i = 16 * dd + 8 * hi + j; const int e1 = aa * 64 + i;
;           const float rev = pos * exp2f(-(float)i * 0.41524101186092029f) * 0.15915494309189535f;
;           const float sn = __builtin_amdgcn_sinf(rev), cs = __builtin_amdgcn_cosf(rev);
; __global__ void __launch_bounds__(NWAVES * 64, 2) mk_fwd(Args args) {
;     ...
;                 const int u = u0 + k * ustep;
;                 if (k < nA && u < uend) {
;                     const int combo = u >> 8, b = combo >> 1, kvh = combo & 1, hq = kvh * 4 + ((u >> 6) & 3), qb = u & 63;
;                     const size_t rowq = (size_t)b * SEQ + (size_t)qb * 256;
;                     att::attn_unit<0, true>(P + rowq * INW + O_QA + hq * 128, INW, P + (size_t)b * SEQ * INW + O_KA + kvh * 128, P + (size_t)b * SEQ * INW + O_VA + kvh * 128, INW,
;                                       (att::bf16*)MIX + rowq * DM + hq * 128, DM, SEQ / 64, (char*)lds, 0, 0, nullptr, nullptr, 0, args.in[I_QN], qb * 256);
.LBB0_484:
	s_mul_i32 s0, s19, s51
	s_add_i32 s0, s35, s0
	s_cmp_lt_i32 s51, s60
	s_cselect_b64 s[2:3], -1, 0
	s_cmp_lt_i32 s0, s31
	s_cselect_b64 s[4:5], -1, 0
	s_and_b64 s[2:3], s[2:3], s[4:5]
	s_andn2_b64 vcc, exec, s[2:3]
	s_cbranch_vccnz .LBB0_478
	s_ashr_i32 s2, s0, 9
	s_ashr_i32 s3, s2, 31
	s_lshl_b64 s[20:21], s[2:3], 14
	s_lshl_b32 s3, s0, 8
	s_and_b32 s39, s3, 0x3f00
	s_or_b32 s20, s20, s39
	s_bfe_u32 s1, s0, 0x10008
	s_mul_i32 s3, s21, 0x5400
	s_mul_hi_u32 s5, s20, 0x5400
	s_lshl_b32 s4, s1, 8
	s_add_i32 s5, s5, s3
	s_mul_i32 s3, s20, 0x5400
	s_add_u32 s3, s64, s3
	s_addc_u32 s5, s65, s5
	s_lshl_b32 s0, s0, 1
	s_lshl_b32 s1, s1, 9
	s_and_b32 s0, s0, 0x180
	s_or_b32 s14, s1, s0
	s_lshl_b32 s0, s14, 1
	s_add_u32 s0, s3, s0
	s_addc_u32 s1, s5, 0
	s_mul_i32 s28, s2, 0x15000000
	s_mul_hi_i32 s5, s2, 0x15000000
	s_add_u32 s2, s64, s28
	s_addc_u32 s3, s65, s5
	v_mov_b32_e32 v230, v218
	s_add_u32 s2, s2, s4
	s_addc_u32 s3, s3, 0
	v_readfirstlane_b32 s29, v230
	s_ashr_i32 s42, s29, 1
	v_mov_b32_e32 v0, s42
	v_bfe_u32 v229, v230, 5, 1
	v_bfi_b32 v2, s72, v0, v230
	v_mov_b64_e32 v[0:1], s[0:1]
	s_movk_i32 s0, 0x5400
	v_mad_i64_i32 v[0:1], s[0:1], v2, s0, v[0:1]
	v_lshlrev_b32_e32 v164, 4, v229
	v_and_b32_e32 v228, 31, v230
	v_lshl_add_u64 v[0:1], v[0:1], 0, v[164:165]
	s_and_b32 s38, s42, 0xffffffe0
	global_load_dwordx4 v[56:59], v[0:1], off
	global_load_dwordx4 v[72:75], v[0:1], off offset:32
	global_load_dwordx4 v[60:63], v[0:1], off offset:64
	global_load_dwordx4 v[76:79], v[0:1], off offset:96
	global_load_dwordx4 v[80:83], v[0:1], off offset:128
	global_load_dwordx4 v[88:91], v[0:1], off offset:160
	global_load_dwordx4 v[84:87], v[0:1], off offset:192
	global_load_dwordx4 v[92:95], v[0:1], off offset:224
	v_or_b32_e32 v0, s39, v228
	v_lshlrev_b32_e32 v20, 3, v229
	v_add_u32_e32 v0, s38, v0
	v_ashrrev_i32_e32 v1, 6, v0
	v_and_b32_e32 v40, 63, v0
	v_cvt_f32_ubyte0_e32 v0, v20
	v_or_b32_e32 v4, 1, v20
	v_mul_f32_e32 v2, 0xbed49a78, v0
	v_cvt_f32_ubyte0_e32 v4, v4
	v_cmp_gt_f32_e32 vcc, s74, v2
	v_mul_f32_e32 v5, 0xbed49a78, v4
	v_cvt_f32_i32_e32 v41, v1
	v_cndmask_b32_e32 v2, 0, v225, vcc
	v_cndmask_b32_e32 v1, 0, v226, vcc
	v_cmp_gt_f32_e32 vcc, s74, v5
	v_or_b32_e32 v16, 16, v20
	v_cvt_f32_ubyte0_e32 v16, v16
	v_cndmask_b32_e32 v5, 0, v225, vcc
	v_fmac_f32_e32 v5, 0xbed49a78, v4
	v_exp_f32_e32 v17, v5
	v_cndmask_b32_e32 v18, 0, v226, vcc
	v_or_b32_e32 v21, 17, v20
	v_cvt_f32_ubyte0_e32 v21, v21
	v_ldexp_f32 v118, v17, v18
	v_or_b32_e32 v18, 2, v20
	v_cvt_f32_ubyte0_e32 v18, v18
	v_mul_f32_e32 v19, 0xbed49a78, v18
	v_cmp_gt_f32_e32 vcc, s74, v19
	v_mul_f32_e32 v17, v118, v41
	v_mul_f32_e32 v17, 0.15915494, v17
	v_cndmask_b32_e32 v19, 0, v225, vcc
	v_fmac_f32_e32 v19, 0xbed49a78, v18
	v_exp_f32_e32 v18, v19
	v_sin_f32_e32 v99, v17
	v_cos_f32_e32 v98, v17
	v_cndmask_b32_e32 v17, 0, v226, vcc
	v_ldexp_f32 v119, v18, v17
	v_or_b32_e32 v18, 3, v20
	v_cvt_f32_ubyte0_e32 v18, v18
	v_mul_f32_e32 v19, 0xbed49a78, v18
	v_cmp_gt_f32_e32 vcc, s74, v19
	v_mul_f32_e32 v17, v119, v41
	v_mul_f32_e32 v17, 0.15915494, v17
	v_cndmask_b32_e32 v19, 0, v225, vcc
	v_fmac_f32_e32 v19, 0xbed49a78, v18
	v_exp_f32_e32 v18, v19
	v_sin_f32_e32 v100, v17
	v_cos_f32_e32 v101, v17
	v_cndmask_b32_e32 v17, 0, v226, vcc
	v_ldexp_f32 v120, v18, v17
	v_or_b32_e32 v18, 4, v20
	v_cvt_f32_ubyte0_e32 v18, v18
	v_mul_f32_e32 v19, 0xbed49a78, v18
	v_cmp_gt_f32_e32 vcc, s74, v19
	v_mul_f32_e32 v17, v120, v41
	v_mul_f32_e32 v17, 0.15915494, v17
	v_cndmask_b32_e32 v19, 0, v225, vcc
	v_fmac_f32_e32 v19, 0xbed49a78, v18
	v_exp_f32_e32 v18, v19
	v_sin_f32_e32 v103, v17
	v_cos_f32_e32 v102, v17
	v_cndmask_b32_e32 v17, 0, v226, vcc
	v_ldexp_f32 v121, v18, v17
	v_or_b32_e32 v18, 5, v20
	v_cvt_f32_ubyte0_e32 v18, v18
	v_mul_f32_e32 v19, 0xbed49a78, v18
	v_cmp_gt_f32_e32 vcc, s74, v19
	v_mul_f32_e32 v17, v121, v41
	v_mul_f32_e32 v17, 0.15915494, v17
	v_cndmask_b32_e32 v19, 0, v225, vcc
	v_fmac_f32_e32 v19, 0xbed49a78, v18
	v_exp_f32_e32 v18, v19
	v_sin_f32_e32 v104, v17
	v_cos_f32_e32 v105, v17
	v_cndmask_b32_e32 v17, 0, v226, vcc
	v_ldexp_f32 v124, v18, v17
	v_or_b32_e32 v18, 6, v20
	v_cvt_f32_ubyte0_e32 v18, v18
	v_mul_f32_e32 v19, 0xbed49a78, v18
	v_cmp_gt_f32_e32 vcc, s74, v19
	v_mul_f32_e32 v17, v124, v41
	v_mul_f32_e32 v17, 0.15915494, v17
	v_cndmask_b32_e32 v19, 0, v225, vcc
	v_fmac_f32_e32 v19, 0xbed49a78, v18
	v_exp_f32_e32 v18, v19
	v_sin_f32_e32 v107, v17
	v_cos_f32_e32 v106, v17
	v_cndmask_b32_e32 v17, 0, v226, vcc
	v_ldexp_f32 v125, v18, v17
	v_or_b32_e32 v18, 7, v20
	v_cvt_f32_ubyte0_e32 v18, v18
	v_mul_f32_e32 v19, 0xbed49a78, v18
	v_cmp_gt_f32_e32 vcc, s74, v19
	v_mul_f32_e32 v17, v125, v41
	v_mul_f32_e32 v17, 0.15915494, v17
	v_cndmask_b32_e32 v19, 0, v225, vcc
	v_fmac_f32_e32 v19, 0xbed49a78, v18
	v_exp_f32_e32 v18, v19
	v_sin_f32_e32 v108, v17
	v_cos_f32_e32 v109, v17
	v_cndmask_b32_e32 v17, 0, v226, vcc
	v_ldexp_f32 v128, v18, v17
	v_mul_f32_e32 v17, v128, v41
	v_mul_f32_e32 v18, 0xbed49a78, v16
	v_mul_f32_e32 v17, 0.15915494, v17
	v_cmp_gt_f32_e32 vcc, s74, v18
	v_mul_f32_e32 v22, 0xbed49a78, v21
	v_sin_f32_e32 v113, v17
	v_cndmask_b32_e32 v18, 0, v225, vcc
	v_cos_f32_e32 v112, v17
	v_cndmask_b32_e32 v17, 0, v226, vcc
	v_cmp_gt_f32_e32 vcc, s74, v22
	v_fmac_f32_e32 v2, 0xbed49a78, v0
	v_fmac_f32_e32 v18, 0xbed49a78, v16
	v_cndmask_b32_e32 v22, 0, v225, vcc
	v_fmac_f32_e32 v22, 0xbed49a78, v21
	v_exp_f32_e32 v21, v22
	v_cndmask_b32_e32 v22, 0, v226, vcc
	v_exp_f32_e32 v0, v2
	v_exp_f32_e32 v16, v18
	v_ldexp_f32 v130, v21, v22
	v_or_b32_e32 v22, 18, v20
	v_cvt_f32_ubyte0_e32 v22, v22
	v_mul_f32_e32 v23, 0xbed49a78, v22
	v_cmp_gt_f32_e32 vcc, s74, v23
;     ...
;     for (int aa = 0; aa < 2; ++aa) { const float pos = (float)(aa == 0 ? (sq >> 6) : (sq & 63));
; #pragma unroll
;       for (int dd = 0; dd < 2; ++dd) { const int d0 = aa * 4 + dd;
; #pragma unroll
;         for (int j = 0; j < 8; ++j) { const int i = 16 * dd + 8 * hi + j; const int e1 = aa * 64 + i;
;           const float rev = pos * exp2f(-(float)i * 0.41524101186092029f) * 0.15915494309189535f;
;           const float sn = __builtin_amdgcn_sinf(rev), cs = __builtin_amdgcn_cosf(rev);
;           const float y1 = x[d0][j] * rstd * qgain[e1], y2 = x[d0 + 2][j] * rstd * qgain[e1 + 32];
	v_mul_f32_e32 v21, v130, v41
	v_mul_f32_e32 v21, 0.15915494, v21
	v_cndmask_b32_e32 v23, 0, v225, vcc
	v_fmac_f32_e32 v23, 0xbed49a78, v22
	v_exp_f32_e32 v22, v23
	v_sin_f32_e32 v115, v21
	v_cos_f32_e32 v114, v21
	v_cndmask_b32_e32 v21, 0, v226, vcc
	v_ldexp_f32 v131, v22, v21
	v_or_b32_e32 v22, 19, v20
	v_cvt_f32_ubyte0_e32 v22, v22
	v_mul_f32_e32 v23, 0xbed49a78, v22
	v_cmp_gt_f32_e32 vcc, s74, v23
	v_mul_f32_e32 v21, v131, v41
	v_mul_f32_e32 v21, 0.15915494, v21
	v_cndmask_b32_e32 v23, 0, v225, vcc
	v_fmac_f32_e32 v23, 0xbed49a78, v22
	v_exp_f32_e32 v22, v23
	v_sin_f32_e32 v116, v21
	v_cos_f32_e32 v117, v21
	v_cndmask_b32_e32 v21, 0, v226, vcc
	v_ldexp_f32 v132, v22, v21
	v_or_b32_e32 v22, 20, v20
	v_cvt_f32_ubyte0_e32 v22, v22
	v_mul_f32_e32 v23, 0xbed49a78, v22
	v_cmp_gt_f32_e32 vcc, s74, v23
	v_mul_f32_e32 v21, v132, v41
	v_mul_f32_e32 v21, 0.15915494, v21
	v_cndmask_b32_e32 v23, 0, v225, vcc
	v_fmac_f32_e32 v23, 0xbed49a78, v22
	v_exp_f32_e32 v22, v23
	v_sin_f32_e32 v123, v21
	v_cos_f32_e32 v122, v21
	v_cndmask_b32_e32 v21, 0, v226, vcc
	v_ldexp_f32 v133, v22, v21
	v_or_b32_e32 v22, 21, v20
	v_cvt_f32_ubyte0_e32 v22, v22
	v_mul_f32_e32 v23, 0xbed49a78, v22
	v_cmp_gt_f32_e32 vcc, s74, v23
	v_mul_f32_e32 v21, v133, v41
	v_mul_f32_e32 v21, 0.15915494, v21
	v_cndmask_b32_e32 v23, 0, v225, vcc
	v_fmac_f32_e32 v23, 0xbed49a78, v22
	v_exp_f32_e32 v22, v23
	v_sin_f32_e32 v126, v21
	v_cos_f32_e32 v127, v21
	v_cndmask_b32_e32 v21, 0, v226, vcc
	v_ldexp_f32 v134, v22, v21
	v_or_b32_e32 v22, 22, v20
	v_cvt_f32_ubyte0_e32 v22, v22
	v_mul_f32_e32 v23, 0xbed49a78, v22
	v_cmp_gt_f32_e32 vcc, s74, v23
	v_mul_f32_e32 v21, v134, v41
	v_mul_f32_e32 v21, 0.15915494, v21
	v_cndmask_b32_e32 v23, 0, v225, vcc
	v_fmac_f32_e32 v23, 0xbed49a78, v22
	v_exp_f32_e32 v22, v23
	v_sin_f32_e32 v137, v21
	v_cos_f32_e32 v136, v21
	v_cndmask_b32_e32 v21, 0, v226, vcc
	v_ldexp_f32 v135, v22, v21
	v_or_b32_e32 v20, 23, v20
	v_mul_f32_e32 v21, v135, v41
	v_cvt_f32_ubyte0_e32 v20, v20
	v_ldexp_f32 v42, v0, v1
	v_ldexp_f32 v129, v16, v17
	v_mul_f32_e32 v43, 0.15915494, v21
	v_mul_f32_e32 v21, 0xbed49a78, v20
	v_mul_f32_e32 v0, v42, v41
	v_mul_f32_e32 v16, v129, v41
	v_cmp_gt_f32_e32 vcc, s74, v21
	v_mul_f32_e32 v0, 0.15915494, v0
	v_and_b32_e32 v68, 32, v230
	v_mul_f32_e32 v16, 0.15915494, v16
	v_cndmask_b32_e32 v44, 0, v225, vcc
	v_sin_f32_e32 v96, v0
	v_cos_f32_e32 v97, v0
	global_load_dwordx4 v[0:3], v68, s[36:37] offset:16
	global_load_dwordx4 v[8:11], v68, s[36:37]
	global_load_dwordx4 v[4:7], v68, s[36:37] offset:144
	global_load_dwordx4 v[12:15], v68, s[36:37] offset:128
	v_sin_f32_e32 v110, v16
	v_cos_f32_e32 v111, v16
	global_load_dwordx4 v[16:19], v68, s[36:37] offset:80
	global_load_dwordx4 v[32:35], v68, s[36:37] offset:64
	global_load_dwordx4 v[28:31], v68, s[36:37] offset:208
	global_load_dwordx4 v[36:39], v68, s[36:37] offset:192
	v_fmac_f32_e32 v44, 0xbed49a78, v20
	global_load_dwordx4 v[20:23], v68, s[36:37] offset:336
	global_load_dwordx4 v[24:27], v68, s[36:37] offset:464
	v_cvt_f32_ubyte0_e32 v151, v40
	v_mul_f32_e32 v118, v118, v151
	v_mul_f32_e32 v118, 0.15915494, v118
	v_sin_f32_e32 v163, v118
	v_cos_f32_e32 v162, v118
	v_mul_f32_e32 v118, v119, v151
	v_mul_f32_e32 v118, 0.15915494, v118
	v_sin_f32_e32 v160, v118
	v_cos_f32_e32 v161, v118
	v_mul_f32_e32 v118, v120, v151
	v_mul_f32_e32 v118, 0.15915494, v118
	v_sin_f32_e32 v159, v118
	v_cos_f32_e32 v158, v118
	v_mul_f32_e32 v118, v121, v151
	v_mul_f32_e32 v118, 0.15915494, v118
	v_sin_f32_e32 v156, v118
	v_cos_f32_e32 v157, v118
	v_mul_f32_e32 v118, v124, v151
	v_mul_f32_e32 v118, 0.15915494, v118
	v_sin_f32_e32 v153, v118
	v_cos_f32_e32 v152, v118
	v_mul_f32_e32 v118, v125, v151
	v_mul_f32_e32 v118, 0.15915494, v118
	v_sin_f32_e32 v148, v118
	v_cos_f32_e32 v149, v118
	v_mul_f32_e32 v118, v128, v151
	v_mul_f32_e32 v118, 0.15915494, v118
	v_sin_f32_e32 v147, v118
	v_cos_f32_e32 v146, v118
	v_mul_f32_e32 v118, v129, v151
	v_mul_f32_e32 v118, 0.15915494, v118
	v_sin_f32_e32 v144, v118
	v_cos_f32_e32 v145, v118
	v_mul_f32_e32 v118, v130, v151
	v_mul_f32_e32 v118, 0.15915494, v118
	v_sin_f32_e32 v143, v118
	v_cos_f32_e32 v142, v118
	v_mul_f32_e32 v118, v131, v151
	v_mul_f32_e32 v118, 0.15915494, v118
	v_sin_f32_e32 v140, v118
	v_cos_f32_e32 v141, v118
	v_mul_f32_e32 v118, v132, v151
	v_exp_f32_e32 v44, v44
	v_mul_f32_e32 v118, 0.15915494, v118
	v_sin_f32_e32 v139, v118
	v_cos_f32_e32 v138, v118
	v_mul_f32_e32 v118, v133, v151
	v_mul_f32_e32 v118, 0.15915494, v118
	v_sin_f32_e32 v174, v43
	v_cos_f32_e32 v175, v43
	v_cndmask_b32_e32 v43, 0, v226, vcc
	v_sin_f32_e32 v132, v118
	v_cos_f32_e32 v133, v118
	v_mul_f32_e32 v118, v134, v151
	v_ldexp_f32 v150, v44, v43
	v_mul_f32_e32 v118, 0.15915494, v118
	v_mul_f32_e32 v40, v42, v151
	v_sin_f32_e32 v125, v118
	v_cos_f32_e32 v124, v118
	v_mul_f32_e32 v118, v135, v151
	s_waitcnt vmcnt(0)
;     ...
;     for (int d0 = 0; d0 < 8; ++d0)
; #pragma unroll
;       for (int j = 0; j < 8; ++j) { x[d0][j] = __builtin_bit_cast(float, (unsigned)(unsigned short)qr[d0][j] << 16); ssq += x[d0][j] * x[d0][j]; }
;     { auto rr = __builtin_amdgcn_permlane32_swap(__float_as_uint(ssq), __float_as_uint(ssq), false, false); ssq = __uint_as_float(rr[0]) + __uint_as_float(rr[1]); }
	v_lshlrev_b32_e32 v128, 16, v91
	v_and_b32_e32 v134, 0xffff0000, v91
	v_and_b32_e32 v91, 0xffff0000, v94
	v_lshlrev_b32_e32 v170, 16, v89
	v_lshlrev_b32_e32 v177, 16, v92
	v_lshlrev_b32_e32 v180, 16, v83
	v_lshlrev_b32_e32 v185, 16, v86
	v_lshlrev_b32_e32 v188, 16, v81
	v_lshlrev_b32_e32 v193, 16, v84
	v_lshlrev_b32_e32 v196, 16, v75
	v_lshlrev_b32_e32 v201, 16, v78
	v_lshlrev_b32_e32 v204, 16, v73
	v_lshlrev_b32_e32 v209, 16, v76
	v_lshlrev_b32_e32 v214, 16, v59
	v_lshlrev_b32_e32 v233, 16, v62
	v_and_b32_e32 v234, 0xffff0000, v57
	v_lshlrev_b32_e32 v236, 16, v56
	v_and_b32_e32 v56, 0xffff0000, v56
	v_mov_b32_e32 v130, v22
	v_mul_f32_e32 v22, v150, v151
	v_lshlrev_b32_e32 v151, 16, v94
	v_and_b32_e32 v94, 0xffff0000, v89
	v_and_b32_e32 v89, 0xffff0000, v92
	v_and_b32_e32 v92, 0xffff0000, v83
	v_and_b32_e32 v83, 0xffff0000, v86
	v_and_b32_e32 v86, 0xffff0000, v81
	v_and_b32_e32 v81, 0xffff0000, v84
	v_and_b32_e32 v84, 0xffff0000, v75
	v_and_b32_e32 v75, 0xffff0000, v78
	v_and_b32_e32 v78, 0xffff0000, v73
	v_and_b32_e32 v73, 0xffff0000, v76
	v_and_b32_e32 v76, 0xffff0000, v59
	v_and_b32_e32 v59, 0xffff0000, v62
	v_lshlrev_b32_e32 v62, 16, v57
	v_and_b32_e32 v57, 0xffff0000, v60
	v_lshlrev_b32_e32 v129, 16, v95
	v_and_b32_e32 v135, 0xffff0000, v95
	v_lshlrev_b32_e32 v171, 16, v93
	v_and_b32_e32 v95, 0xffff0000, v93
	v_lshlrev_b32_e32 v181, 16, v87
	v_and_b32_e32 v93, 0xffff0000, v87
	v_lshlrev_b32_e32 v189, 16, v85
	v_and_b32_e32 v87, 0xffff0000, v85
	v_lshlrev_b32_e32 v197, 16, v79
	v_and_b32_e32 v85, 0xffff0000, v79
	v_lshlrev_b32_e32 v205, 16, v77
	v_and_b32_e32 v79, 0xffff0000, v77
	v_lshlrev_b32_e32 v215, 16, v63
	v_and_b32_e32 v77, 0xffff0000, v63
	v_lshlrev_b32_e32 v63, 16, v61
	v_and_b32_e32 v235, 0xffff0000, v61
	v_lshlrev_b32_e32 v237, 16, v60
	v_pk_mul_f32 v[60:61], v[56:57], v[56:57]
	v_lshlrev_b32_e32 v232, 16, v58
	v_pk_fma_f32 v[238:239], v[236:237], v[236:237], v[60:61]
	v_and_b32_e32 v58, 0xffff0000, v58
	v_pk_fma_f32 v[238:239], v[62:63], v[62:63], v[238:239]
	v_lshlrev_b32_e32 v208, 16, v72
	v_pk_fma_f32 v[238:239], v[234:235], v[234:235], v[238:239]
	v_and_b32_e32 v72, 0xffff0000, v72
	v_pk_fma_f32 v[238:239], v[232:233], v[232:233], v[238:239]
	v_lshlrev_b32_e32 v200, 16, v74
	v_pk_fma_f32 v[238:239], v[58:59], v[58:59], v[238:239]
	v_and_b32_e32 v74, 0xffff0000, v74
	v_pk_fma_f32 v[238:239], v[214:215], v[214:215], v[238:239]
	v_mov_b32_e32 v216, v2
	v_pk_fma_f32 v[238:239], v[76:77], v[76:77], v[238:239]
	v_mul_f32_e32 v2, v237, v237
	v_pk_fma_f32 v[238:239], v[208:209], v[208:209], v[238:239]
	v_lshlrev_b32_e32 v192, 16, v80
	v_pk_fma_f32 v[238:239], v[72:73], v[72:73], v[238:239]
	v_and_b32_e32 v80, 0xffff0000, v80
	v_pk_fma_f32 v[238:239], v[204:205], v[204:205], v[238:239]
	v_lshlrev_b32_e32 v184, 16, v82
	v_pk_fma_f32 v[238:239], v[78:79], v[78:79], v[238:239]
	v_and_b32_e32 v82, 0xffff0000, v82
	v_pk_fma_f32 v[238:239], v[200:201], v[200:201], v[238:239]
	v_lshlrev_b32_e32 v176, 16, v88
	v_pk_fma_f32 v[238:239], v[74:75], v[74:75], v[238:239]
	v_and_b32_e32 v88, 0xffff0000, v88
	v_pk_fma_f32 v[238:239], v[196:197], v[196:197], v[238:239]
	v_mul_f32_e32 v41, v150, v41
	v_pk_fma_f32 v[238:239], v[84:85], v[84:85], v[238:239]
	v_lshlrev_b32_e32 v150, 16, v90
	v_pk_add_f32 v[238:239], v[2:3], v[238:239] op_sel_hi:[0,1]
	v_pk_add_f32 v[60:61], v[60:61], v[238:239] op_sel:[1,0] op_sel_hi:[0,1]
	v_mul_f32_e32 v2, v63, v63
	v_pk_add_f32 v[60:61], v[2:3], v[60:61] op_sel_hi:[0,1]
	v_mul_f32_e32 v2, v235, v235
	v_pk_add_f32 v[60:61], v[2:3], v[60:61] op_sel_hi:[0,1]
	v_mul_f32_e32 v2, v233, v233
	v_pk_add_f32 v[60:61], v[2:3], v[60:61] op_sel_hi:[0,1]
	v_mul_f32_e32 v2, v59, v59
	v_pk_add_f32 v[60:61], v[2:3], v[60:61] op_sel_hi:[0,1]
	v_mul_f32_e32 v2, v215, v215
	v_pk_add_f32 v[60:61], v[2:3], v[60:61] op_sel_hi:[0,1]
	v_mul_f32_e32 v2, v77, v77
	v_pk_add_f32 v[60:61], v[2:3], v[60:61] op_sel_hi:[0,1]
	v_mul_f32_e32 v2, v209, v209
	v_pk_add_f32 v[60:61], v[2:3], v[60:61] op_sel_hi:[0,1]
	v_mul_f32_e32 v2, v73, v73
	v_pk_add_f32 v[60:61], v[2:3], v[60:61] op_sel_hi:[0,1]
	v_mul_f32_e32 v2, v205, v205
	v_pk_add_f32 v[60:61], v[2:3], v[60:61] op_sel_hi:[0,1]
	v_mul_f32_e32 v2, v79, v79
	v_pk_add_f32 v[60:61], v[2:3], v[60:61] op_sel_hi:[0,1]
	v_mul_f32_e32 v2, v201, v201
	v_pk_add_f32 v[60:61], v[2:3], v[60:61] op_sel_hi:[0,1]
	v_mul_f32_e32 v2, v75, v75
	v_pk_add_f32 v[60:61], v[2:3], v[60:61] op_sel_hi:[0,1]
	v_mul_f32_e32 v2, v197, v197
	v_pk_add_f32 v[60:61], v[2:3], v[60:61] op_sel_hi:[0,1]
	v_mul_f32_e32 v2, v85, v85
	v_pk_add_f32 v[60:61], v[2:3], v[60:61] op_sel_hi:[0,1]
	v_pk_fma_f32 v[60:61], v[192:193], v[192:193], v[60:61]
	v_and_b32_e32 v90, 0xffff0000, v90
	v_pk_fma_f32 v[60:61], v[80:81], v[80:81], v[60:61]
	v_mul_f32_e32 v2, v193, v193
	v_pk_fma_f32 v[60:61], v[188:189], v[188:189], v[60:61]
	v_mul_f32_e32 v41, 0.15915494, v41
	v_pk_fma_f32 v[60:61], v[86:87], v[86:87], v[60:61]
	v_mul_f32_e32 v40, 0.15915494, v40
	v_pk_fma_f32 v[60:61], v[184:185], v[184:185], v[60:61]
	v_sin_f32_e32 v169, v41
	v_pk_fma_f32 v[60:61], v[82:83], v[82:83], v[60:61]
	v_cos_f32_e32 v168, v41
	v_pk_fma_f32 v[60:61], v[180:181], v[180:181], v[60:61]
	v_sin_f32_e32 v166, v40
	v_pk_fma_f32 v[60:61], v[92:93], v[92:93], v[60:61]
	v_cos_f32_e32 v167, v40
	v_pk_fma_f32 v[60:61], v[176:177], v[176:177], v[60:61]
	global_load_dwordx4 v[48:51], v68, s[36:37] offset:272
	global_load_dwordx4 v[64:67], v68, s[36:37] offset:256
	global_load_dwordx4 v[44:47], v68, s[36:37] offset:320
	global_load_dwordx4 v[40:43], v68, s[36:37] offset:448
	global_load_dwordx4 v[52:55], v68, s[36:37] offset:400
	s_nop 0
	global_load_dwordx4 v[68:71], v68, s[36:37] offset:384
;     ...
;     { auto rr = __builtin_amdgcn_permlane32_swap(__float_as_uint(ssq), __float_as_uint(ssq), false, false); ssq = __uint_as_float(rr[0]) + __uint_as_float(rr[1]); }
;     const float rstd = 1.0f / sqrtf(ssq * (1.0f / 128.0f) + 1e-6f);
;     const int sq = qs0 + wid * QBLK + r32;
; #pragma unroll
;     for (int aa = 0; aa < 2; ++aa) { const float pos = (float)(aa == 0 ? (sq >> 6) : (sq & 63));
; #pragma unroll
;       for (int dd = 0; dd < 2; ++dd) { const int d0 = aa * 4 + dd;
; #pragma unroll
;         for (int j = 0; j < 8; ++j) { const int i = 16 * dd + 8 * hi + j; const int e1 = aa * 64 + i;
;           const float rev = pos * exp2f(-(float)i * 0.41524101186092029f) * 0.15915494309189535f;
;           const float sn = __builtin_amdgcn_sinf(rev), cs = __builtin_amdgcn_cosf(rev);
;           const float y1 = x[d0][j] * rstd * qgain[e1], y2 = x[d0 + 2][j] * rstd * qgain[e1 + 32];
;           x[d0][j] = y1 * cs - y2 * sn; x[d0 + 2][j] = y2 * cs + y1 * sn; } } }
	v_pk_fma_f32 v[60:61], v[88:89], v[88:89], v[60:61]
	v_mov_b32_e32 v212, v135
	v_pk_fma_f32 v[60:61], v[170:171], v[170:171], v[60:61]
	v_mov_b32_e32 v213, v129
	v_pk_fma_f32 v[60:61], v[94:95], v[94:95], v[60:61]
	v_mov_b32_e32 v217, v6
	v_pk_fma_f32 v[60:61], v[150:151], v[150:151], v[60:61]
	v_mov_b32_e32 v6, 0x358637bd
	v_pk_fma_f32 v[60:61], v[90:91], v[90:91], v[60:61]
	s_mov_b32 s0, 0xf800000
	v_pk_fma_f32 v[60:61], v[128:129], v[128:129], v[60:61]
	v_mov_b32_e32 v238, v8
	v_pk_fma_f32 v[60:61], v[134:135], v[134:135], v[60:61]
	v_mov_b32_e32 v239, v12
	v_pk_add_f32 v[60:61], v[2:3], v[60:61] op_sel_hi:[0,1]
	v_mul_f32_e32 v2, v81, v81
	v_pk_add_f32 v[60:61], v[2:3], v[60:61] op_sel_hi:[0,1]
	v_mul_f32_e32 v2, v189, v189
	v_pk_add_f32 v[60:61], v[2:3], v[60:61] op_sel_hi:[0,1]
	v_mul_f32_e32 v2, v87, v87
	v_pk_add_f32 v[60:61], v[2:3], v[60:61] op_sel_hi:[0,1]
	v_mul_f32_e32 v2, v185, v185
	v_pk_add_f32 v[60:61], v[2:3], v[60:61] op_sel_hi:[0,1]
	v_mul_f32_e32 v2, v83, v83
	v_pk_add_f32 v[60:61], v[2:3], v[60:61] op_sel_hi:[0,1]
	v_mul_f32_e32 v2, v181, v181
	v_pk_add_f32 v[60:61], v[2:3], v[60:61] op_sel_hi:[0,1]
	v_mul_f32_e32 v2, v93, v93
	v_pk_add_f32 v[60:61], v[2:3], v[60:61] op_sel_hi:[0,1]
	v_mul_f32_e32 v2, v177, v177
	v_pk_add_f32 v[60:61], v[2:3], v[60:61] op_sel_hi:[0,1]
	v_mul_f32_e32 v2, v89, v89
	v_pk_add_f32 v[60:61], v[2:3], v[60:61] op_sel_hi:[0,1]
	v_mul_f32_e32 v2, v171, v171
	v_pk_add_f32 v[60:61], v[2:3], v[60:61] op_sel_hi:[0,1]
	v_mul_f32_e32 v2, v95, v95
	v_pk_add_f32 v[60:61], v[2:3], v[60:61] op_sel_hi:[0,1]
	v_mul_f32_e32 v2, v151, v151
	v_pk_add_f32 v[60:61], v[2:3], v[60:61] op_sel_hi:[0,1]
	v_mul_f32_e32 v2, v91, v91
	v_pk_add_f32 v[60:61], v[2:3], v[60:61] op_sel_hi:[0,1]
	v_mul_f32_e32 v2, v129, v129
	v_pk_add_f32 v[60:61], v[2:3], v[60:61] op_sel_hi:[0,1]
	v_pk_fma_f32 v[60:61], v[212:213], v[212:213], v[60:61]
	v_mov_b32_e32 v212, v10
	v_mov_b32_e32 v2, v60
	s_nop 1
	v_permlane32_swap_b32_e32 v60, v2
	v_add_f32_e32 v2, v60, v2
	v_fmamk_f32 v2, v2, 0x3c000000, v6
	v_mul_f32_e32 v6, 0x4f800000, v2
	v_cmp_gt_f32_e32 vcc, s0, v2
	v_mov_b32_e32 v60, v0
	v_mov_b32_e32 v61, v4
	v_cndmask_b32_e32 v2, v2, v6, vcc
	v_sqrt_f32_e32 v6, v2
	v_mov_b32_e32 v12, v9
	v_mov_b32_e32 v154, v20
	v_mul_f32_e32 v22, 0.15915494, v22
	v_add_u32_e32 v0, -1, v6
	v_fma_f32 v4, -v0, v6, v2
	v_cmp_ge_f32_e64 s[0:1], 0, v4
	v_add_u32_e32 v4, 1, v6
	v_sin_f32_e32 v121, v22
	v_cndmask_b32_e64 v0, v6, v0, s[0:1]
	v_fma_f32 v6, -v4, v6, v2
	v_cmp_lt_f32_e64 s[0:1], 0, v6
	v_cos_f32_e32 v120, v22
	v_mov_b32_e32 v213, v14
	v_cndmask_b32_e64 v0, v0, v4, s[0:1]
	v_mul_f32_e32 v4, 0x37800000, v0
	v_cndmask_b32_e32 v0, v0, v4, vcc
	v_cmp_class_f32_e32 vcc, v2, v223
	v_mov_b32_e32 v14, v11
	v_mov_b32_e32 v210, v32
	v_cndmask_b32_e32 v0, v0, v2, vcc
	v_div_scale_f32 v2, s[0:1], v0, v0, 1.0
	v_rcp_f32_e32 v4, v2
	v_mov_b32_e32 v206, v34
	v_mov_b32_e32 v211, v36
	s_waitcnt vmcnt(3)
	v_mov_b32_e32 v172, v46
	v_fma_f32 v6, -v2, v4, 1.0
	v_fmac_f32_e32 v4, v6, v4
	v_div_scale_f32 v6, vcc, 1.0, v0, 1.0
	v_mul_f32_e32 v8, v6, v4
	v_fma_f32 v10, -v2, v8, v6
	v_fmac_f32_e32 v8, v10, v4
	v_fma_f32 v2, -v2, v8, v6
	v_div_fmas_f32 v2, v2, v4, v8
	v_div_fixup_f32 v0, v2, v0, 1.0
	v_mul_f32_e32 v0, 0x3e0293ee, v0
	v_pk_mul_f32 v[56:57], v[0:1], v[56:57] op_sel_hi:[0,1]
	v_pk_mul_f32 v[8:9], v[12:13], v[56:57]
	v_mov_b32_e32 v4, v1
	v_pk_mul_f32 v[12:13], v[98:99], v[8:9]
	v_mov_b32_e32 v6, v3
	v_sub_f32_e32 v20, v12, v13
	v_mov_b32_e32 v12, v99
	v_mov_b32_e32 v13, v98
	v_pk_mul_f32 v[8:9], v[12:13], v[8:9]
	v_mov_b32_e32 v12, v101
	v_add_f32_e32 v22, v8, v9
	v_pk_mul_f32 v[8:9], v[0:1], v[62:63] op_sel_hi:[0,1]
	v_pk_mul_f32 v[8:9], v[212:213], v[8:9]
	v_mov_b32_e32 v13, v100
	v_pk_mul_f32 v[12:13], v[12:13], v[8:9]
	v_pk_mul_f32 v[8:9], v[100:101], v[8:9]
	v_sub_f32_e32 v12, v12, v13
	v_add_f32_e32 v13, v8, v9
	v_pk_mul_f32 v[8:9], v[0:1], v[234:235] op_sel_hi:[0,1]
	v_pk_mul_f32 v[8:9], v[14:15], v[8:9]
	v_mov_b32_e32 v36, v33
	v_pk_mul_f32 v[10:11], v[102:103], v[8:9]
	v_mov_b32_e32 v178, v44
	v_sub_f32_e32 v14, v10, v11
	v_mov_b32_e32 v10, v103
	v_mov_b32_e32 v11, v102
	v_pk_mul_f32 v[8:9], v[10:11], v[8:9]
	v_mov_b32_e32 v10, v105
	v_add_f32_e32 v15, v8, v9
	v_pk_mul_f32 v[8:9], v[0:1], v[232:233] op_sel_hi:[0,1]
	v_pk_mul_f32 v[8:9], v[8:9], v[60:61]
	v_mov_b32_e32 v11, v104
	v_pk_mul_f32 v[10:11], v[10:11], v[8:9]
	v_pk_mul_f32 v[8:9], v[104:105], v[8:9]
	v_sub_f32_e32 v10, v10, v11
	v_add_f32_e32 v11, v8, v9
	v_pk_mul_f32 v[8:9], v[0:1], v[58:59] op_sel_hi:[0,1]
	v_pk_mul_f32 v[4:5], v[8:9], v[4:5]
	v_mov_b32_e32 v207, v38
	v_pk_mul_f32 v[8:9], v[106:107], v[4:5]
	v_mov_b32_e32 v186, v48
	v_sub_f32_e32 v32, v8, v9
	v_mov_b32_e32 v8, v107
	v_mov_b32_e32 v9, v106
	v_pk_mul_f32 v[4:5], v[8:9], v[4:5]
	v_mov_b32_e32 v8, v109
	v_add_f32_e32 v34, v4, v5
	v_pk_mul_f32 v[4:5], v[0:1], v[214:215] op_sel_hi:[0,1]
	v_pk_mul_f32 v[4:5], v[4:5], v[216:217]
	v_mov_b32_e32 v9, v108
	v_pk_mul_f32 v[8:9], v[8:9], v[4:5]
	v_pk_mul_f32 v[4:5], v[108:109], v[4:5]
	v_sub_f32_e32 v8, v8, v9
	v_add_f32_e32 v9, v4, v5
	v_pk_mul_f32 v[4:5], v[0:1], v[76:77] op_sel_hi:[0,1]
	v_pk_mul_f32 v[2:3], v[4:5], v[6:7]
	v_mov_b32_e32 v38, v35
	v_pk_mul_f32 v[4:5], v[112:113], v[2:3]
	v_mov_b32_e32 v202, v16
	v_sub_f32_e32 v6, v4, v5
	v_mov_b32_e32 v4, v113
	v_mov_b32_e32 v5, v112
	v_pk_mul_f32 v[2:3], v[4:5], v[2:3]
	v_mov_b32_e32 v4, v111
	v_add_f32_e32 v7, v2, v3
	v_pk_mul_f32 v[2:3], v[0:1], v[208:209] op_sel_hi:[0,1]
	v_pk_mul_f32 v[2:3], v[2:3], v[210:211]
	v_mov_b32_e32 v5, v110
	v_pk_mul_f32 v[4:5], v[4:5], v[2:3]
	v_pk_mul_f32 v[2:3], v[110:111], v[2:3]
;     ...
;         for (int j = 0; j < 8; ++j) { const int i = 16 * dd + 8 * hi + j; const int e1 = aa * 64 + i;
;           const float rev = pos * exp2f(-(float)i * 0.41524101186092029f) * 0.15915494309189535f;
;           const float sn = __builtin_amdgcn_sinf(rev), cs = __builtin_amdgcn_cosf(rev);
;           const float y1 = x[d0][j] * rstd * qgain[e1], y2 = x[d0 + 2][j] * rstd * qgain[e1 + 32];
;           x[d0][j] = y1 * cs - y2 * sn; x[d0 + 2][j] = y2 * cs + y1 * sn; } } }
	v_sub_f32_e32 v44, v4, v5
	v_add_f32_e32 v46, v2, v3
	v_pk_mul_f32 v[2:3], v[0:1], v[72:73] op_sel_hi:[0,1]
	v_pk_mul_f32 v[2:3], v[2:3], v[36:37]
	v_mov_b32_e32 v203, v28
	v_pk_mul_f32 v[4:5], v[114:115], v[2:3]
	v_mov_b32_e32 v182, v50
	v_sub_f32_e32 v33, v4, v5
	v_mov_b32_e32 v4, v115
	v_mov_b32_e32 v5, v114
	v_pk_mul_f32 v[2:3], v[4:5], v[2:3]
	v_mov_b32_e32 v4, v117
	v_add_f32_e32 v36, v2, v3
	v_pk_mul_f32 v[2:3], v[0:1], v[204:205] op_sel_hi:[0,1]
	v_pk_mul_f32 v[2:3], v[2:3], v[206:207]
	v_mov_b32_e32 v5, v116
	v_pk_mul_f32 v[4:5], v[4:5], v[2:3]
	v_pk_mul_f32 v[2:3], v[116:117], v[2:3]
	v_sub_f32_e32 v37, v4, v5
	v_add_f32_e32 v48, v2, v3
	v_pk_mul_f32 v[2:3], v[0:1], v[78:79] op_sel_hi:[0,1]
	v_pk_mul_f32 v[2:3], v[2:3], v[38:39]
	v_mov_b32_e32 v28, v17
	v_pk_mul_f32 v[4:5], v[122:123], v[2:3]
	v_mov_b32_e32 v198, v18
	v_sub_f32_e32 v35, v4, v5
	v_mov_b32_e32 v4, v123
	v_mov_b32_e32 v5, v122
	v_pk_mul_f32 v[2:3], v[4:5], v[2:3]
	v_mov_b32_e32 v4, v127
	v_add_f32_e32 v38, v2, v3
	v_pk_mul_f32 v[2:3], v[0:1], v[200:201] op_sel_hi:[0,1]
	v_pk_mul_f32 v[2:3], v[2:3], v[202:203]
	v_mov_b32_e32 v5, v126
	v_pk_mul_f32 v[4:5], v[4:5], v[2:3]
	v_pk_mul_f32 v[2:3], v[126:127], v[2:3]
	v_sub_f32_e32 v39, v4, v5
	v_add_f32_e32 v50, v2, v3
	v_pk_mul_f32 v[2:3], v[0:1], v[74:75] op_sel_hi:[0,1]
	v_pk_mul_f32 v[2:3], v[2:3], v[28:29]
	v_mov_b32_e32 v199, v30
	v_pk_mul_f32 v[4:5], v[136:137], v[2:3]
	v_mov_b32_e32 v30, v19
	v_sub_f32_e32 v17, v4, v5
	v_mov_b32_e32 v4, v137
	v_mov_b32_e32 v5, v136
	v_pk_mul_f32 v[2:3], v[4:5], v[2:3]
	v_mov_b32_e32 v4, v175
	v_add_f32_e32 v28, v2, v3
	v_pk_mul_f32 v[2:3], v[0:1], v[196:197] op_sel_hi:[0,1]
	v_pk_mul_f32 v[2:3], v[2:3], v[198:199]
	v_mov_b32_e32 v5, v174
	v_pk_mul_f32 v[4:5], v[4:5], v[2:3]
	v_pk_mul_f32 v[2:3], v[174:175], v[2:3]
	v_sub_f32_e32 v29, v4, v5
	v_add_f32_e32 v56, v2, v3
	v_pk_mul_f32 v[2:3], v[0:1], v[84:85] op_sel_hi:[0,1]
	v_pk_mul_f32 v[2:3], v[2:3], v[30:31]
	v_mov_b32_e32 v194, v64
	v_pk_mul_f32 v[4:5], v[168:169], v[2:3]
	s_waitcnt vmcnt(0)
	v_mov_b32_e32 v195, v68
	v_sub_f32_e32 v19, v4, v5
	v_mov_b32_e32 v4, v169
	v_mov_b32_e32 v5, v168
	v_pk_mul_f32 v[2:3], v[4:5], v[2:3]
	v_mov_b32_e32 v4, v167
	v_add_f32_e32 v30, v2, v3
	v_pk_mul_f32 v[2:3], v[0:1], v[192:193] op_sel_hi:[0,1]
	v_pk_mul_f32 v[2:3], v[2:3], v[194:195]
	v_mov_b32_e32 v5, v166
	v_pk_mul_f32 v[4:5], v[4:5], v[2:3]
	v_pk_mul_f32 v[2:3], v[166:167], v[2:3]
	v_mov_b32_e32 v68, v65
	v_add_f32_e32 v57, v2, v3
	v_pk_mul_f32 v[2:3], v[0:1], v[80:81] op_sel_hi:[0,1]
	v_pk_mul_f32 v[2:3], v[2:3], v[68:69]
	v_sub_f32_e32 v31, v4, v5
	v_pk_mul_f32 v[4:5], v[162:163], v[2:3]
	v_mov_b32_e32 v190, v66
	v_sub_f32_e32 v58, v4, v5
	v_mov_b32_e32 v4, v163
	v_mov_b32_e32 v5, v162
	v_pk_mul_f32 v[2:3], v[4:5], v[2:3]
	v_mov_b32_e32 v191, v70
	v_add_f32_e32 v59, v2, v3
	v_pk_mul_f32 v[2:3], v[0:1], v[188:189] op_sel_hi:[0,1]
	v_pk_mul_f32 v[2:3], v[2:3], v[190:191]
	v_mov_b32_e32 v4, v161
	v_mov_b32_e32 v5, v160
	v_pk_mul_f32 v[4:5], v[4:5], v[2:3]
	v_pk_mul_f32 v[2:3], v[160:161], v[2:3]
	v_mov_b32_e32 v70, v67
	v_add_f32_e32 v61, v2, v3
	v_pk_mul_f32 v[2:3], v[0:1], v[86:87] op_sel_hi:[0,1]
	v_pk_mul_f32 v[2:3], v[2:3], v[70:71]
	v_sub_f32_e32 v60, v4, v5
	v_pk_mul_f32 v[4:5], v[158:159], v[2:3]
	v_mov_b32_e32 v187, v52
	v_sub_f32_e32 v62, v4, v5
	v_mov_b32_e32 v4, v159
	v_mov_b32_e32 v5, v158
	v_pk_mul_f32 v[2:3], v[4:5], v[2:3]
	v_mov_b32_e32 v4, v157
	v_add_f32_e32 v63, v2, v3
	v_pk_mul_f32 v[2:3], v[0:1], v[184:185] op_sel_hi:[0,1]
	v_pk_mul_f32 v[2:3], v[2:3], v[186:187]
	v_mov_b32_e32 v5, v156
	v_pk_mul_f32 v[4:5], v[4:5], v[2:3]
	v_pk_mul_f32 v[2:3], v[156:157], v[2:3]
	v_mov_b32_e32 v52, v49
	v_add_f32_e32 v65, v2, v3
	v_pk_mul_f32 v[2:3], v[0:1], v[82:83] op_sel_hi:[0,1]
	v_pk_mul_f32 v[2:3], v[2:3], v[52:53]
	v_sub_f32_e32 v64, v4, v5
	v_pk_mul_f32 v[4:5], v[152:153], v[2:3]
	v_mov_b32_e32 v183, v54
	v_sub_f32_e32 v49, v4, v5
	v_mov_b32_e32 v4, v153
	v_mov_b32_e32 v5, v152
	v_pk_mul_f32 v[2:3], v[4:5], v[2:3]
	v_mov_b32_e32 v4, v149
	v_add_f32_e32 v52, v2, v3
	v_pk_mul_f32 v[2:3], v[0:1], v[180:181] op_sel_hi:[0,1]
	v_pk_mul_f32 v[2:3], v[2:3], v[182:183]
	v_mov_b32_e32 v5, v148
	v_pk_mul_f32 v[4:5], v[4:5], v[2:3]
	v_pk_mul_f32 v[2:3], v[148:149], v[2:3]
	v_mov_b32_e32 v54, v51
	v_add_f32_e32 v66, v2, v3
	v_pk_mul_f32 v[2:3], v[0:1], v[92:93] op_sel_hi:[0,1]
	v_pk_mul_f32 v[2:3], v[2:3], v[54:55]
	v_sub_f32_e32 v53, v4, v5
	v_pk_mul_f32 v[4:5], v[146:147], v[2:3]
	v_mov_b32_e32 v179, v40
	v_sub_f32_e32 v51, v4, v5
	v_mov_b32_e32 v4, v147
	v_mov_b32_e32 v5, v146
	v_pk_mul_f32 v[2:3], v[4:5], v[2:3]
	v_mov_b32_e32 v4, v145
	v_add_f32_e32 v54, v2, v3
	v_pk_mul_f32 v[2:3], v[0:1], v[176:177] op_sel_hi:[0,1]
	v_pk_mul_f32 v[2:3], v[2:3], v[178:179]
	v_mov_b32_e32 v5, v144
	v_pk_mul_f32 v[4:5], v[4:5], v[2:3]
	v_pk_mul_f32 v[2:3], v[144:145], v[2:3]
	v_mov_b32_e32 v40, v45
	v_add_f32_e32 v67, v2, v3
	v_pk_mul_f32 v[2:3], v[0:1], v[88:89] op_sel_hi:[0,1]
	v_pk_mul_f32 v[2:3], v[2:3], v[40:41]
	v_sub_f32_e32 v55, v4, v5
	v_pk_mul_f32 v[4:5], v[142:143], v[2:3]
	v_mov_b32_e32 v173, v42
	v_sub_f32_e32 v40, v4, v5
	v_mov_b32_e32 v4, v143
	v_mov_b32_e32 v5, v142
	v_pk_mul_f32 v[2:3], v[4:5], v[2:3]
	v_mov_b32_e32 v4, v141
	v_add_f32_e32 v41, v2, v3
	v_pk_mul_f32 v[2:3], v[0:1], v[170:171] op_sel_hi:[0,1]
	v_pk_mul_f32 v[2:3], v[2:3], v[172:173]
	v_mov_b32_e32 v5, v140
	v_pk_mul_f32 v[4:5], v[4:5], v[2:3]
	v_pk_mul_f32 v[2:3], v[140:141], v[2:3]
	v_mov_b32_e32 v42, v47
	v_add_f32_e32 v68, v2, v3
	v_pk_mul_f32 v[2:3], v[0:1], v[94:95] op_sel_hi:[0,1]
	v_pk_mul_f32 v[2:3], v[2:3], v[42:43]
	v_sub_f32_e32 v45, v4, v5
; __device__ __forceinline__ unsigned cvtpk(float lo, float hi) { unsigned r; asm volatile("v_cvt_pk_bf16_f32 %0, %1, %2" : "=v"(r) : "v"(lo), "v"(hi)); return r; }
; __device__ __forceinline__ int v_st(int k, int c) { const int kk = (k & ~0xC) | ((k & 4) << 1) | ((k & 8) >> 1); return ((kk >> 3) * 4 + (c >> 5)) * 512 + ((kk & 7) * 32 + (c & 31)) * 2; }
; __device__ __forceinline__ int v_rd_base(int lane) { return ((lane & 3) << 3) | (((lane >> 2) & 3) << 6) | (((lane >> 4) & 1) << 5) | (((lane >> 5) & 1) << 8); }
;     ...
;           x[d0][j] = y1 * cs - y2 * sn; x[d0 + 2][j] = y2 * cs + y1 * sn; } } }
; #pragma unroll
;     for (int d0 = 0; d0 < 8; ++d0) { u32x4 w = {cvtpk(x[d0][0], x[d0][1]), cvtpk(x[d0][2], x[d0][3]), cvtpk(x[d0][4], x[d0][5]), cvtpk(x[d0][6], x[d0][7])}; qr[d0] = *reinterpret_cast<bf16x8*>(&w); }
;   }
;   const int sr = tid >> 4, sc = (tid & 15) * 8, vst0 = v_st(sr, sc), vst1 = vst0 + 8192;
;   const int vb0 = (int)(uintptr_t)V_lds + v_rd_base(lane);
;   const int qrel = wid * QBLK + r32;
;   constexpr int SD = (MODE == 0) ? ATT_SD0 : 2;
;   struct { bf16x8 vs0, vs1, ks0, ks1; } sr_[SD];
;   const unsigned soff0 = (unsigned)(sr * (int)ldk + sc) * 2u, soff1 = soff0 + (unsigned)(32 * (int)ldk) * 2u;
;     ...
;   PLOAD(0); asm volatile("s_waitcnt vmcnt(0)" ::: "memory"); PWRITE(0); __syncthreads();
	v_pk_mul_f32 v[4:5], v[138:139], v[2:3]
	v_mov_b32_e32 v155, v24
	v_sub_f32_e32 v42, v4, v5
	v_mov_b32_e32 v4, v139
	v_mov_b32_e32 v5, v138
	v_pk_mul_f32 v[2:3], v[4:5], v[2:3]
	v_mov_b32_e32 v4, v133
	v_add_f32_e32 v43, v2, v3
	v_pk_mul_f32 v[2:3], v[0:1], v[150:151] op_sel_hi:[0,1]
	v_pk_mul_f32 v[2:3], v[2:3], v[154:155]
	v_mov_b32_e32 v5, v132
	v_pk_mul_f32 v[4:5], v[4:5], v[2:3]
	v_pk_mul_f32 v[2:3], v[132:133], v[2:3]
	v_mov_b32_e32 v24, v21
	v_add_f32_e32 v69, v2, v3
	v_pk_mul_f32 v[2:3], v[0:1], v[90:91] op_sel_hi:[0,1]
	v_mul_f32_e32 v119, 0.15915494, v118
	v_pk_mul_f32 v[2:3], v[2:3], v[24:25]
	v_sin_f32_e32 v118, v119
	v_cos_f32_e32 v119, v119
	v_sub_f32_e32 v47, v4, v5
	v_pk_mul_f32 v[4:5], v[124:125], v[2:3]
	v_mov_b32_e32 v131, v26
	v_sub_f32_e32 v21, v4, v5
	v_mov_b32_e32 v4, v125
	v_mov_b32_e32 v5, v124
	v_pk_mul_f32 v[2:3], v[4:5], v[2:3]
	v_pk_mul_f32 v[236:237], v[0:1], v[236:237] op_sel_hi:[0,1]
	v_add_f32_e32 v24, v2, v3
	v_pk_mul_f32 v[2:3], v[0:1], v[128:129] op_sel_hi:[0,1]
	v_pk_mul_f32 v[2:3], v[2:3], v[130:131]
	v_mov_b32_e32 v4, v119
	v_mov_b32_e32 v5, v118
	v_pk_mul_f32 v[0:1], v[0:1], v[134:135] op_sel_hi:[0,1]
	v_mov_b32_e32 v26, v23
	v_pk_mul_f32 v[4:5], v[4:5], v[2:3]
	v_pk_mul_f32 v[2:3], v[118:119], v[2:3]
	v_pk_mul_f32 v[0:1], v[0:1], v[26:27]
	v_sub_f32_e32 v4, v4, v5
	v_add_f32_e32 v5, v2, v3
	v_pk_mul_f32 v[2:3], v[120:121], v[0:1]
	v_pk_mul_f32 v[236:237], v[238:239], v[236:237]
	v_mov_b32_e32 v238, v97
	v_mov_b32_e32 v239, v96
	v_sub_f32_e32 v23, v2, v3
	v_mov_b32_e32 v2, v121
	v_mov_b32_e32 v3, v120
	v_pk_mul_f32 v[238:239], v[238:239], v[236:237]
	v_pk_mul_f32 v[0:1], v[2:3], v[0:1]
	v_sub_f32_e32 v16, v238, v239
	v_pk_mul_f32 v[96:97], v[96:97], v[236:237]
	v_add_f32_e32 v0, v0, v1
	v_cvt_pk_bf16_f32 v124, v16, v20
	v_cvt_pk_bf16_f32 v125, v12, v14
	v_cvt_pk_bf16_f32 v126, v10, v32
	v_cvt_pk_bf16_f32 v127, v8, v6
	v_cvt_pk_bf16_f32 v120, v44, v33
	v_ashrrev_i32_e32 v32, 4, v230
	v_lshlrev_b32_e32 v33, 3, v230
	s_movk_i32 s0, 0x2a00
	v_add_f32_e32 v18, v96, v97
	v_cvt_pk_bf16_f32 v121, v37, v35
	v_cvt_pk_bf16_f32 v122, v39, v17
	v_cvt_pk_bf16_f32 v123, v29, v19
	v_cvt_pk_bf16_f32 v116, v18, v22
	v_cvt_pk_bf16_f32 v117, v13, v15
	v_cvt_pk_bf16_f32 v118, v11, v34
	v_cvt_pk_bf16_f32 v119, v9, v7
	v_cvt_pk_bf16_f32 v112, v46, v36
	v_cvt_pk_bf16_f32 v113, v48, v38
	v_cvt_pk_bf16_f32 v114, v50, v28
	v_cvt_pk_bf16_f32 v115, v56, v30
	v_cvt_pk_bf16_f32 v108, v31, v58
	v_cvt_pk_bf16_f32 v109, v60, v62
	v_cvt_pk_bf16_f32 v110, v64, v49
	v_cvt_pk_bf16_f32 v111, v53, v51
	v_cvt_pk_bf16_f32 v104, v55, v40
	v_cvt_pk_bf16_f32 v105, v45, v42
	v_cvt_pk_bf16_f32 v106, v47, v21
	v_cvt_pk_bf16_f32 v107, v4, v23
	v_cvt_pk_bf16_f32 v100, v57, v59
	v_cvt_pk_bf16_f32 v101, v61, v63
	v_cvt_pk_bf16_f32 v102, v65, v52
	v_cvt_pk_bf16_f32 v103, v66, v54
	v_cvt_pk_bf16_f32 v96, v67, v41
	v_cvt_pk_bf16_f32 v97, v68, v43
	v_cvt_pk_bf16_f32 v98, v69, v24
	v_cvt_pk_bf16_f32 v99, v5, v0
	v_and_b32_e32 v34, 0x78, v33
	v_mul_lo_u32 v0, v32, s0
	v_or_b32_e32 v0, v0, v34
	v_lshlrev_b32_e32 v48, 1, v0
	v_mov_b32_e32 v49, v165
	v_lshl_add_u64 v[166:167], s[2:3], 0, v[48:49]
	v_add_co_u32_e32 v20, vcc, s75, v166
	global_load_dwordx4 v[0:3], v48, s[2:3] offset:2560
	s_nop 0
	v_addc_co_u32_e32 v21, vcc, 0, v167, vcc
	v_add_co_u32_e32 v24, vcc, s76, v166
	global_load_dwordx4 v[4:7], v[20:21], off offset:2560
	s_nop 0
	v_addc_co_u32_e32 v25, vcc, 0, v167, vcc
	global_load_dwordx4 v[8:11], v[24:25], off offset:2560
	v_add_co_u32_e32 v28, vcc, s77, v166
	v_and_b32_e32 v35, 0xfffff0, v32
	s_nop 0
	v_addc_co_u32_e32 v29, vcc, 0, v167, vcc
	global_load_dwordx4 v[12:15], v[28:29], off offset:2560
	global_load_dwordx4 v[16:19], v48, s[2:3] offset:2048
	s_nop 0
	global_load_dwordx4 v[20:23], v[20:21], off offset:2048
	s_nop 0
	global_load_dwordx4 v[24:27], v[24:25], off offset:2048
	s_nop 0
	global_load_dwordx4 v[28:31], v[28:29], off offset:2048
	v_lshlrev_b32_e32 v36, 1, v32
	v_and_or_b32 v35, v36, 8, v35
	v_lshrrev_b32_e32 v35, 1, v35
	v_bfe_u32 v33, v33, 5, 2
	s_and_b32 s0, s29, 0x3fffffc0
	v_lshrrev_b32_e32 v36, 1, v32
	v_or_b32_e32 v33, v35, v33
	v_and_b32_e32 v35, 3, v32
	v_lshlrev_b32_e32 v34, 1, v34
	s_lshl_b32 s0, s0, 2
	v_and_or_b32 v35, v36, 4, v35
	v_and_b32_e32 v36, 48, v34
	s_add_i32 s39, s0, 0
	v_lshl_or_b32 v35, v35, 6, v36
	s_add_i32 s39, s39, 0x20400
	v_lshl_or_b32 v162, v33, 9, v35
	s_add_i32 s1, 0, 0x10000
	v_add_u32_e32 v33, 0x2000, v162
	s_cmp_lg_u32 s1, -1
	v_add_u32_e32 v35, s1, v162
	s_cselect_b32 s0, s1, 0
	s_waitcnt vmcnt(0)
	v_lshlrev_b32_e32 v50, 4, v230
	v_and_b32_e32 v54, 63, v230
	s_mov_b32 s44, 0
	s_mov_b32 s45, s44
	s_mov_b32 s46, s44
	s_mov_b32 s47, s44
	s_mov_b32 s48, s44
	s_mov_b32 s49, s44
	s_mov_b32 s50, s44
	s_mov_b32 s51, s44
	s_mov_b32 s52, s44
	s_mov_b32 s53, s44
	s_mov_b32 s54, s44
	s_mov_b32 s55, s44
	s_mov_b32 s56, s44
	s_mov_b32 s57, s44
	s_mov_b32 s58, s44
	s_mov_b32 s59, s44
	v_cmp_gt_u32_e64 s[2:3], 32, v54
	v_lshl_add_u32 v168, v228, 2, s39
	v_mov_b32_e32 v169, 0
	s_waitcnt vmcnt(7)
	ds_write_b128 v35, v[0:3]
	v_add_u32_e32 v0, s1, v33
	s_add_i32 s1, 0, 0x14000
	v_and_b32_e32 v1, 0xf0, v230
	s_waitcnt vmcnt(6)
	ds_write_b128 v0, v[4:7]
	v_add_u32_e32 v0, s1, v162
	s_waitcnt vmcnt(5)
	ds_write_b128 v0, v[8:11]
	v_add_u32_e32 v0, s1, v33
	s_waitcnt vmcnt(4)
	ds_write_b128 v0, v[12:15]
	v_lshlrev_b32_e32 v0, 8, v32
	v_bitop3_b32 v0, v34, v0, v1 bitop3:0xde
	v_lshlrev_b32_e32 v8, 8, v228
	v_and_b32_e32 v9, 0xf0, v50
	v_add_u32_e32 v181, 0, v0
	v_bitop3_b32 v0, v164, v8, v9 bitop3:0xde
	v_add_u32_e32 v172, 0, v0
	s_waitcnt vmcnt(3)
	ds_write_b128 v181, v[16:19]
	s_waitcnt vmcnt(2)
	ds_write_b128 v181, v[20:23] offset:8192
	s_waitcnt vmcnt(1)
	ds_write_b128 v181, v[24:27] offset:16384
	s_waitcnt vmcnt(0)
	ds_write_b128 v181, v[28:31] offset:24576
	s_waitcnt lgkmcnt(0)
	s_barrier
; __device__ __forceinline__ void qkt(f32x16& p0, f32x16& p1, const bf16* Ks, const bf16x8* qr, int r32, int hi) {
;   p0 = f32x16{}; p1 = f32x16{};
; #pragma unroll
;   for (int d0 = 0; d0 < 8; ++d0) { int cb = (d0 * 16 + hi * 8) * 2;
;     bf16x8 b0 = *reinterpret_cast<const bf16x8*>((const char*)Ks + KSWZ(r32, cb));
;     bf16x8 b1 = *reinterpret_cast<const bf16x8*>((const char*)Ks + KSWZ(32 + r32, cb));
;     p0 = __builtin_amdgcn_mfma_f32_32x32x16_bf16(b0, qr[d0], p0, 0, 0, 0);
;     p1 = __builtin_amdgcn_mfma_f32_32x32x16_bf16(b1, qr[d0], p1, 0, 0, 0); }
; }
;     ...
;   PLOAD(0); asm volatile("s_waitcnt vmcnt(0)" ::: "memory"); PWRITE(0); __syncthreads();
;   qkt(pA0, pA1, KSUB(0, 0), qr, r32, hi); partialSM(pA0, pA1, m_reg, mnA, alA);
	ds_read_b128 v[0:3], v172
	ds_read_b128 v[4:7], v172 offset:8192
	s_waitcnt lgkmcnt(1)
	v_mfma_f32_32x32x16_bf16 v[32:47], v[0:3], v[124:127], 0
	v_or_b32_e32 v0, 32, v164
	v_bitop3_b32 v0, v0, v8, v9 bitop3:0xde
	v_add_u32_e32 v173, 0, v0
	v_lshlrev_b32_e32 v10, 3, v54
	v_and_b32_e32 v11, 0xc0, v50
	s_waitcnt lgkmcnt(0)
	v_mfma_f32_32x32x16_bf16 v[16:31], v[4:7], v[124:127], 0
	ds_read_b128 v[0:3], v173
	ds_read_b128 v[4:7], v173 offset:8192
	s_waitcnt lgkmcnt(1)
	v_mfma_f32_32x32x16_bf16 v[32:47], v[0:3], v[120:123], v[32:47]
	v_or_b32_e32 v0, 64, v164
	v_bitop3_b32 v0, v0, v8, v9 bitop3:0xde
	v_add_u32_e32 v174, 0, v0
	s_waitcnt lgkmcnt(0)
	v_mfma_f32_32x32x16_bf16 v[16:31], v[4:7], v[120:123], v[16:31]
	ds_read_b128 v[0:3], v174
	ds_read_b128 v[4:7], v174 offset:8192
	s_waitcnt lgkmcnt(1)
	v_mfma_f32_32x32x16_bf16 v[32:47], v[0:3], v[116:119], v[32:47]
	v_or_b32_e32 v0, 0x60, v164
	v_bitop3_b32 v0, v0, v8, v9 bitop3:0xde
	v_add_u32_e32 v175, 0, v0
	s_waitcnt lgkmcnt(0)
	v_mfma_f32_32x32x16_bf16 v[16:31], v[4:7], v[116:119], v[16:31]
	ds_read_b128 v[0:3], v175
	ds_read_b128 v[4:7], v175 offset:8192
	s_waitcnt lgkmcnt(1)
	v_mfma_f32_32x32x16_bf16 v[32:47], v[0:3], v[112:115], v[32:47]
	v_or_b32_e32 v0, 0x80, v164
	v_bitop3_b32 v0, v0, v8, v9 bitop3:0xde
	v_add_u32_e32 v176, 0, v0
	s_waitcnt lgkmcnt(0)
	v_mfma_f32_32x32x16_bf16 v[16:31], v[4:7], v[112:115], v[16:31]
	ds_read_b128 v[0:3], v176
	ds_read_b128 v[4:7], v176 offset:8192
	s_waitcnt lgkmcnt(1)
	v_mfma_f32_32x32x16_bf16 v[32:47], v[0:3], v[108:111], v[32:47]
	v_or_b32_e32 v0, 0xa0, v164
	v_bitop3_b32 v0, v0, v8, v9 bitop3:0xde
	v_add_u32_e32 v177, 0, v0
	ds_read_b128 v[0:3], v177
	s_waitcnt lgkmcnt(1)
	v_mfma_f32_32x32x16_bf16 v[16:31], v[4:7], v[108:111], v[16:31]
	ds_read_b128 v[4:7], v177 offset:8192
	s_waitcnt lgkmcnt(1)
	v_mfma_f32_32x32x16_bf16 v[32:47], v[0:3], v[104:107], v[32:47]
	v_or_b32_e32 v0, 0xc0, v164
	v_bitop3_b32 v0, v0, v8, v9 bitop3:0xde
	v_add_u32_e32 v178, 0, v0
	ds_read_b128 v[0:3], v178
	s_waitcnt lgkmcnt(1)
	v_mfma_f32_32x32x16_bf16 v[16:31], v[4:7], v[104:107], v[16:31]
	v_lshlrev_b32_e32 v5, 1, v230
	v_and_or_b32 v4, v10, 24, v11
	v_and_b32_e32 v5, 32, v5
	v_and_b32_e32 v6, 0x100, v10
	v_or3_b32 v55, v4, v5, v6
	ds_read_b128 v[4:7], v178 offset:8192
	v_add_u32_e32 v182, s0, v55
	s_waitcnt lgkmcnt(1)
	v_mfma_f32_32x32x16_bf16 v[32:47], v[0:3], v[100:103], v[32:47]
	v_or_b32_e32 v0, 0xe0, v164
	v_bitop3_b32 v0, v0, v8, v9 bitop3:0xde
	v_add_u32_e32 v179, 0, v0
	ds_read_b128 v[0:3], v179
	ds_read_b128 v[50:53], v179 offset:8192
	s_waitcnt lgkmcnt(2)
	v_mfma_f32_32x32x16_bf16 v[16:31], v[4:7], v[100:103], v[16:31]
	s_waitcnt lgkmcnt(1)
	v_mfma_f32_32x32x16_bf16 v[32:47], v[0:3], v[96:99], v[32:47]
	v_mov_b64_e32 v[0:1], s[44:45]
	v_mov_b64_e32 v[14:15], s[58:59]
	v_mov_b64_e32 v[2:3], s[46:47]
	v_mov_b64_e32 v[4:5], s[48:49]
	v_mov_b64_e32 v[6:7], s[50:51]
	v_mov_b64_e32 v[8:9], s[52:53]
	v_mov_b64_e32 v[10:11], s[54:55]
	s_waitcnt lgkmcnt(0)
	v_mfma_f32_32x32x16_bf16 v[16:31], v[50:53], v[96:99], v[16:31]
	s_nop 2
	s_add_i32 s1, s0, 0x4000
	v_add_u32_e32 v180, s1, v55
	s_add_i32 s1, s0, 0x8000
	s_add_i32 s0, s0, 0xc000
	v_exp_f32_e32 v64, v32
	v_exp_f32_e32 v65, v33
	v_exp_f32_e32 v66, v34
	v_exp_f32_e32 v67, v35
	v_exp_f32_e32 v68, v36
	v_exp_f32_e32 v69, v37
	v_exp_f32_e32 v70, v38
	v_exp_f32_e32 v71, v39
	v_exp_f32_e32 v72, v40
	v_exp_f32_e32 v73, v41
	v_exp_f32_e32 v74, v42
	v_exp_f32_e32 v75, v43
	v_exp_f32_e32 v76, v44
	v_exp_f32_e32 v77, v45
	v_exp_f32_e32 v78, v46
	v_exp_f32_e32 v79, v47
	v_add_u32_e32 v170, s0, v55
	s_or_b32 s0, s28, s4
	v_exp_f32_e32 v80, v16
	v_exp_f32_e32 v81, v17
	v_exp_f32_e32 v82, v18
	v_exp_f32_e32 v83, v19
	v_exp_f32_e32 v84, v20
	v_exp_f32_e32 v85, v21
	v_exp_f32_e32 v86, v22
	v_exp_f32_e32 v87, v23
	v_exp_f32_e32 v88, v24
	v_exp_f32_e32 v89, v25
	v_exp_f32_e32 v90, v26
	v_exp_f32_e32 v91, v27
	v_exp_f32_e32 v92, v28
	v_exp_f32_e32 v93, v29
	v_exp_f32_e32 v94, v30
	v_exp_f32_e32 v95, v31
	s_add_u32 s0, s69, s0
	v_add_u32_e32 v171, s1, v55
	s_addc_u32 s1, s71, s5
	v_mov_b64_e32 v[12:13], s[56:57]
	v_lshl_add_u64 v[160:161], s[0:1], 0, v[48:49]
	s_mov_b64 s[98:99], s[0:1]
	v_mov_b32_e32 v183, v48
	v_mov_b64_e32 v[62:63], v[14:15]
	v_mov_b64_e32 v[46:47], v[14:15]
	v_mov_b64_e32 v[30:31], v[14:15]
	v_mov_b64_e32 v[60:61], v[12:13]
	v_mov_b64_e32 v[58:59], v[10:11]
	v_mov_b64_e32 v[56:57], v[8:9]
	v_mov_b64_e32 v[54:55], v[6:7]
	v_mov_b64_e32 v[52:53], v[4:5]
	v_mov_b64_e32 v[50:51], v[2:3]
	v_mov_b64_e32 v[48:49], v[0:1]
	v_mov_b64_e32 v[44:45], v[12:13]
	v_mov_b64_e32 v[42:43], v[10:11]
	v_mov_b64_e32 v[40:41], v[8:9]
	v_mov_b64_e32 v[38:39], v[6:7]
	v_mov_b64_e32 v[36:37], v[4:5]
	v_mov_b64_e32 v[34:35], v[2:3]
	v_mov_b64_e32 v[32:33], v[0:1]
	v_mov_b64_e32 v[28:29], v[12:13]
	v_mov_b64_e32 v[26:27], v[10:11]
	v_mov_b64_e32 v[24:25], v[8:9]
	v_mov_b64_e32 v[22:23], v[6:7]
	v_mov_b64_e32 v[20:21], v[4:5]
	v_mov_b64_e32 v[18:19], v[2:3]
	v_mov_b64_e32 v[16:17], v[0:1]
.LBB0_486:
	v_add_u32_e32 v180, 0x10000, v162
	s_add_u32 s100, s98, 0xa8000
	s_addc_u32 s101, s99, 0
	s_mov_b64 s[0:1], s[98:99]
	s_mov_b64 s[4:5], s[100:101]
	v_mov_b32_e32 v169, 0
	v_mov_b32_e32 v219, 0
	v_mov_b32_e32 v222, 0
	v_mov_b32_e32 v254, 0
	s_mov_b32 s44, 0
	global_load_dwordx4 v[246:249], v183, s[98:99]
	global_load_dwordx4 v[250:253], v183, s[100:101]
	s_add_u32 s98, s98, 0x150000
	s_addc_u32 s99, s99, 0
	s_add_u32 s100, s100, 0x150000
	s_addc_u32 s101, s101, 0
	s_waitcnt vmcnt(0)
	ds_write_b128 v181, v[246:249] offset:32768
	ds_write_b128 v181, v[250:253] offset:40960
	ds_read_b128 v[200:203], v172 offset:16384
	ds_read_b128 v[204:207], v172 offset:24576
	ds_read_b128 v[208:211], v173 offset:16384
	ds_read_b128 v[212:215], v173 offset:24576
	ds_read_b128 v[230:233], v174 offset:16384
	ds_read_b128 v[234:237], v174 offset:24576
	ds_read_b128 v[238:241], v175 offset:16384
	ds_read_b128 v[242:245], v175 offset:24576
	s_waitcnt lgkmcnt(8)
	s_barrier
; __device__ __forceinline__ void finishSM(f32x16& p0, f32x16& p1, float alpha, float& l_reg, bf16x8& pa0, bf16x8& pa1, bf16x8& pa2, bf16x8& pa3) {
; #pragma unroll
;   for (int r = 0; r < 16; ++r) p1[r] = __builtin_amdgcn_exp2f(p1[r]);
;   float ps = 0;
; #pragma unroll
;   for (int r = 0; r < 16; ++r) ps += p0[r];
; #pragma unroll
;   for (int r = 0; r < 16; ++r) ps += p1[r];
;   { auto rr = __builtin_amdgcn_permlane32_swap(__float_as_uint(ps), __float_as_uint(ps), false, false);
;     ps = __uint_as_float(rr[0]) + __uint_as_float(rr[1]); }
;   l_reg = l_reg * alpha + ps;
;     ...
;   PK4(p0, 0, pa0); PK4(p0, 8, pa1); PK4(p1, 0, pa2); PK4(p1, 8, pa3);
;     ...
; }
; __device__ __forceinline__ void qkt(f32x16& p0, f32x16& p1, const bf16* Ks, const bf16x8* qr, int r32, int hi) {
;   p0 = f32x16{}; p1 = f32x16{};
; #pragma unroll
;   for (int d0 = 0; d0 < 8; ++d0) { int cb = (d0 * 16 + hi * 8) * 2;
;     bf16x8 b0 = *reinterpret_cast<const bf16x8*>((const char*)Ks + KSWZ(r32, cb));
;     bf16x8 b1 = *reinterpret_cast<const bf16x8*>((const char*)Ks + KSWZ(32 + r32, cb));
;     p0 = __builtin_amdgcn_mfma_f32_32x32x16_bf16(b0, qr[d0], p0, 0, 0, 0);
;     p1 = __builtin_amdgcn_mfma_f32_32x32x16_bf16(b1, qr[d0], p1, 0, 0, 0); }
; }
; __device__ __forceinline__ int v_st(int k, int c) { const int kk = (k & ~0xC) | ((k & 4) << 1) | ((k & 8) >> 1); return ((kk >> 3) * 4 + (c >> 5)) * 512 + ((kk & 7) * 32 + (c & 31)) * 2; }
; __device__ __forceinline__ int v_rd_base(int lane) { return ((lane & 3) << 3) | (((lane >> 2) & 3) << 6) | (((lane >> 4) & 1) << 5) | (((lane >> 5) & 1) << 8); }
; template <int OFF> __device__ __forceinline__ s16x4 tr_read(int vb) {
;   s16x4 r; asm volatile("ds_read_b64_tr_b16 %0, %1 offset:%2" : "=&v"(r) : "v"(vb), "i"(OFF) : "memory"); return r;
; }
; template <int D0> __device__ __forceinline__ void pv_one(f32x16& od, int vb, bf16x8 pa0, bf16x8 pa1, bf16x8 pa2, bf16x8 pa3) {
;   const s16x4 l0 = tr_read<v_rd_off(D0, 0, 0)>(vb), h0 = tr_read<v_rd_off(D0, 0, 1)>(vb), l1 = tr_read<v_rd_off(D0, 1, 0)>(vb), h1 = tr_read<v_rd_off(D0, 1, 1)>(vb);
;   const s16x4 l2 = tr_read<v_rd_off(D0, 2, 0)>(vb), h2 = tr_read<v_rd_off(D0, 2, 1)>(vb), l3 = tr_read<v_rd_off(D0, 3, 0)>(vb), h3 = tr_read<v_rd_off(D0, 3, 1)>(vb);
;     ...
;   for (int p = 0; p + 2 < NP; p += 2) {
;     PAIR_FULL(0, 1, p + 1);
;     PAIR_FULL(1, 0, p + 2);
.Ldense_loop:
	s_waitcnt lgkmcnt(7)
	v_mfma_f32_32x32x16_bf16 v[128:143], v[200:203], v[124:127], 0
	ds_read_b128 v[200:203], v176 offset:16384
	v_cvt_pk_bf16_f32 v184, v64, v65
	v_add_f32_e32 v169, v169, v64
	v_add_f32_e32 v219, v219, v65
	global_load_dwordx4 v[246:249], v183, s[98:99]
	s_waitcnt lgkmcnt(7)
	v_mfma_f32_32x32x16_bf16 v[144:159], v[204:207], v[124:127], 0
	ds_read_b128 v[204:207], v176 offset:24576
	v_cvt_pk_bf16_f32 v185, v66, v67
	v_add_f32_e32 v222, v222, v66
	v_add_f32_e32 v254, v254, v67
	s_waitcnt lgkmcnt(7)
	v_mfma_f32_32x32x16_bf16 v[128:143], v[208:211], v[120:123], v[128:143]
	ds_read_b128 v[208:211], v177 offset:16384
	v_cvt_pk_bf16_f32 v186, v68, v69
	v_add_f32_e32 v169, v169, v68
	v_add_f32_e32 v219, v219, v69
	global_load_dwordx4 v[250:253], v183, s[100:101]
	s_add_u32 s98, s98, 0x150000
	s_addc_u32 s99, s99, 0
	s_add_u32 s100, s100, 0x150000
	s_addc_u32 s101, s101, 0
	s_waitcnt lgkmcnt(7)
	v_mfma_f32_32x32x16_bf16 v[144:159], v[212:215], v[120:123], v[144:159]
	ds_read_b128 v[212:215], v177 offset:24576
	v_cvt_pk_bf16_f32 v187, v70, v71
	v_add_f32_e32 v222, v222, v70
	v_add_f32_e32 v254, v254, v71
	s_waitcnt lgkmcnt(7)
	v_mfma_f32_32x32x16_bf16 v[128:143], v[230:233], v[116:119], v[128:143]
	ds_read_b128 v[230:233], v178 offset:16384
	v_cvt_pk_bf16_f32 v188, v72, v73
	v_add_f32_e32 v169, v169, v72
	v_add_f32_e32 v219, v219, v73
	v_permlane32_swap_b32_e32 v184, v186
	global_load_dwordx4 v[164:167], v183, s[0:1] offset:512
	s_waitcnt lgkmcnt(7)
	v_mfma_f32_32x32x16_bf16 v[144:159], v[234:237], v[116:119], v[144:159]
	ds_read_b128 v[234:237], v178 offset:24576
	v_cvt_pk_bf16_f32 v189, v74, v75
	v_add_f32_e32 v222, v222, v74
	v_add_f32_e32 v254, v254, v75
	v_permlane32_swap_b32_e32 v185, v187
	s_waitcnt lgkmcnt(7)
	v_mfma_f32_32x32x16_bf16 v[128:143], v[238:241], v[112:115], v[128:143]
	ds_read_b128 v[238:241], v179 offset:16384
	v_cvt_pk_bf16_f32 v190, v76, v77
	v_add_f32_e32 v169, v169, v76
	v_add_f32_e32 v219, v219, v77
	global_load_dwordx4 v[160:163], v183, s[4:5] offset:512
	s_add_u32 s0, s0, 0x150000
	s_addc_u32 s1, s1, 0
	s_add_u32 s4, s4, 0x150000
	s_addc_u32 s5, s5, 0
	s_waitcnt lgkmcnt(7)
	v_mfma_f32_32x32x16_bf16 v[144:159], v[242:245], v[112:115], v[144:159]
	ds_read_b128 v[242:245], v179 offset:24576
	v_cvt_pk_bf16_f32 v191, v78, v79
	v_add_f32_e32 v222, v222, v78
	v_add_f32_e32 v254, v254, v79
	s_waitcnt lgkmcnt(7)
	v_mfma_f32_32x32x16_bf16 v[128:143], v[200:203], v[108:111], v[128:143]
	v_cvt_pk_bf16_f32 v192, v80, v81
	v_add_f32_e32 v169, v169, v80
	v_add_f32_e32 v219, v219, v81
	v_permlane32_swap_b32_e32 v188, v190
	s_waitcnt lgkmcnt(6)
	v_mfma_f32_32x32x16_bf16 v[144:159], v[204:207], v[108:111], v[144:159]
	v_cvt_pk_bf16_f32 v193, v82, v83
	v_add_f32_e32 v222, v222, v82
	v_add_f32_e32 v254, v254, v83
	v_permlane32_swap_b32_e32 v189, v191
	s_waitcnt lgkmcnt(5)
	v_mfma_f32_32x32x16_bf16 v[128:143], v[208:211], v[104:107], v[128:143]
	v_cvt_pk_bf16_f32 v194, v84, v85
	v_add_f32_e32 v169, v169, v84
	v_add_f32_e32 v219, v219, v85
	s_waitcnt lgkmcnt(4)
	v_mfma_f32_32x32x16_bf16 v[144:159], v[212:215], v[104:107], v[144:159]
	ds_read_b64_tr_b16 v[200:201], v182 offset:0
	ds_read_b64_tr_b16 v[202:203], v182 offset:2048
	v_cvt_pk_bf16_f32 v195, v86, v87
	v_add_f32_e32 v222, v222, v86
	v_add_f32_e32 v254, v254, v87
	s_waitcnt lgkmcnt(5)
	v_mfma_f32_32x32x16_bf16 v[128:143], v[230:233], v[100:103], v[128:143]
	ds_read_b64_tr_b16 v[204:205], v182 offset:4096
	ds_read_b64_tr_b16 v[206:207], v182 offset:6144
	v_cvt_pk_bf16_f32 v196, v88, v89
	v_add_f32_e32 v169, v169, v88
	v_add_f32_e32 v219, v219, v89
	v_permlane32_swap_b32_e32 v192, v194
	s_waitcnt lgkmcnt(6)
	v_mfma_f32_32x32x16_bf16 v[144:159], v[234:237], v[100:103], v[144:159]
	ds_read_b64_tr_b16 v[208:209], v182 offset:8192
	ds_read_b64_tr_b16 v[210:211], v182 offset:10240
	v_cvt_pk_bf16_f32 v197, v90, v91
	v_add_f32_e32 v222, v222, v90
	v_add_f32_e32 v254, v254, v91
	v_permlane32_swap_b32_e32 v193, v195
	s_waitcnt lgkmcnt(7)
	v_mfma_f32_32x32x16_bf16 v[128:143], v[238:241], v[96:99], v[128:143]
	ds_read_b64_tr_b16 v[212:213], v182 offset:12288
	ds_read_b64_tr_b16 v[214:215], v182 offset:14336
	v_cvt_pk_bf16_f32 v198, v92, v93
	v_add_f32_e32 v169, v169, v92
	v_add_f32_e32 v219, v219, v93
	s_waitcnt lgkmcnt(8)
	v_mfma_f32_32x32x16_bf16 v[144:159], v[242:245], v[96:99], v[144:159]
	ds_read_b64_tr_b16 v[230:231], v182 offset:512
	ds_read_b64_tr_b16 v[232:233], v182 offset:2560
	v_cvt_pk_bf16_f32 v199, v94, v95
	v_add_f32_e32 v222, v222, v94
	v_add_f32_e32 v254, v254, v95
	v_permlane32_swap_b32_e32 v196, v198
	v_permlane32_swap_b32_e32 v197, v199
	s_waitcnt lgkmcnt(8)
	v_mfma_f32_32x32x16_bf16 v[0:15], v[184:187], v[200:203], v[0:15]
	ds_read_b64_tr_b16 v[234:235], v182 offset:4608
	ds_read_b64_tr_b16 v[236:237], v182 offset:6656
	v_exp_f32_e32 v128, v128
	v_exp_f32_e32 v129, v129
	s_waitcnt lgkmcnt(8)
	v_mfma_f32_32x32x16_bf16 v[0:15], v[188:191], v[204:207], v[0:15]
	ds_read_b64_tr_b16 v[238:239], v182 offset:8704
	ds_read_b64_tr_b16 v[240:241], v182 offset:10752
	v_exp_f32_e32 v130, v130
	v_exp_f32_e32 v131, v131
	s_waitcnt vmcnt(3)
	ds_write_b128 v181, v[246:249] offset:49152
	s_waitcnt lgkmcnt(9)
	v_mfma_f32_32x32x16_bf16 v[0:15], v[192:195], v[208:211], v[0:15]
	ds_read_b64_tr_b16 v[242:243], v182 offset:12800
	ds_read_b64_tr_b16 v[244:245], v182 offset:14848
	v_exp_f32_e32 v132, v132
	v_exp_f32_e32 v133, v133
	s_waitcnt lgkmcnt(9)
	v_mfma_f32_32x32x16_bf16 v[0:15], v[196:199], v[212:215], v[0:15]
	ds_read_b64_tr_b16 v[200:201], v182 offset:1024
	ds_read_b64_tr_b16 v[202:203], v182 offset:3072
	v_exp_f32_e32 v134, v134
	v_exp_f32_e32 v135, v135
	s_waitcnt vmcnt(2)
; __device__ __forceinline__ void finishSM(f32x16& p0, f32x16& p1, float alpha, float& l_reg, bf16x8& pa0, bf16x8& pa1, bf16x8& pa2, bf16x8& pa3) {
; #pragma unroll
;   for (int r = 0; r < 16; ++r) p1[r] = __builtin_amdgcn_exp2f(p1[r]);
;   float ps = 0;
; #pragma unroll
;   for (int r = 0; r < 16; ++r) ps += p0[r];
; #pragma unroll
;   for (int r = 0; r < 16; ++r) ps += p1[r];
;   { auto rr = __builtin_amdgcn_permlane32_swap(__float_as_uint(ps), __float_as_uint(ps), false, false);
;     ps = __uint_as_float(rr[0]) + __uint_as_float(rr[1]); }
;   l_reg = l_reg * alpha + ps;
;     ...
;   PK4(p0, 0, pa0); PK4(p0, 8, pa1); PK4(p1, 0, pa2); PK4(p1, 8, pa3);
;     ...
; }
; __device__ __forceinline__ void qkt(f32x16& p0, f32x16& p1, const bf16* Ks, const bf16x8* qr, int r32, int hi) {
;   p0 = f32x16{}; p1 = f32x16{};
; #pragma unroll
;   for (int d0 = 0; d0 < 8; ++d0) { int cb = (d0 * 16 + hi * 8) * 2;
;     bf16x8 b0 = *reinterpret_cast<const bf16x8*>((const char*)Ks + KSWZ(r32, cb));
;     bf16x8 b1 = *reinterpret_cast<const bf16x8*>((const char*)Ks + KSWZ(32 + r32, cb));
;     p0 = __builtin_amdgcn_mfma_f32_32x32x16_bf16(b0, qr[d0], p0, 0, 0, 0);
;     p1 = __builtin_amdgcn_mfma_f32_32x32x16_bf16(b1, qr[d0], p1, 0, 0, 0); }
; }
; __device__ __forceinline__ int v_st(int k, int c) { const int kk = (k & ~0xC) | ((k & 4) << 1) | ((k & 8) >> 1); return ((kk >> 3) * 4 + (c >> 5)) * 512 + ((kk & 7) * 32 + (c & 31)) * 2; }
; __device__ __forceinline__ int v_rd_base(int lane) { return ((lane & 3) << 3) | (((lane >> 2) & 3) << 6) | (((lane >> 4) & 1) << 5) | (((lane >> 5) & 1) << 8); }
; template <int OFF> __device__ __forceinline__ s16x4 tr_read(int vb) {
;   s16x4 r; asm volatile("ds_read_b64_tr_b16 %0, %1 offset:%2" : "=&v"(r) : "v"(vb), "i"(OFF) : "memory"); return r;
; }
; template <int D0> __device__ __forceinline__ void pv_one(f32x16& od, int vb, bf16x8 pa0, bf16x8 pa1, bf16x8 pa2, bf16x8 pa3) {
;   const s16x4 l0 = tr_read<v_rd_off(D0, 0, 0)>(vb), h0 = tr_read<v_rd_off(D0, 0, 1)>(vb), l1 = tr_read<v_rd_off(D0, 1, 0)>(vb), h1 = tr_read<v_rd_off(D0, 1, 1)>(vb);
;   const s16x4 l2 = tr_read<v_rd_off(D0, 2, 0)>(vb), h2 = tr_read<v_rd_off(D0, 2, 1)>(vb), l3 = tr_read<v_rd_off(D0, 3, 0)>(vb), h3 = tr_read<v_rd_off(D0, 3, 1)>(vb);
;     ...
;   for (int p = 0; p + 2 < NP; p += 2) {
;     PAIR_FULL(0, 1, p + 1);
;     PAIR_FULL(1, 0, p + 2);
	ds_write_b128 v181, v[250:253] offset:57344
	s_waitcnt lgkmcnt(10)
	v_mfma_f32_32x32x16_bf16 v[48:63], v[184:187], v[230:233], v[48:63]
	ds_read_b64_tr_b16 v[204:205], v182 offset:5120
	ds_read_b64_tr_b16 v[206:207], v182 offset:7168
	v_exp_f32_e32 v136, v136
	v_exp_f32_e32 v137, v137
	s_waitcnt lgkmcnt(10)
	v_mfma_f32_32x32x16_bf16 v[48:63], v[188:191], v[234:237], v[48:63]
	ds_read_b64_tr_b16 v[208:209], v182 offset:9216
	ds_read_b64_tr_b16 v[210:211], v182 offset:11264
	v_exp_f32_e32 v138, v138
	v_exp_f32_e32 v139, v139
	s_waitcnt vmcnt(1)
	ds_write_b128 v180, v[164:167] offset:32768
	s_waitcnt lgkmcnt(11)
	v_mfma_f32_32x32x16_bf16 v[48:63], v[192:195], v[238:241], v[48:63]
	ds_read_b64_tr_b16 v[212:213], v182 offset:13312
	ds_read_b64_tr_b16 v[214:215], v182 offset:15360
	v_exp_f32_e32 v140, v140
	v_exp_f32_e32 v141, v141
	s_waitcnt lgkmcnt(10)
	v_mfma_f32_32x32x16_bf16 v[48:63], v[196:199], v[242:245], v[48:63]
	ds_read_b64_tr_b16 v[230:231], v182 offset:1536
	ds_read_b64_tr_b16 v[232:233], v182 offset:3584
	v_exp_f32_e32 v142, v142
	v_exp_f32_e32 v143, v143
	s_waitcnt vmcnt(0)
	ds_write_b128 v180, v[160:163] offset:40960
	s_waitcnt lgkmcnt(11)
	v_mfma_f32_32x32x16_bf16 v[32:47], v[184:187], v[200:203], v[32:47]
	ds_read_b64_tr_b16 v[234:235], v182 offset:5632
	ds_read_b64_tr_b16 v[236:237], v182 offset:7680
	ds_read_b128 v[200:203], v172 offset:32768
	v_exp_f32_e32 v144, v144
	v_exp_f32_e32 v145, v145
	s_waitcnt lgkmcnt(11)
	v_mfma_f32_32x32x16_bf16 v[32:47], v[188:191], v[204:207], v[32:47]
	ds_read_b64_tr_b16 v[238:239], v182 offset:9728
	ds_read_b64_tr_b16 v[240:241], v182 offset:11776
	ds_read_b128 v[204:207], v172 offset:40960
	v_exp_f32_e32 v146, v146
	v_exp_f32_e32 v147, v147
	s_waitcnt lgkmcnt(12)
	v_mfma_f32_32x32x16_bf16 v[32:47], v[192:195], v[208:211], v[32:47]
	ds_read_b64_tr_b16 v[242:243], v182 offset:13824
	ds_read_b64_tr_b16 v[244:245], v182 offset:15872
	ds_read_b128 v[208:211], v173 offset:32768
	v_exp_f32_e32 v148, v148
	v_exp_f32_e32 v149, v149
	s_waitcnt lgkmcnt(12)
	v_mfma_f32_32x32x16_bf16 v[32:47], v[196:199], v[212:215], v[32:47]
	ds_read_b128 v[212:215], v173 offset:40960
	v_exp_f32_e32 v150, v150
	v_exp_f32_e32 v151, v151
	s_waitcnt lgkmcnt(11)
	v_mfma_f32_32x32x16_bf16 v[16:31], v[184:187], v[230:233], v[16:31]
	ds_read_b128 v[230:233], v174 offset:32768
	v_exp_f32_e32 v152, v152
	v_exp_f32_e32 v153, v153
	s_waitcnt lgkmcnt(9)
	v_mfma_f32_32x32x16_bf16 v[16:31], v[188:191], v[234:237], v[16:31]
	ds_read_b128 v[234:237], v174 offset:40960
	v_exp_f32_e32 v154, v154
	v_exp_f32_e32 v155, v155
	s_waitcnt lgkmcnt(7)
	v_mfma_f32_32x32x16_bf16 v[16:31], v[192:195], v[238:241], v[16:31]
	ds_read_b128 v[238:241], v175 offset:32768
	v_exp_f32_e32 v156, v156
	v_exp_f32_e32 v157, v157
	s_waitcnt lgkmcnt(5)
	v_mfma_f32_32x32x16_bf16 v[16:31], v[196:199], v[242:245], v[16:31]
	ds_read_b128 v[242:245], v175 offset:40960
	v_exp_f32_e32 v158, v158
	v_exp_f32_e32 v159, v159
	s_barrier
	v_mfma_f32_32x32x16_bf16 v[64:79], v[200:203], v[124:127], 0
	ds_read_b128 v[200:203], v176 offset:32768
	v_cvt_pk_bf16_f32 v184, v128, v129
	v_add_f32_e32 v169, v169, v128
	v_add_f32_e32 v219, v219, v129
	global_load_dwordx4 v[246:249], v183, s[98:99]
	v_mfma_f32_32x32x16_bf16 v[80:95], v[204:207], v[124:127], 0
	ds_read_b128 v[204:207], v176 offset:40960
	v_cvt_pk_bf16_f32 v185, v130, v131
	v_add_f32_e32 v222, v222, v130
	v_add_f32_e32 v254, v254, v131
	s_waitcnt lgkmcnt(7)
	v_mfma_f32_32x32x16_bf16 v[64:79], v[208:211], v[120:123], v[64:79]
	ds_read_b128 v[208:211], v177 offset:32768
	v_cvt_pk_bf16_f32 v186, v132, v133
	v_add_f32_e32 v169, v169, v132
	v_add_f32_e32 v219, v219, v133
	global_load_dwordx4 v[250:253], v183, s[100:101]
	s_add_u32 s98, s98, 0x150000
	s_addc_u32 s99, s99, 0
	s_add_u32 s100, s100, 0x150000
	s_addc_u32 s101, s101, 0
	s_waitcnt lgkmcnt(7)
	v_mfma_f32_32x32x16_bf16 v[80:95], v[212:215], v[120:123], v[80:95]
	ds_read_b128 v[212:215], v177 offset:40960
	v_cvt_pk_bf16_f32 v187, v134, v135
	v_add_f32_e32 v222, v222, v134
	v_add_f32_e32 v254, v254, v135
	s_waitcnt lgkmcnt(7)
	v_mfma_f32_32x32x16_bf16 v[64:79], v[230:233], v[116:119], v[64:79]
	ds_read_b128 v[230:233], v178 offset:32768
	v_cvt_pk_bf16_f32 v188, v136, v137
	v_add_f32_e32 v169, v169, v136
	v_add_f32_e32 v219, v219, v137
	v_permlane32_swap_b32_e32 v184, v186
	global_load_dwordx4 v[164:167], v183, s[0:1] offset:512
	s_waitcnt lgkmcnt(7)
	v_mfma_f32_32x32x16_bf16 v[80:95], v[234:237], v[116:119], v[80:95]
	ds_read_b128 v[234:237], v178 offset:40960
	v_cvt_pk_bf16_f32 v189, v138, v139
	v_add_f32_e32 v222, v222, v138
	v_add_f32_e32 v254, v254, v139
	v_permlane32_swap_b32_e32 v185, v187
	s_waitcnt lgkmcnt(7)
	v_mfma_f32_32x32x16_bf16 v[64:79], v[238:241], v[112:115], v[64:79]
	ds_read_b128 v[238:241], v179 offset:32768
	v_cvt_pk_bf16_f32 v190, v140, v141
	v_add_f32_e32 v169, v169, v140
	v_add_f32_e32 v219, v219, v141
	global_load_dwordx4 v[160:163], v183, s[4:5] offset:512
	s_add_u32 s0, s0, 0x150000
	s_addc_u32 s1, s1, 0
	s_add_u32 s4, s4, 0x150000
	s_addc_u32 s5, s5, 0
	s_waitcnt lgkmcnt(7)
	v_mfma_f32_32x32x16_bf16 v[80:95], v[242:245], v[112:115], v[80:95]
	ds_read_b128 v[242:245], v179 offset:40960
	v_cvt_pk_bf16_f32 v191, v142, v143
	v_add_f32_e32 v222, v222, v142
	v_add_f32_e32 v254, v254, v143
	s_waitcnt lgkmcnt(7)
	v_mfma_f32_32x32x16_bf16 v[64:79], v[200:203], v[108:111], v[64:79]
	v_cvt_pk_bf16_f32 v192, v144, v145
	v_add_f32_e32 v169, v169, v144
	v_add_f32_e32 v219, v219, v145
	v_permlane32_swap_b32_e32 v188, v190
	s_waitcnt lgkmcnt(6)
; __device__ __forceinline__ void finishSM(f32x16& p0, f32x16& p1, float alpha, float& l_reg, bf16x8& pa0, bf16x8& pa1, bf16x8& pa2, bf16x8& pa3) {
; #pragma unroll
;   for (int r = 0; r < 16; ++r) p1[r] = __builtin_amdgcn_exp2f(p1[r]);
;   float ps = 0;
; #pragma unroll
;   for (int r = 0; r < 16; ++r) ps += p0[r];
; #pragma unroll
;   for (int r = 0; r < 16; ++r) ps += p1[r];
;   { auto rr = __builtin_amdgcn_permlane32_swap(__float_as_uint(ps), __float_as_uint(ps), false, false);
;     ps = __uint_as_float(rr[0]) + __uint_as_float(rr[1]); }
;   l_reg = l_reg * alpha + ps;
;     ...
;   PK4(p0, 0, pa0); PK4(p0, 8, pa1); PK4(p1, 0, pa2); PK4(p1, 8, pa3);
;     ...
; }
; __device__ __forceinline__ void qkt(f32x16& p0, f32x16& p1, const bf16* Ks, const bf16x8* qr, int r32, int hi) {
;   p0 = f32x16{}; p1 = f32x16{};
; #pragma unroll
;   for (int d0 = 0; d0 < 8; ++d0) { int cb = (d0 * 16 + hi * 8) * 2;
;     bf16x8 b0 = *reinterpret_cast<const bf16x8*>((const char*)Ks + KSWZ(r32, cb));
;     bf16x8 b1 = *reinterpret_cast<const bf16x8*>((const char*)Ks + KSWZ(32 + r32, cb));
;     p0 = __builtin_amdgcn_mfma_f32_32x32x16_bf16(b0, qr[d0], p0, 0, 0, 0);
;     p1 = __builtin_amdgcn_mfma_f32_32x32x16_bf16(b1, qr[d0], p1, 0, 0, 0); }
; }
; __device__ __forceinline__ int v_st(int k, int c) { const int kk = (k & ~0xC) | ((k & 4) << 1) | ((k & 8) >> 1); return ((kk >> 3) * 4 + (c >> 5)) * 512 + ((kk & 7) * 32 + (c & 31)) * 2; }
; __device__ __forceinline__ int v_rd_base(int lane) { return ((lane & 3) << 3) | (((lane >> 2) & 3) << 6) | (((lane >> 4) & 1) << 5) | (((lane >> 5) & 1) << 8); }
; template <int OFF> __device__ __forceinline__ s16x4 tr_read(int vb) {
;   s16x4 r; asm volatile("ds_read_b64_tr_b16 %0, %1 offset:%2" : "=&v"(r) : "v"(vb), "i"(OFF) : "memory"); return r;
; }
; template <int D0> __device__ __forceinline__ void pv_one(f32x16& od, int vb, bf16x8 pa0, bf16x8 pa1, bf16x8 pa2, bf16x8 pa3) {
;   const s16x4 l0 = tr_read<v_rd_off(D0, 0, 0)>(vb), h0 = tr_read<v_rd_off(D0, 0, 1)>(vb), l1 = tr_read<v_rd_off(D0, 1, 0)>(vb), h1 = tr_read<v_rd_off(D0, 1, 1)>(vb);
;   const s16x4 l2 = tr_read<v_rd_off(D0, 2, 0)>(vb), h2 = tr_read<v_rd_off(D0, 2, 1)>(vb), l3 = tr_read<v_rd_off(D0, 3, 0)>(vb), h3 = tr_read<v_rd_off(D0, 3, 1)>(vb);
;     ...
;   for (int p = 0; p + 2 < NP; p += 2) {
;     PAIR_FULL(0, 1, p + 1);
;     PAIR_FULL(1, 0, p + 2);
	v_mfma_f32_32x32x16_bf16 v[80:95], v[204:207], v[108:111], v[80:95]
	v_cvt_pk_bf16_f32 v193, v146, v147
	v_add_f32_e32 v222, v222, v146
	v_add_f32_e32 v254, v254, v147
	v_permlane32_swap_b32_e32 v189, v191
	s_waitcnt lgkmcnt(5)
	v_mfma_f32_32x32x16_bf16 v[64:79], v[208:211], v[104:107], v[64:79]
	v_cvt_pk_bf16_f32 v194, v148, v149
	v_add_f32_e32 v169, v169, v148
	v_add_f32_e32 v219, v219, v149
	s_waitcnt lgkmcnt(4)
	v_mfma_f32_32x32x16_bf16 v[80:95], v[212:215], v[104:107], v[80:95]
	ds_read_b64_tr_b16 v[200:201], v182 offset:16384
	ds_read_b64_tr_b16 v[202:203], v182 offset:18432
	v_cvt_pk_bf16_f32 v195, v150, v151
	v_add_f32_e32 v222, v222, v150
	v_add_f32_e32 v254, v254, v151
	s_waitcnt lgkmcnt(5)
	v_mfma_f32_32x32x16_bf16 v[64:79], v[230:233], v[100:103], v[64:79]
	ds_read_b64_tr_b16 v[204:205], v182 offset:20480
	ds_read_b64_tr_b16 v[206:207], v182 offset:22528
	v_cvt_pk_bf16_f32 v196, v152, v153
	v_add_f32_e32 v169, v169, v152
	v_add_f32_e32 v219, v219, v153
	v_permlane32_swap_b32_e32 v192, v194
	s_waitcnt lgkmcnt(6)
	v_mfma_f32_32x32x16_bf16 v[80:95], v[234:237], v[100:103], v[80:95]
	ds_read_b64_tr_b16 v[208:209], v182 offset:24576
	ds_read_b64_tr_b16 v[210:211], v182 offset:26624
	v_cvt_pk_bf16_f32 v197, v154, v155
	v_add_f32_e32 v222, v222, v154
	v_add_f32_e32 v254, v254, v155
	v_permlane32_swap_b32_e32 v193, v195
	s_waitcnt lgkmcnt(7)
	v_mfma_f32_32x32x16_bf16 v[64:79], v[238:241], v[96:99], v[64:79]
	ds_read_b64_tr_b16 v[212:213], v182 offset:28672
	ds_read_b64_tr_b16 v[214:215], v182 offset:30720
	v_cvt_pk_bf16_f32 v198, v156, v157
	v_add_f32_e32 v169, v169, v156
	v_add_f32_e32 v219, v219, v157
	s_waitcnt lgkmcnt(8)
	v_mfma_f32_32x32x16_bf16 v[80:95], v[242:245], v[96:99], v[80:95]
	ds_read_b64_tr_b16 v[230:231], v182 offset:16896
	ds_read_b64_tr_b16 v[232:233], v182 offset:18944
	v_cvt_pk_bf16_f32 v199, v158, v159
	v_add_f32_e32 v222, v222, v158
	v_add_f32_e32 v254, v254, v159
	v_permlane32_swap_b32_e32 v196, v198
	v_permlane32_swap_b32_e32 v197, v199
	s_waitcnt lgkmcnt(8)
	v_mfma_f32_32x32x16_bf16 v[0:15], v[184:187], v[200:203], v[0:15]
	ds_read_b64_tr_b16 v[234:235], v182 offset:20992
	ds_read_b64_tr_b16 v[236:237], v182 offset:23040
	v_exp_f32_e32 v64, v64
	v_exp_f32_e32 v65, v65
	s_waitcnt lgkmcnt(8)
	v_mfma_f32_32x32x16_bf16 v[0:15], v[188:191], v[204:207], v[0:15]
	ds_read_b64_tr_b16 v[238:239], v182 offset:25088
	ds_read_b64_tr_b16 v[240:241], v182 offset:27136
	v_exp_f32_e32 v66, v66
	v_exp_f32_e32 v67, v67
	s_waitcnt vmcnt(3)
	ds_write_b128 v181, v[246:249] offset:0
	s_waitcnt lgkmcnt(9)
	v_mfma_f32_32x32x16_bf16 v[0:15], v[192:195], v[208:211], v[0:15]
	ds_read_b64_tr_b16 v[242:243], v182 offset:29184
	ds_read_b64_tr_b16 v[244:245], v182 offset:31232
	v_exp_f32_e32 v68, v68
	v_exp_f32_e32 v69, v69
	s_waitcnt lgkmcnt(9)
	v_mfma_f32_32x32x16_bf16 v[0:15], v[196:199], v[212:215], v[0:15]
	ds_read_b64_tr_b16 v[200:201], v182 offset:17408
	ds_read_b64_tr_b16 v[202:203], v182 offset:19456
	v_exp_f32_e32 v70, v70
	v_exp_f32_e32 v71, v71
	s_waitcnt vmcnt(2)
	ds_write_b128 v181, v[250:253] offset:8192
	s_waitcnt lgkmcnt(10)
	v_mfma_f32_32x32x16_bf16 v[48:63], v[184:187], v[230:233], v[48:63]
	ds_read_b64_tr_b16 v[204:205], v182 offset:21504
	ds_read_b64_tr_b16 v[206:207], v182 offset:23552
	v_exp_f32_e32 v72, v72
	v_exp_f32_e32 v73, v73
	s_waitcnt lgkmcnt(10)
	v_mfma_f32_32x32x16_bf16 v[48:63], v[188:191], v[234:237], v[48:63]
	ds_read_b64_tr_b16 v[208:209], v182 offset:25600
	ds_read_b64_tr_b16 v[210:211], v182 offset:27648
	v_exp_f32_e32 v74, v74
	v_exp_f32_e32 v75, v75
	s_waitcnt vmcnt(1)
	ds_write_b128 v180, v[164:167] offset:49152
	s_waitcnt lgkmcnt(11)
	v_mfma_f32_32x32x16_bf16 v[48:63], v[192:195], v[238:241], v[48:63]
	ds_read_b64_tr_b16 v[212:213], v182 offset:29696
	ds_read_b64_tr_b16 v[214:215], v182 offset:31744
	v_exp_f32_e32 v76, v76
	v_exp_f32_e32 v77, v77
	s_waitcnt lgkmcnt(10)
	v_mfma_f32_32x32x16_bf16 v[48:63], v[196:199], v[242:245], v[48:63]
	ds_read_b64_tr_b16 v[230:231], v182 offset:17920
	ds_read_b64_tr_b16 v[232:233], v182 offset:19968
	v_exp_f32_e32 v78, v78
	v_exp_f32_e32 v79, v79
	s_waitcnt vmcnt(0)
	ds_write_b128 v180, v[160:163] offset:57344
	s_waitcnt lgkmcnt(11)
	v_mfma_f32_32x32x16_bf16 v[32:47], v[184:187], v[200:203], v[32:47]
	ds_read_b64_tr_b16 v[234:235], v182 offset:22016
	ds_read_b64_tr_b16 v[236:237], v182 offset:24064
	ds_read_b128 v[200:203], v172 offset:49152
	v_exp_f32_e32 v80, v80
	v_exp_f32_e32 v81, v81
	s_waitcnt lgkmcnt(11)
	v_mfma_f32_32x32x16_bf16 v[32:47], v[188:191], v[204:207], v[32:47]
	ds_read_b64_tr_b16 v[238:239], v182 offset:26112
	ds_read_b64_tr_b16 v[240:241], v182 offset:28160
	ds_read_b128 v[204:207], v172 offset:57344
	v_exp_f32_e32 v82, v82
	v_exp_f32_e32 v83, v83
	s_waitcnt lgkmcnt(12)
	v_mfma_f32_32x32x16_bf16 v[32:47], v[192:195], v[208:211], v[32:47]
	ds_read_b64_tr_b16 v[242:243], v182 offset:30208
	ds_read_b64_tr_b16 v[244:245], v182 offset:32256
	ds_read_b128 v[208:211], v173 offset:49152
	v_exp_f32_e32 v84, v84
	v_exp_f32_e32 v85, v85
	s_waitcnt lgkmcnt(12)
	v_mfma_f32_32x32x16_bf16 v[32:47], v[196:199], v[212:215], v[32:47]
	ds_read_b128 v[212:215], v173 offset:57344
	v_exp_f32_e32 v86, v86
	v_exp_f32_e32 v87, v87
	s_waitcnt lgkmcnt(11)
	v_mfma_f32_32x32x16_bf16 v[16:31], v[184:187], v[230:233], v[16:31]
	ds_read_b128 v[230:233], v174 offset:49152
	v_exp_f32_e32 v88, v88
	v_exp_f32_e32 v89, v89
	s_waitcnt lgkmcnt(9)
	v_mfma_f32_32x32x16_bf16 v[16:31], v[188:191], v[234:237], v[16:31]
	ds_read_b128 v[234:237], v174 offset:57344
	v_exp_f32_e32 v90, v90
	v_exp_f32_e32 v91, v91
	s_waitcnt lgkmcnt(7)
	v_mfma_f32_32x32x16_bf16 v[16:31], v[192:195], v[238:241], v[16:31]
	ds_read_b128 v[238:241], v175 offset:49152
	v_exp_f32_e32 v92, v92
	v_exp_f32_e32 v93, v93
	s_waitcnt lgkmcnt(5)
	v_mfma_f32_32x32x16_bf16 v[16:31], v[196:199], v[242:245], v[16:31]
	ds_read_b128 v[242:245], v175 offset:57344
	v_exp_f32_e32 v94, v94
	v_exp_f32_e32 v95, v95
	s_barrier
; __device__ __forceinline__ void finishSM(f32x16& p0, f32x16& p1, float alpha, float& l_reg, bf16x8& pa0, bf16x8& pa1, bf16x8& pa2, bf16x8& pa3) {
; #pragma unroll
;   for (int r = 0; r < 16; ++r) p1[r] = __builtin_amdgcn_exp2f(p1[r]);
;   float ps = 0;
; #pragma unroll
;   for (int r = 0; r < 16; ++r) ps += p0[r];
; #pragma unroll
;   for (int r = 0; r < 16; ++r) ps += p1[r];
;   { auto rr = __builtin_amdgcn_permlane32_swap(__float_as_uint(ps), __float_as_uint(ps), false, false);
;     ps = __uint_as_float(rr[0]) + __uint_as_float(rr[1]); }
;   l_reg = l_reg * alpha + ps;
;     ...
;   PK4(p0, 0, pa0); PK4(p0, 8, pa1); PK4(p1, 0, pa2); PK4(p1, 8, pa3);
;     ...
; }
; __device__ __forceinline__ void qkt(f32x16& p0, f32x16& p1, const bf16* Ks, const bf16x8* qr, int r32, int hi) {
;   p0 = f32x16{}; p1 = f32x16{};
; #pragma unroll
;   for (int d0 = 0; d0 < 8; ++d0) { int cb = (d0 * 16 + hi * 8) * 2;
;     bf16x8 b0 = *reinterpret_cast<const bf16x8*>((const char*)Ks + KSWZ(r32, cb));
;     bf16x8 b1 = *reinterpret_cast<const bf16x8*>((const char*)Ks + KSWZ(32 + r32, cb));
;     p0 = __builtin_amdgcn_mfma_f32_32x32x16_bf16(b0, qr[d0], p0, 0, 0, 0);
;     p1 = __builtin_amdgcn_mfma_f32_32x32x16_bf16(b1, qr[d0], p1, 0, 0, 0); }
; }
; __device__ __forceinline__ int v_st(int k, int c) { const int kk = (k & ~0xC) | ((k & 4) << 1) | ((k & 8) >> 1); return ((kk >> 3) * 4 + (c >> 5)) * 512 + ((kk & 7) * 32 + (c & 31)) * 2; }
; __device__ __forceinline__ int v_rd_base(int lane) { return ((lane & 3) << 3) | (((lane >> 2) & 3) << 6) | (((lane >> 4) & 1) << 5) | (((lane >> 5) & 1) << 8); }
; template <int OFF> __device__ __forceinline__ s16x4 tr_read(int vb) {
;   s16x4 r; asm volatile("ds_read_b64_tr_b16 %0, %1 offset:%2" : "=&v"(r) : "v"(vb), "i"(OFF) : "memory"); return r;
; }
; template <int D0> __device__ __forceinline__ void pv_one(f32x16& od, int vb, bf16x8 pa0, bf16x8 pa1, bf16x8 pa2, bf16x8 pa3) {
;   const s16x4 l0 = tr_read<v_rd_off(D0, 0, 0)>(vb), h0 = tr_read<v_rd_off(D0, 0, 1)>(vb), l1 = tr_read<v_rd_off(D0, 1, 0)>(vb), h1 = tr_read<v_rd_off(D0, 1, 1)>(vb);
;   const s16x4 l2 = tr_read<v_rd_off(D0, 2, 0)>(vb), h2 = tr_read<v_rd_off(D0, 2, 1)>(vb), l3 = tr_read<v_rd_off(D0, 3, 0)>(vb), h3 = tr_read<v_rd_off(D0, 3, 1)>(vb);
;     ...
;   for (int p = 0; p + 2 < NP; p += 2) {
;     PAIR_FULL(0, 1, p + 1);
;     PAIR_FULL(1, 0, p + 2);
	v_mfma_f32_32x32x16_bf16 v[128:143], v[200:203], v[124:127], 0
	ds_read_b128 v[200:203], v176 offset:49152
	v_cvt_pk_bf16_f32 v184, v64, v65
	v_add_f32_e32 v169, v169, v64
	v_add_f32_e32 v219, v219, v65
	global_load_dwordx4 v[246:249], v183, s[98:99]
	v_mfma_f32_32x32x16_bf16 v[144:159], v[204:207], v[124:127], 0
	ds_read_b128 v[204:207], v176 offset:57344
	v_cvt_pk_bf16_f32 v185, v66, v67
	v_add_f32_e32 v222, v222, v66
	v_add_f32_e32 v254, v254, v67
	s_waitcnt lgkmcnt(7)
	v_mfma_f32_32x32x16_bf16 v[128:143], v[208:211], v[120:123], v[128:143]
	ds_read_b128 v[208:211], v177 offset:49152
	v_cvt_pk_bf16_f32 v186, v68, v69
	v_add_f32_e32 v169, v169, v68
	v_add_f32_e32 v219, v219, v69
	global_load_dwordx4 v[250:253], v183, s[100:101]
	s_add_u32 s98, s98, 0x150000
	s_addc_u32 s99, s99, 0
	s_add_u32 s100, s100, 0x150000
	s_addc_u32 s101, s101, 0
	s_waitcnt lgkmcnt(7)
	v_mfma_f32_32x32x16_bf16 v[144:159], v[212:215], v[120:123], v[144:159]
	ds_read_b128 v[212:215], v177 offset:57344
	v_cvt_pk_bf16_f32 v187, v70, v71
	v_add_f32_e32 v222, v222, v70
	v_add_f32_e32 v254, v254, v71
	s_waitcnt lgkmcnt(7)
	v_mfma_f32_32x32x16_bf16 v[128:143], v[230:233], v[116:119], v[128:143]
	ds_read_b128 v[230:233], v178 offset:49152
	v_cvt_pk_bf16_f32 v188, v72, v73
	v_add_f32_e32 v169, v169, v72
	v_add_f32_e32 v219, v219, v73
	v_permlane32_swap_b32_e32 v184, v186
	global_load_dwordx4 v[164:167], v183, s[0:1] offset:512
	s_waitcnt lgkmcnt(7)
	v_mfma_f32_32x32x16_bf16 v[144:159], v[234:237], v[116:119], v[144:159]
	ds_read_b128 v[234:237], v178 offset:57344
	v_cvt_pk_bf16_f32 v189, v74, v75
	v_add_f32_e32 v222, v222, v74
	v_add_f32_e32 v254, v254, v75
	v_permlane32_swap_b32_e32 v185, v187
	s_waitcnt lgkmcnt(7)
	v_mfma_f32_32x32x16_bf16 v[128:143], v[238:241], v[112:115], v[128:143]
	ds_read_b128 v[238:241], v179 offset:49152
	v_cvt_pk_bf16_f32 v190, v76, v77
	v_add_f32_e32 v169, v169, v76
	v_add_f32_e32 v219, v219, v77
	global_load_dwordx4 v[160:163], v183, s[4:5] offset:512
	s_add_u32 s0, s0, 0x150000
	s_addc_u32 s1, s1, 0
	s_add_u32 s4, s4, 0x150000
	s_addc_u32 s5, s5, 0
	s_waitcnt lgkmcnt(7)
	v_mfma_f32_32x32x16_bf16 v[144:159], v[242:245], v[112:115], v[144:159]
	ds_read_b128 v[242:245], v179 offset:57344
	v_cvt_pk_bf16_f32 v191, v78, v79
	v_add_f32_e32 v222, v222, v78
	v_add_f32_e32 v254, v254, v79
	s_waitcnt lgkmcnt(7)
	v_mfma_f32_32x32x16_bf16 v[128:143], v[200:203], v[108:111], v[128:143]
	v_cvt_pk_bf16_f32 v192, v80, v81
	v_add_f32_e32 v169, v169, v80
	v_add_f32_e32 v219, v219, v81
	v_permlane32_swap_b32_e32 v188, v190
	s_waitcnt lgkmcnt(6)
	v_mfma_f32_32x32x16_bf16 v[144:159], v[204:207], v[108:111], v[144:159]
	v_cvt_pk_bf16_f32 v193, v82, v83
	v_add_f32_e32 v222, v222, v82
	v_add_f32_e32 v254, v254, v83
	v_permlane32_swap_b32_e32 v189, v191
	s_waitcnt lgkmcnt(5)
	v_mfma_f32_32x32x16_bf16 v[128:143], v[208:211], v[104:107], v[128:143]
	v_cvt_pk_bf16_f32 v194, v84, v85
	v_add_f32_e32 v169, v169, v84
	v_add_f32_e32 v219, v219, v85
	s_waitcnt lgkmcnt(4)
	v_mfma_f32_32x32x16_bf16 v[144:159], v[212:215], v[104:107], v[144:159]
	ds_read_b64_tr_b16 v[200:201], v182 offset:32768
	ds_read_b64_tr_b16 v[202:203], v182 offset:34816
	v_cvt_pk_bf16_f32 v195, v86, v87
	v_add_f32_e32 v222, v222, v86
	v_add_f32_e32 v254, v254, v87
	s_waitcnt lgkmcnt(5)
	v_mfma_f32_32x32x16_bf16 v[128:143], v[230:233], v[100:103], v[128:143]
	ds_read_b64_tr_b16 v[204:205], v182 offset:36864
	ds_read_b64_tr_b16 v[206:207], v182 offset:38912
	v_cvt_pk_bf16_f32 v196, v88, v89
	v_add_f32_e32 v169, v169, v88
	v_add_f32_e32 v219, v219, v89
	v_permlane32_swap_b32_e32 v192, v194
	s_waitcnt lgkmcnt(6)
	v_mfma_f32_32x32x16_bf16 v[144:159], v[234:237], v[100:103], v[144:159]
	ds_read_b64_tr_b16 v[208:209], v182 offset:40960
	ds_read_b64_tr_b16 v[210:211], v182 offset:43008
	v_cvt_pk_bf16_f32 v197, v90, v91
	v_add_f32_e32 v222, v222, v90
	v_add_f32_e32 v254, v254, v91
	v_permlane32_swap_b32_e32 v193, v195
	s_waitcnt lgkmcnt(7)
	v_mfma_f32_32x32x16_bf16 v[128:143], v[238:241], v[96:99], v[128:143]
	ds_read_b64_tr_b16 v[212:213], v182 offset:45056
	ds_read_b64_tr_b16 v[214:215], v182 offset:47104
	v_cvt_pk_bf16_f32 v198, v92, v93
	v_add_f32_e32 v169, v169, v92
	v_add_f32_e32 v219, v219, v93
	s_waitcnt lgkmcnt(8)
	v_mfma_f32_32x32x16_bf16 v[144:159], v[242:245], v[96:99], v[144:159]
	ds_read_b64_tr_b16 v[230:231], v182 offset:33280
	ds_read_b64_tr_b16 v[232:233], v182 offset:35328
	v_cvt_pk_bf16_f32 v199, v94, v95
	v_add_f32_e32 v222, v222, v94
	v_add_f32_e32 v254, v254, v95
	v_permlane32_swap_b32_e32 v196, v198
	v_permlane32_swap_b32_e32 v197, v199
	s_waitcnt lgkmcnt(8)
	v_mfma_f32_32x32x16_bf16 v[0:15], v[184:187], v[200:203], v[0:15]
	ds_read_b64_tr_b16 v[234:235], v182 offset:37376
	ds_read_b64_tr_b16 v[236:237], v182 offset:39424
	v_exp_f32_e32 v128, v128
	v_exp_f32_e32 v129, v129
	s_waitcnt lgkmcnt(8)
	v_mfma_f32_32x32x16_bf16 v[0:15], v[188:191], v[204:207], v[0:15]
	ds_read_b64_tr_b16 v[238:239], v182 offset:41472
	ds_read_b64_tr_b16 v[240:241], v182 offset:43520
	v_exp_f32_e32 v130, v130
	v_exp_f32_e32 v131, v131
	s_waitcnt vmcnt(3)
	ds_write_b128 v181, v[246:249] offset:16384
	s_waitcnt lgkmcnt(9)
	v_mfma_f32_32x32x16_bf16 v[0:15], v[192:195], v[208:211], v[0:15]
	ds_read_b64_tr_b16 v[242:243], v182 offset:45568
	ds_read_b64_tr_b16 v[244:245], v182 offset:47616
	v_exp_f32_e32 v132, v132
	v_exp_f32_e32 v133, v133
	s_waitcnt lgkmcnt(9)
	v_mfma_f32_32x32x16_bf16 v[0:15], v[196:199], v[212:215], v[0:15]
	ds_read_b64_tr_b16 v[200:201], v182 offset:33792
	ds_read_b64_tr_b16 v[202:203], v182 offset:35840
	v_exp_f32_e32 v134, v134
	v_exp_f32_e32 v135, v135
	s_waitcnt vmcnt(2)
; __device__ __forceinline__ void finishSM(f32x16& p0, f32x16& p1, float alpha, float& l_reg, bf16x8& pa0, bf16x8& pa1, bf16x8& pa2, bf16x8& pa3) {
; #pragma unroll
;   for (int r = 0; r < 16; ++r) p1[r] = __builtin_amdgcn_exp2f(p1[r]);
;   float ps = 0;
; #pragma unroll
;   for (int r = 0; r < 16; ++r) ps += p0[r];
; #pragma unroll
;   for (int r = 0; r < 16; ++r) ps += p1[r];
;   { auto rr = __builtin_amdgcn_permlane32_swap(__float_as_uint(ps), __float_as_uint(ps), false, false);
;     ps = __uint_as_float(rr[0]) + __uint_as_float(rr[1]); }
;   l_reg = l_reg * alpha + ps;
;     ...
;   PK4(p0, 0, pa0); PK4(p0, 8, pa1); PK4(p1, 0, pa2); PK4(p1, 8, pa3);
;     ...
; }
; __device__ __forceinline__ void qkt(f32x16& p0, f32x16& p1, const bf16* Ks, const bf16x8* qr, int r32, int hi) {
;   p0 = f32x16{}; p1 = f32x16{};
; #pragma unroll
;   for (int d0 = 0; d0 < 8; ++d0) { int cb = (d0 * 16 + hi * 8) * 2;
;     bf16x8 b0 = *reinterpret_cast<const bf16x8*>((const char*)Ks + KSWZ(r32, cb));
;     bf16x8 b1 = *reinterpret_cast<const bf16x8*>((const char*)Ks + KSWZ(32 + r32, cb));
;     p0 = __builtin_amdgcn_mfma_f32_32x32x16_bf16(b0, qr[d0], p0, 0, 0, 0);
;     p1 = __builtin_amdgcn_mfma_f32_32x32x16_bf16(b1, qr[d0], p1, 0, 0, 0); }
; }
; __device__ __forceinline__ int v_st(int k, int c) { const int kk = (k & ~0xC) | ((k & 4) << 1) | ((k & 8) >> 1); return ((kk >> 3) * 4 + (c >> 5)) * 512 + ((kk & 7) * 32 + (c & 31)) * 2; }
; __device__ __forceinline__ int v_rd_base(int lane) { return ((lane & 3) << 3) | (((lane >> 2) & 3) << 6) | (((lane >> 4) & 1) << 5) | (((lane >> 5) & 1) << 8); }
; template <int OFF> __device__ __forceinline__ s16x4 tr_read(int vb) {
;   s16x4 r; asm volatile("ds_read_b64_tr_b16 %0, %1 offset:%2" : "=&v"(r) : "v"(vb), "i"(OFF) : "memory"); return r;
; }
; template <int D0> __device__ __forceinline__ void pv_one(f32x16& od, int vb, bf16x8 pa0, bf16x8 pa1, bf16x8 pa2, bf16x8 pa3) {
;   const s16x4 l0 = tr_read<v_rd_off(D0, 0, 0)>(vb), h0 = tr_read<v_rd_off(D0, 0, 1)>(vb), l1 = tr_read<v_rd_off(D0, 1, 0)>(vb), h1 = tr_read<v_rd_off(D0, 1, 1)>(vb);
;   const s16x4 l2 = tr_read<v_rd_off(D0, 2, 0)>(vb), h2 = tr_read<v_rd_off(D0, 2, 1)>(vb), l3 = tr_read<v_rd_off(D0, 3, 0)>(vb), h3 = tr_read<v_rd_off(D0, 3, 1)>(vb);
;     ...
;   for (int p = 0; p + 2 < NP; p += 2) {
;     PAIR_FULL(0, 1, p + 1);
;     PAIR_FULL(1, 0, p + 2);
	ds_write_b128 v181, v[250:253] offset:24576
	s_waitcnt lgkmcnt(10)
	v_mfma_f32_32x32x16_bf16 v[48:63], v[184:187], v[230:233], v[48:63]
	ds_read_b64_tr_b16 v[204:205], v182 offset:37888
	ds_read_b64_tr_b16 v[206:207], v182 offset:39936
	v_exp_f32_e32 v136, v136
	v_exp_f32_e32 v137, v137
	s_waitcnt lgkmcnt(10)
	v_mfma_f32_32x32x16_bf16 v[48:63], v[188:191], v[234:237], v[48:63]
	ds_read_b64_tr_b16 v[208:209], v182 offset:41984
	ds_read_b64_tr_b16 v[210:211], v182 offset:44032
	v_exp_f32_e32 v138, v138
	v_exp_f32_e32 v139, v139
	s_waitcnt vmcnt(1)
	ds_write_b128 v180, v[164:167] offset:0
	s_waitcnt lgkmcnt(11)
	v_mfma_f32_32x32x16_bf16 v[48:63], v[192:195], v[238:241], v[48:63]
	ds_read_b64_tr_b16 v[212:213], v182 offset:46080
	ds_read_b64_tr_b16 v[214:215], v182 offset:48128
	v_exp_f32_e32 v140, v140
	v_exp_f32_e32 v141, v141
	s_waitcnt lgkmcnt(10)
	v_mfma_f32_32x32x16_bf16 v[48:63], v[196:199], v[242:245], v[48:63]
	ds_read_b64_tr_b16 v[230:231], v182 offset:34304
	ds_read_b64_tr_b16 v[232:233], v182 offset:36352
	v_exp_f32_e32 v142, v142
	v_exp_f32_e32 v143, v143
	s_waitcnt vmcnt(0)
	ds_write_b128 v180, v[160:163] offset:8192
	s_waitcnt lgkmcnt(11)
	v_mfma_f32_32x32x16_bf16 v[32:47], v[184:187], v[200:203], v[32:47]
	ds_read_b64_tr_b16 v[234:235], v182 offset:38400
	ds_read_b64_tr_b16 v[236:237], v182 offset:40448
	ds_read_b128 v[200:203], v172 offset:0
	v_exp_f32_e32 v144, v144
	v_exp_f32_e32 v145, v145
	s_waitcnt lgkmcnt(11)
	v_mfma_f32_32x32x16_bf16 v[32:47], v[188:191], v[204:207], v[32:47]
	ds_read_b64_tr_b16 v[238:239], v182 offset:42496
	ds_read_b64_tr_b16 v[240:241], v182 offset:44544
	ds_read_b128 v[204:207], v172 offset:8192
	v_exp_f32_e32 v146, v146
	v_exp_f32_e32 v147, v147
	s_waitcnt lgkmcnt(12)
	v_mfma_f32_32x32x16_bf16 v[32:47], v[192:195], v[208:211], v[32:47]
	ds_read_b64_tr_b16 v[242:243], v182 offset:46592
	ds_read_b64_tr_b16 v[244:245], v182 offset:48640
	ds_read_b128 v[208:211], v173 offset:0
	v_exp_f32_e32 v148, v148
	v_exp_f32_e32 v149, v149
	s_waitcnt lgkmcnt(12)
	v_mfma_f32_32x32x16_bf16 v[32:47], v[196:199], v[212:215], v[32:47]
	ds_read_b128 v[212:215], v173 offset:8192
	v_exp_f32_e32 v150, v150
	v_exp_f32_e32 v151, v151
	s_waitcnt lgkmcnt(11)
	v_mfma_f32_32x32x16_bf16 v[16:31], v[184:187], v[230:233], v[16:31]
	ds_read_b128 v[230:233], v174 offset:0
	v_exp_f32_e32 v152, v152
	v_exp_f32_e32 v153, v153
	s_waitcnt lgkmcnt(9)
	v_mfma_f32_32x32x16_bf16 v[16:31], v[188:191], v[234:237], v[16:31]
	ds_read_b128 v[234:237], v174 offset:8192
	v_exp_f32_e32 v154, v154
	v_exp_f32_e32 v155, v155
	s_waitcnt lgkmcnt(7)
	v_mfma_f32_32x32x16_bf16 v[16:31], v[192:195], v[238:241], v[16:31]
	ds_read_b128 v[238:241], v175 offset:0
	v_exp_f32_e32 v156, v156
	v_exp_f32_e32 v157, v157
	s_waitcnt lgkmcnt(5)
	v_mfma_f32_32x32x16_bf16 v[16:31], v[196:199], v[242:245], v[16:31]
	ds_read_b128 v[242:245], v175 offset:8192
	v_exp_f32_e32 v158, v158
	v_exp_f32_e32 v159, v159
	s_barrier
	v_mfma_f32_32x32x16_bf16 v[64:79], v[200:203], v[124:127], 0
	ds_read_b128 v[200:203], v176 offset:0
	v_cvt_pk_bf16_f32 v184, v128, v129
	v_add_f32_e32 v169, v169, v128
	v_add_f32_e32 v219, v219, v129
	global_load_dwordx4 v[246:249], v183, s[98:99]
	v_mfma_f32_32x32x16_bf16 v[80:95], v[204:207], v[124:127], 0
	ds_read_b128 v[204:207], v176 offset:8192
	v_cvt_pk_bf16_f32 v185, v130, v131
	v_add_f32_e32 v222, v222, v130
	v_add_f32_e32 v254, v254, v131
	s_waitcnt lgkmcnt(7)
	v_mfma_f32_32x32x16_bf16 v[64:79], v[208:211], v[120:123], v[64:79]
	ds_read_b128 v[208:211], v177 offset:0
	v_cvt_pk_bf16_f32 v186, v132, v133
	v_add_f32_e32 v169, v169, v132
	v_add_f32_e32 v219, v219, v133
	global_load_dwordx4 v[250:253], v183, s[100:101]
	s_add_u32 s98, s98, 0x150000
	s_addc_u32 s99, s99, 0
	s_add_u32 s100, s100, 0x150000
	s_addc_u32 s101, s101, 0
	s_waitcnt lgkmcnt(7)
	v_mfma_f32_32x32x16_bf16 v[80:95], v[212:215], v[120:123], v[80:95]
	ds_read_b128 v[212:215], v177 offset:8192
	v_cvt_pk_bf16_f32 v187, v134, v135
	v_add_f32_e32 v222, v222, v134
	v_add_f32_e32 v254, v254, v135
	s_waitcnt lgkmcnt(7)
	v_mfma_f32_32x32x16_bf16 v[64:79], v[230:233], v[116:119], v[64:79]
	ds_read_b128 v[230:233], v178 offset:0
	v_cvt_pk_bf16_f32 v188, v136, v137
	v_add_f32_e32 v169, v169, v136
	v_add_f32_e32 v219, v219, v137
	v_permlane32_swap_b32_e32 v184, v186
	global_load_dwordx4 v[164:167], v183, s[0:1] offset:512
	s_waitcnt lgkmcnt(7)
	v_mfma_f32_32x32x16_bf16 v[80:95], v[234:237], v[116:119], v[80:95]
	ds_read_b128 v[234:237], v178 offset:8192
	v_cvt_pk_bf16_f32 v189, v138, v139
	v_add_f32_e32 v222, v222, v138
	v_add_f32_e32 v254, v254, v139
	v_permlane32_swap_b32_e32 v185, v187
	s_waitcnt lgkmcnt(7)
	v_mfma_f32_32x32x16_bf16 v[64:79], v[238:241], v[112:115], v[64:79]
	ds_read_b128 v[238:241], v179 offset:0
	v_cvt_pk_bf16_f32 v190, v140, v141
	v_add_f32_e32 v169, v169, v140
	v_add_f32_e32 v219, v219, v141
	global_load_dwordx4 v[160:163], v183, s[4:5] offset:512
	s_add_u32 s0, s0, 0x150000
	s_addc_u32 s1, s1, 0
	s_add_u32 s4, s4, 0x150000
	s_addc_u32 s5, s5, 0
	s_waitcnt lgkmcnt(7)
	v_mfma_f32_32x32x16_bf16 v[80:95], v[242:245], v[112:115], v[80:95]
	ds_read_b128 v[242:245], v179 offset:8192
	v_cvt_pk_bf16_f32 v191, v142, v143
	v_add_f32_e32 v222, v222, v142
	v_add_f32_e32 v254, v254, v143
	s_waitcnt lgkmcnt(7)
	v_mfma_f32_32x32x16_bf16 v[64:79], v[200:203], v[108:111], v[64:79]
	v_cvt_pk_bf16_f32 v192, v144, v145
	v_add_f32_e32 v169, v169, v144
	v_add_f32_e32 v219, v219, v145
	v_permlane32_swap_b32_e32 v188, v190
	s_waitcnt lgkmcnt(6)
	v_mfma_f32_32x32x16_bf16 v[80:95], v[204:207], v[108:111], v[80:95]
	v_cvt_pk_bf16_f32 v193, v146, v147
	v_add_f32_e32 v222, v222, v146
	v_add_f32_e32 v254, v254, v147
	v_permlane32_swap_b32_e32 v189, v191
	s_waitcnt lgkmcnt(5)
; __device__ __forceinline__ void finishSM(f32x16& p0, f32x16& p1, float alpha, float& l_reg, bf16x8& pa0, bf16x8& pa1, bf16x8& pa2, bf16x8& pa3) {
; #pragma unroll
;   for (int r = 0; r < 16; ++r) p1[r] = __builtin_amdgcn_exp2f(p1[r]);
;   float ps = 0;
; #pragma unroll
;   for (int r = 0; r < 16; ++r) ps += p0[r];
; #pragma unroll
;   for (int r = 0; r < 16; ++r) ps += p1[r];
;   { auto rr = __builtin_amdgcn_permlane32_swap(__float_as_uint(ps), __float_as_uint(ps), false, false);
;     ps = __uint_as_float(rr[0]) + __uint_as_float(rr[1]); }
;   l_reg = l_reg * alpha + ps;
;     ...
;   PK4(p0, 0, pa0); PK4(p0, 8, pa1); PK4(p1, 0, pa2); PK4(p1, 8, pa3);
;     ...
; }
; __device__ __forceinline__ void qkt(f32x16& p0, f32x16& p1, const bf16* Ks, const bf16x8* qr, int r32, int hi) {
;   p0 = f32x16{}; p1 = f32x16{};
; #pragma unroll
;   for (int d0 = 0; d0 < 8; ++d0) { int cb = (d0 * 16 + hi * 8) * 2;
;     bf16x8 b0 = *reinterpret_cast<const bf16x8*>((const char*)Ks + KSWZ(r32, cb));
;     bf16x8 b1 = *reinterpret_cast<const bf16x8*>((const char*)Ks + KSWZ(32 + r32, cb));
;     p0 = __builtin_amdgcn_mfma_f32_32x32x16_bf16(b0, qr[d0], p0, 0, 0, 0);
;     p1 = __builtin_amdgcn_mfma_f32_32x32x16_bf16(b1, qr[d0], p1, 0, 0, 0); }
; }
; __device__ __forceinline__ int v_st(int k, int c) { const int kk = (k & ~0xC) | ((k & 4) << 1) | ((k & 8) >> 1); return ((kk >> 3) * 4 + (c >> 5)) * 512 + ((kk & 7) * 32 + (c & 31)) * 2; }
; __device__ __forceinline__ int v_rd_base(int lane) { return ((lane & 3) << 3) | (((lane >> 2) & 3) << 6) | (((lane >> 4) & 1) << 5) | (((lane >> 5) & 1) << 8); }
; template <int OFF> __device__ __forceinline__ s16x4 tr_read(int vb) {
;   s16x4 r; asm volatile("ds_read_b64_tr_b16 %0, %1 offset:%2" : "=&v"(r) : "v"(vb), "i"(OFF) : "memory"); return r;
; }
; template <int D0> __device__ __forceinline__ void pv_one(f32x16& od, int vb, bf16x8 pa0, bf16x8 pa1, bf16x8 pa2, bf16x8 pa3) {
;   const s16x4 l0 = tr_read<v_rd_off(D0, 0, 0)>(vb), h0 = tr_read<v_rd_off(D0, 0, 1)>(vb), l1 = tr_read<v_rd_off(D0, 1, 0)>(vb), h1 = tr_read<v_rd_off(D0, 1, 1)>(vb);
;   const s16x4 l2 = tr_read<v_rd_off(D0, 2, 0)>(vb), h2 = tr_read<v_rd_off(D0, 2, 1)>(vb), l3 = tr_read<v_rd_off(D0, 3, 0)>(vb), h3 = tr_read<v_rd_off(D0, 3, 1)>(vb);
;     ...
;   for (int p = 0; p + 2 < NP; p += 2) {
;     PAIR_FULL(0, 1, p + 1);
;     PAIR_FULL(1, 0, p + 2);
	v_mfma_f32_32x32x16_bf16 v[64:79], v[208:211], v[104:107], v[64:79]
	v_cvt_pk_bf16_f32 v194, v148, v149
	v_add_f32_e32 v169, v169, v148
	v_add_f32_e32 v219, v219, v149
	s_waitcnt lgkmcnt(4)
	v_mfma_f32_32x32x16_bf16 v[80:95], v[212:215], v[104:107], v[80:95]
	ds_read_b64_tr_b16 v[200:201], v182 offset:49152
	ds_read_b64_tr_b16 v[202:203], v182 offset:51200
	v_cvt_pk_bf16_f32 v195, v150, v151
	v_add_f32_e32 v222, v222, v150
	v_add_f32_e32 v254, v254, v151
	s_waitcnt lgkmcnt(5)
	v_mfma_f32_32x32x16_bf16 v[64:79], v[230:233], v[100:103], v[64:79]
	ds_read_b64_tr_b16 v[204:205], v182 offset:53248
	ds_read_b64_tr_b16 v[206:207], v182 offset:55296
	v_cvt_pk_bf16_f32 v196, v152, v153
	v_add_f32_e32 v169, v169, v152
	v_add_f32_e32 v219, v219, v153
	v_permlane32_swap_b32_e32 v192, v194
	s_waitcnt lgkmcnt(6)
	v_mfma_f32_32x32x16_bf16 v[80:95], v[234:237], v[100:103], v[80:95]
	ds_read_b64_tr_b16 v[208:209], v182 offset:57344
	ds_read_b64_tr_b16 v[210:211], v182 offset:59392
	v_cvt_pk_bf16_f32 v197, v154, v155
	v_add_f32_e32 v222, v222, v154
	v_add_f32_e32 v254, v254, v155
	v_permlane32_swap_b32_e32 v193, v195
	s_waitcnt lgkmcnt(7)
	v_mfma_f32_32x32x16_bf16 v[64:79], v[238:241], v[96:99], v[64:79]
	ds_read_b64_tr_b16 v[212:213], v182 offset:61440
	ds_read_b64_tr_b16 v[214:215], v182 offset:63488
	v_cvt_pk_bf16_f32 v198, v156, v157
	v_add_f32_e32 v169, v169, v156
	v_add_f32_e32 v219, v219, v157
	s_waitcnt lgkmcnt(8)
	v_mfma_f32_32x32x16_bf16 v[80:95], v[242:245], v[96:99], v[80:95]
	ds_read_b64_tr_b16 v[230:231], v182 offset:49664
	ds_read_b64_tr_b16 v[232:233], v182 offset:51712
	v_cvt_pk_bf16_f32 v199, v158, v159
	v_add_f32_e32 v222, v222, v158
	v_add_f32_e32 v254, v254, v159
	v_permlane32_swap_b32_e32 v196, v198
	v_permlane32_swap_b32_e32 v197, v199
	s_waitcnt lgkmcnt(8)
	v_mfma_f32_32x32x16_bf16 v[0:15], v[184:187], v[200:203], v[0:15]
	ds_read_b64_tr_b16 v[234:235], v182 offset:53760
	ds_read_b64_tr_b16 v[236:237], v182 offset:55808
	v_exp_f32_e32 v64, v64
	v_exp_f32_e32 v65, v65
	s_waitcnt lgkmcnt(8)
	v_mfma_f32_32x32x16_bf16 v[0:15], v[188:191], v[204:207], v[0:15]
	ds_read_b64_tr_b16 v[238:239], v182 offset:57856
	ds_read_b64_tr_b16 v[240:241], v182 offset:59904
	v_exp_f32_e32 v66, v66
	v_exp_f32_e32 v67, v67
	s_waitcnt vmcnt(3)
	ds_write_b128 v181, v[246:249] offset:32768
	s_waitcnt lgkmcnt(9)
	v_mfma_f32_32x32x16_bf16 v[0:15], v[192:195], v[208:211], v[0:15]
	ds_read_b64_tr_b16 v[242:243], v182 offset:61952
	ds_read_b64_tr_b16 v[244:245], v182 offset:64000
	v_exp_f32_e32 v68, v68
	v_exp_f32_e32 v69, v69
	s_waitcnt lgkmcnt(9)
	v_mfma_f32_32x32x16_bf16 v[0:15], v[196:199], v[212:215], v[0:15]
	ds_read_b64_tr_b16 v[200:201], v182 offset:50176
	ds_read_b64_tr_b16 v[202:203], v182 offset:52224
	v_exp_f32_e32 v70, v70
	v_exp_f32_e32 v71, v71
	s_waitcnt vmcnt(2)
	ds_write_b128 v181, v[250:253] offset:40960
	s_waitcnt lgkmcnt(10)
	v_mfma_f32_32x32x16_bf16 v[48:63], v[184:187], v[230:233], v[48:63]
	ds_read_b64_tr_b16 v[204:205], v182 offset:54272
	ds_read_b64_tr_b16 v[206:207], v182 offset:56320
	v_exp_f32_e32 v72, v72
	v_exp_f32_e32 v73, v73
	s_waitcnt lgkmcnt(10)
	v_mfma_f32_32x32x16_bf16 v[48:63], v[188:191], v[234:237], v[48:63]
	ds_read_b64_tr_b16 v[208:209], v182 offset:58368
	ds_read_b64_tr_b16 v[210:211], v182 offset:60416
	v_exp_f32_e32 v74, v74
	v_exp_f32_e32 v75, v75
	s_waitcnt vmcnt(1)
	ds_write_b128 v180, v[164:167] offset:16384
	s_waitcnt lgkmcnt(11)
	v_mfma_f32_32x32x16_bf16 v[48:63], v[192:195], v[238:241], v[48:63]
	ds_read_b64_tr_b16 v[212:213], v182 offset:62464
	ds_read_b64_tr_b16 v[214:215], v182 offset:64512
	v_exp_f32_e32 v76, v76
	v_exp_f32_e32 v77, v77
	s_waitcnt lgkmcnt(10)
	v_mfma_f32_32x32x16_bf16 v[48:63], v[196:199], v[242:245], v[48:63]
	ds_read_b64_tr_b16 v[230:231], v182 offset:50688
	ds_read_b64_tr_b16 v[232:233], v182 offset:52736
	v_exp_f32_e32 v78, v78
	v_exp_f32_e32 v79, v79
	s_waitcnt vmcnt(0)
	ds_write_b128 v180, v[160:163] offset:24576
	s_waitcnt lgkmcnt(11)
	v_mfma_f32_32x32x16_bf16 v[32:47], v[184:187], v[200:203], v[32:47]
	ds_read_b64_tr_b16 v[234:235], v182 offset:54784
	ds_read_b64_tr_b16 v[236:237], v182 offset:56832
	ds_read_b128 v[200:203], v172 offset:16384
	v_exp_f32_e32 v80, v80
	v_exp_f32_e32 v81, v81
	s_waitcnt lgkmcnt(11)
	v_mfma_f32_32x32x16_bf16 v[32:47], v[188:191], v[204:207], v[32:47]
	ds_read_b64_tr_b16 v[238:239], v182 offset:58880
	ds_read_b64_tr_b16 v[240:241], v182 offset:60928
	ds_read_b128 v[204:207], v172 offset:24576
	v_exp_f32_e32 v82, v82
	v_exp_f32_e32 v83, v83
	s_waitcnt lgkmcnt(12)
	v_mfma_f32_32x32x16_bf16 v[32:47], v[192:195], v[208:211], v[32:47]
	ds_read_b64_tr_b16 v[242:243], v182 offset:62976
	ds_read_b64_tr_b16 v[244:245], v182 offset:65024
	ds_read_b128 v[208:211], v173 offset:16384
	v_exp_f32_e32 v84, v84
	v_exp_f32_e32 v85, v85
	s_waitcnt lgkmcnt(12)
	v_mfma_f32_32x32x16_bf16 v[32:47], v[196:199], v[212:215], v[32:47]
	ds_read_b128 v[212:215], v173 offset:24576
	v_exp_f32_e32 v86, v86
	v_exp_f32_e32 v87, v87
	s_waitcnt lgkmcnt(11)
	v_mfma_f32_32x32x16_bf16 v[16:31], v[184:187], v[230:233], v[16:31]
	ds_read_b128 v[230:233], v174 offset:16384
	v_exp_f32_e32 v88, v88
	v_exp_f32_e32 v89, v89
	s_waitcnt lgkmcnt(9)
	v_mfma_f32_32x32x16_bf16 v[16:31], v[188:191], v[234:237], v[16:31]
	ds_read_b128 v[234:237], v174 offset:24576
	v_exp_f32_e32 v90, v90
	v_exp_f32_e32 v91, v91
	s_waitcnt lgkmcnt(7)
	v_mfma_f32_32x32x16_bf16 v[16:31], v[192:195], v[238:241], v[16:31]
	ds_read_b128 v[238:241], v175 offset:16384
	v_exp_f32_e32 v92, v92
	v_exp_f32_e32 v93, v93
	s_waitcnt lgkmcnt(5)
	v_mfma_f32_32x32x16_bf16 v[16:31], v[196:199], v[242:245], v[16:31]
	ds_read_b128 v[242:245], v175 offset:24576
	v_exp_f32_e32 v94, v94
	v_exp_f32_e32 v95, v95
	s_barrier
; __device__ __forceinline__ void finishSM(f32x16& p0, f32x16& p1, float alpha, float& l_reg, bf16x8& pa0, bf16x8& pa1, bf16x8& pa2, bf16x8& pa3) {
; #pragma unroll
;   for (int r = 0; r < 16; ++r) p1[r] = __builtin_amdgcn_exp2f(p1[r]);
;   float ps = 0;
; #pragma unroll
;   for (int r = 0; r < 16; ++r) ps += p0[r];
; #pragma unroll
;   for (int r = 0; r < 16; ++r) ps += p1[r];
;   { auto rr = __builtin_amdgcn_permlane32_swap(__float_as_uint(ps), __float_as_uint(ps), false, false);
;     ps = __uint_as_float(rr[0]) + __uint_as_float(rr[1]); }
;   l_reg = l_reg * alpha + ps;
;     ...
;   PK4(p0, 0, pa0); PK4(p0, 8, pa1); PK4(p1, 0, pa2); PK4(p1, 8, pa3);
;     ...
; }
; __device__ __forceinline__ void qkt(f32x16& p0, f32x16& p1, const bf16* Ks, const bf16x8* qr, int r32, int hi) {
;   p0 = f32x16{}; p1 = f32x16{};
; #pragma unroll
;   for (int d0 = 0; d0 < 8; ++d0) { int cb = (d0 * 16 + hi * 8) * 2;
;     bf16x8 b0 = *reinterpret_cast<const bf16x8*>((const char*)Ks + KSWZ(r32, cb));
;     bf16x8 b1 = *reinterpret_cast<const bf16x8*>((const char*)Ks + KSWZ(32 + r32, cb));
;     p0 = __builtin_amdgcn_mfma_f32_32x32x16_bf16(b0, qr[d0], p0, 0, 0, 0);
;     p1 = __builtin_amdgcn_mfma_f32_32x32x16_bf16(b1, qr[d0], p1, 0, 0, 0); }
; }
; __device__ __forceinline__ int v_st(int k, int c) { const int kk = (k & ~0xC) | ((k & 4) << 1) | ((k & 8) >> 1); return ((kk >> 3) * 4 + (c >> 5)) * 512 + ((kk & 7) * 32 + (c & 31)) * 2; }
; __device__ __forceinline__ int v_rd_base(int lane) { return ((lane & 3) << 3) | (((lane >> 2) & 3) << 6) | (((lane >> 4) & 1) << 5) | (((lane >> 5) & 1) << 8); }
; template <int OFF> __device__ __forceinline__ s16x4 tr_read(int vb) {
;   s16x4 r; asm volatile("ds_read_b64_tr_b16 %0, %1 offset:%2" : "=&v"(r) : "v"(vb), "i"(OFF) : "memory"); return r;
; }
; template <int D0> __device__ __forceinline__ void pv_one(f32x16& od, int vb, bf16x8 pa0, bf16x8 pa1, bf16x8 pa2, bf16x8 pa3) {
;   const s16x4 l0 = tr_read<v_rd_off(D0, 0, 0)>(vb), h0 = tr_read<v_rd_off(D0, 0, 1)>(vb), l1 = tr_read<v_rd_off(D0, 1, 0)>(vb), h1 = tr_read<v_rd_off(D0, 1, 1)>(vb);
;   const s16x4 l2 = tr_read<v_rd_off(D0, 2, 0)>(vb), h2 = tr_read<v_rd_off(D0, 2, 1)>(vb), l3 = tr_read<v_rd_off(D0, 3, 0)>(vb), h3 = tr_read<v_rd_off(D0, 3, 1)>(vb);
;     ...
;   for (int p = 0; p + 2 < NP; p += 2) {
;     PAIR_FULL(0, 1, p + 1);
;     PAIR_FULL(1, 0, p + 2);
;   }
	s_add_i32 s44, s44, 1
	s_cmp_lt_u32 s44, 63
	s_cbranch_scc1 .Ldense_loop
	v_mfma_f32_32x32x16_bf16 v[128:143], v[200:203], v[124:127], 0
	ds_read_b128 v[200:203], v176 offset:16384
	v_cvt_pk_bf16_f32 v184, v64, v65
	v_add_f32_e32 v169, v169, v64
	v_add_f32_e32 v219, v219, v65
	global_load_dwordx4 v[246:249], v183, s[98:99]
	v_mfma_f32_32x32x16_bf16 v[144:159], v[204:207], v[124:127], 0
	ds_read_b128 v[204:207], v176 offset:24576
	v_cvt_pk_bf16_f32 v185, v66, v67
	v_add_f32_e32 v222, v222, v66
	v_add_f32_e32 v254, v254, v67
	s_waitcnt lgkmcnt(7)
	v_mfma_f32_32x32x16_bf16 v[128:143], v[208:211], v[120:123], v[128:143]
	ds_read_b128 v[208:211], v177 offset:16384
	v_cvt_pk_bf16_f32 v186, v68, v69
	v_add_f32_e32 v169, v169, v68
	v_add_f32_e32 v219, v219, v69
	global_load_dwordx4 v[250:253], v183, s[100:101]
	s_add_u32 s98, s98, 0x150000
	s_addc_u32 s99, s99, 0
	s_add_u32 s100, s100, 0x150000
	s_addc_u32 s101, s101, 0
	s_waitcnt lgkmcnt(7)
	v_mfma_f32_32x32x16_bf16 v[144:159], v[212:215], v[120:123], v[144:159]
	ds_read_b128 v[212:215], v177 offset:24576
	v_cvt_pk_bf16_f32 v187, v70, v71
	v_add_f32_e32 v222, v222, v70
	v_add_f32_e32 v254, v254, v71
	s_waitcnt lgkmcnt(7)
	v_mfma_f32_32x32x16_bf16 v[128:143], v[230:233], v[116:119], v[128:143]
	ds_read_b128 v[230:233], v178 offset:16384
	v_cvt_pk_bf16_f32 v188, v72, v73
	v_add_f32_e32 v169, v169, v72
	v_add_f32_e32 v219, v219, v73
	v_permlane32_swap_b32_e32 v184, v186
	global_load_dwordx4 v[164:167], v183, s[0:1] offset:512
	s_waitcnt lgkmcnt(7)
	v_mfma_f32_32x32x16_bf16 v[144:159], v[234:237], v[116:119], v[144:159]
	ds_read_b128 v[234:237], v178 offset:24576
	v_cvt_pk_bf16_f32 v189, v74, v75
	v_add_f32_e32 v222, v222, v74
	v_add_f32_e32 v254, v254, v75
	v_permlane32_swap_b32_e32 v185, v187
	s_waitcnt lgkmcnt(7)
	v_mfma_f32_32x32x16_bf16 v[128:143], v[238:241], v[112:115], v[128:143]
	ds_read_b128 v[238:241], v179 offset:16384
	v_cvt_pk_bf16_f32 v190, v76, v77
	v_add_f32_e32 v169, v169, v76
	v_add_f32_e32 v219, v219, v77
	global_load_dwordx4 v[160:163], v183, s[4:5] offset:512
	s_add_u32 s0, s0, 0x150000
	s_addc_u32 s1, s1, 0
	s_add_u32 s4, s4, 0x150000
	s_addc_u32 s5, s5, 0
	s_waitcnt lgkmcnt(7)
	v_mfma_f32_32x32x16_bf16 v[144:159], v[242:245], v[112:115], v[144:159]
	ds_read_b128 v[242:245], v179 offset:24576
	v_cvt_pk_bf16_f32 v191, v78, v79
	v_add_f32_e32 v222, v222, v78
	v_add_f32_e32 v254, v254, v79
	s_waitcnt lgkmcnt(7)
	v_mfma_f32_32x32x16_bf16 v[128:143], v[200:203], v[108:111], v[128:143]
	v_cvt_pk_bf16_f32 v192, v80, v81
	v_add_f32_e32 v169, v169, v80
	v_add_f32_e32 v219, v219, v81
	v_permlane32_swap_b32_e32 v188, v190
	s_waitcnt lgkmcnt(6)
	v_mfma_f32_32x32x16_bf16 v[144:159], v[204:207], v[108:111], v[144:159]
	v_cvt_pk_bf16_f32 v193, v82, v83
	v_add_f32_e32 v222, v222, v82
	v_add_f32_e32 v254, v254, v83
	v_permlane32_swap_b32_e32 v189, v191
	s_waitcnt lgkmcnt(5)
	v_mfma_f32_32x32x16_bf16 v[128:143], v[208:211], v[104:107], v[128:143]
	v_cvt_pk_bf16_f32 v194, v84, v85
	v_add_f32_e32 v169, v169, v84
	v_add_f32_e32 v219, v219, v85
	s_waitcnt lgkmcnt(4)
	v_mfma_f32_32x32x16_bf16 v[144:159], v[212:215], v[104:107], v[144:159]
	ds_read_b64_tr_b16 v[200:201], v182 offset:0
	ds_read_b64_tr_b16 v[202:203], v182 offset:2048
	v_cvt_pk_bf16_f32 v195, v86, v87
	v_add_f32_e32 v222, v222, v86
	v_add_f32_e32 v254, v254, v87
	s_waitcnt lgkmcnt(5)
	v_mfma_f32_32x32x16_bf16 v[128:143], v[230:233], v[100:103], v[128:143]
	ds_read_b64_tr_b16 v[204:205], v182 offset:4096
	ds_read_b64_tr_b16 v[206:207], v182 offset:6144
	v_cvt_pk_bf16_f32 v196, v88, v89
	v_add_f32_e32 v169, v169, v88
	v_add_f32_e32 v219, v219, v89
	v_permlane32_swap_b32_e32 v192, v194
	s_waitcnt lgkmcnt(6)
	v_mfma_f32_32x32x16_bf16 v[144:159], v[234:237], v[100:103], v[144:159]
	ds_read_b64_tr_b16 v[208:209], v182 offset:8192
	ds_read_b64_tr_b16 v[210:211], v182 offset:10240
	v_cvt_pk_bf16_f32 v197, v90, v91
	v_add_f32_e32 v222, v222, v90
	v_add_f32_e32 v254, v254, v91
	v_permlane32_swap_b32_e32 v193, v195
	s_waitcnt lgkmcnt(7)
	v_mfma_f32_32x32x16_bf16 v[128:143], v[238:241], v[96:99], v[128:143]
	ds_read_b64_tr_b16 v[212:213], v182 offset:12288
	ds_read_b64_tr_b16 v[214:215], v182 offset:14336
	v_cvt_pk_bf16_f32 v198, v92, v93
	v_add_f32_e32 v169, v169, v92
	v_add_f32_e32 v219, v219, v93
	s_waitcnt lgkmcnt(8)
	v_mfma_f32_32x32x16_bf16 v[144:159], v[242:245], v[96:99], v[144:159]
	ds_read_b64_tr_b16 v[230:231], v182 offset:512
	ds_read_b64_tr_b16 v[232:233], v182 offset:2560
	v_cvt_pk_bf16_f32 v199, v94, v95
	v_add_f32_e32 v222, v222, v94
	v_add_f32_e32 v254, v254, v95
	v_permlane32_swap_b32_e32 v196, v198
	v_permlane32_swap_b32_e32 v197, v199
	s_waitcnt lgkmcnt(8)
	v_mfma_f32_32x32x16_bf16 v[0:15], v[184:187], v[200:203], v[0:15]
	ds_read_b64_tr_b16 v[234:235], v182 offset:4608
	ds_read_b64_tr_b16 v[236:237], v182 offset:6656
	v_exp_f32_e32 v128, v128
	v_exp_f32_e32 v129, v129
	s_waitcnt lgkmcnt(8)
	v_mfma_f32_32x32x16_bf16 v[0:15], v[188:191], v[204:207], v[0:15]
	ds_read_b64_tr_b16 v[238:239], v182 offset:8704
	ds_read_b64_tr_b16 v[240:241], v182 offset:10752
	v_exp_f32_e32 v130, v130
	v_exp_f32_e32 v131, v131
	s_waitcnt vmcnt(3)
	ds_write_b128 v181, v[246:249] offset:49152
	s_waitcnt lgkmcnt(9)
	v_mfma_f32_32x32x16_bf16 v[0:15], v[192:195], v[208:211], v[0:15]
	ds_read_b64_tr_b16 v[242:243], v182 offset:12800
	ds_read_b64_tr_b16 v[244:245], v182 offset:14848
	v_exp_f32_e32 v132, v132
	v_exp_f32_e32 v133, v133
	s_waitcnt lgkmcnt(9)
	v_mfma_f32_32x32x16_bf16 v[0:15], v[196:199], v[212:215], v[0:15]
	ds_read_b64_tr_b16 v[200:201], v182 offset:1024
	ds_read_b64_tr_b16 v[202:203], v182 offset:3072
	v_exp_f32_e32 v134, v134
	v_exp_f32_e32 v135, v135
	s_waitcnt vmcnt(2)
; #define SBAR() __builtin_amdgcn_sched_barrier(0)
; __device__ __forceinline__ void qkt(f32x16& p0, f32x16& p1, const bf16* Ks, const bf16x8* qr, int r32, int hi) {
;   p0 = f32x16{}; p1 = f32x16{};
; #pragma unroll
;   for (int d0 = 0; d0 < 8; ++d0) { int cb = (d0 * 16 + hi * 8) * 2;
;     bf16x8 b0 = *reinterpret_cast<const bf16x8*>((const char*)Ks + KSWZ(r32, cb));
;     bf16x8 b1 = *reinterpret_cast<const bf16x8*>((const char*)Ks + KSWZ(32 + r32, cb));
;     p0 = __builtin_amdgcn_mfma_f32_32x32x16_bf16(b0, qr[d0], p0, 0, 0, 0);
;     p1 = __builtin_amdgcn_mfma_f32_32x32x16_bf16(b1, qr[d0], p1, 0, 0, 0); }
; }
; __device__ __forceinline__ int v_st(int k, int c) { const int kk = (k & ~0xC) | ((k & 4) << 1) | ((k & 8) >> 1); return ((kk >> 3) * 4 + (c >> 5)) * 512 + ((kk & 7) * 32 + (c & 31)) * 2; }
; __device__ __forceinline__ int v_rd_base(int lane) { return ((lane & 3) << 3) | (((lane >> 2) & 3) << 6) | (((lane >> 4) & 1) << 5) | (((lane >> 5) & 1) << 8); }
; template <int OFF> __device__ __forceinline__ s16x4 tr_read(int vb) {
;   s16x4 r; asm volatile("ds_read_b64_tr_b16 %0, %1 offset:%2" : "=&v"(r) : "v"(vb), "i"(OFF) : "memory"); return r;
; }
; template <int D0> __device__ __forceinline__ void pv_one(f32x16& od, int vb, bf16x8 pa0, bf16x8 pa1, bf16x8 pa2, bf16x8 pa3) {
;   const s16x4 l0 = tr_read<v_rd_off(D0, 0, 0)>(vb), h0 = tr_read<v_rd_off(D0, 0, 1)>(vb), l1 = tr_read<v_rd_off(D0, 1, 0)>(vb), h1 = tr_read<v_rd_off(D0, 1, 1)>(vb);
;   const s16x4 l2 = tr_read<v_rd_off(D0, 2, 0)>(vb), h2 = tr_read<v_rd_off(D0, 2, 1)>(vb), l3 = tr_read<v_rd_off(D0, 3, 0)>(vb), h3 = tr_read<v_rd_off(D0, 3, 1)>(vb);
;   asm volatile("s_waitcnt lgkmcnt(0)" ::: "memory"); SBAR();
;     ...
;   od = __builtin_amdgcn_mfma_f32_32x32x16_bf16(pa0, PK(l0, h0), od, 0, 0, 0);
;   od = __builtin_amdgcn_mfma_f32_32x32x16_bf16(pa1, PK(l1, h1), od, 0, 0, 0);
;   od = __builtin_amdgcn_mfma_f32_32x32x16_bf16(pa2, PK(l2, h2), od, 0, 0, 0);
;   od = __builtin_amdgcn_mfma_f32_32x32x16_bf16(pa3, PK(l3, h3), od, 0, 0, 0);
;     ...
;   PAIR_FULL(0, 1, NP - 1);
;   { SBAR(); qkt(pB0, pB1, KSUB(1, 1), qr, r32, hi);
;     finishSM(pA0, pA1, alA, l_reg, pa0, pa1, pa2, pa3); SBAR();
;     pv_d0(o, VSUB(1, 0), pa0, pa1, pa2, pa3); partialSM(pB0, pB1, m_reg, mnB, alB);
;     RESC(alB);
;     finishSM(pB0, pB1, alB, l_reg, pa0, pa1, pa2, pa3); SBAR();
;     pv_d0(o, VSUB(1, 1), pa0, pa1, pa2, pa3); }
	ds_write_b128 v181, v[250:253] offset:57344
	s_waitcnt lgkmcnt(10)
	v_mfma_f32_32x32x16_bf16 v[48:63], v[184:187], v[230:233], v[48:63]
	ds_read_b64_tr_b16 v[204:205], v182 offset:5120
	ds_read_b64_tr_b16 v[206:207], v182 offset:7168
	v_exp_f32_e32 v136, v136
	v_exp_f32_e32 v137, v137
	s_waitcnt lgkmcnt(10)
	v_mfma_f32_32x32x16_bf16 v[48:63], v[188:191], v[234:237], v[48:63]
	ds_read_b64_tr_b16 v[208:209], v182 offset:9216
	ds_read_b64_tr_b16 v[210:211], v182 offset:11264
	v_exp_f32_e32 v138, v138
	v_exp_f32_e32 v139, v139
	s_waitcnt vmcnt(1)
	ds_write_b128 v180, v[164:167] offset:32768
	s_waitcnt lgkmcnt(11)
	v_mfma_f32_32x32x16_bf16 v[48:63], v[192:195], v[238:241], v[48:63]
	ds_read_b64_tr_b16 v[212:213], v182 offset:13312
	ds_read_b64_tr_b16 v[214:215], v182 offset:15360
	v_exp_f32_e32 v140, v140
	v_exp_f32_e32 v141, v141
	s_waitcnt lgkmcnt(10)
	v_mfma_f32_32x32x16_bf16 v[48:63], v[196:199], v[242:245], v[48:63]
	ds_read_b64_tr_b16 v[230:231], v182 offset:1536
	ds_read_b64_tr_b16 v[232:233], v182 offset:3584
	v_exp_f32_e32 v142, v142
	v_exp_f32_e32 v143, v143
	s_waitcnt vmcnt(0)
	ds_write_b128 v180, v[160:163] offset:40960
	s_waitcnt lgkmcnt(11)
	v_mfma_f32_32x32x16_bf16 v[32:47], v[184:187], v[200:203], v[32:47]
	ds_read_b64_tr_b16 v[234:235], v182 offset:5632
	ds_read_b64_tr_b16 v[236:237], v182 offset:7680
	ds_read_b128 v[200:203], v172 offset:32768
	v_exp_f32_e32 v144, v144
	v_exp_f32_e32 v145, v145
	s_waitcnt lgkmcnt(11)
	v_mfma_f32_32x32x16_bf16 v[32:47], v[188:191], v[204:207], v[32:47]
	ds_read_b64_tr_b16 v[238:239], v182 offset:9728
	ds_read_b64_tr_b16 v[240:241], v182 offset:11776
	ds_read_b128 v[204:207], v172 offset:40960
	v_exp_f32_e32 v146, v146
	v_exp_f32_e32 v147, v147
	s_waitcnt lgkmcnt(12)
	v_mfma_f32_32x32x16_bf16 v[32:47], v[192:195], v[208:211], v[32:47]
	ds_read_b64_tr_b16 v[242:243], v182 offset:13824
	ds_read_b64_tr_b16 v[244:245], v182 offset:15872
	ds_read_b128 v[208:211], v173 offset:32768
	v_exp_f32_e32 v148, v148
	v_exp_f32_e32 v149, v149
	s_waitcnt lgkmcnt(12)
	v_mfma_f32_32x32x16_bf16 v[32:47], v[196:199], v[212:215], v[32:47]
	ds_read_b128 v[212:215], v173 offset:40960
	v_exp_f32_e32 v150, v150
	v_exp_f32_e32 v151, v151
	s_waitcnt lgkmcnt(11)
	v_mfma_f32_32x32x16_bf16 v[16:31], v[184:187], v[230:233], v[16:31]
	ds_read_b128 v[230:233], v174 offset:32768
	v_exp_f32_e32 v152, v152
	v_exp_f32_e32 v153, v153
	s_waitcnt lgkmcnt(9)
	v_mfma_f32_32x32x16_bf16 v[16:31], v[188:191], v[234:237], v[16:31]
	ds_read_b128 v[234:237], v174 offset:40960
	v_exp_f32_e32 v154, v154
	v_exp_f32_e32 v155, v155
	s_waitcnt lgkmcnt(7)
	v_mfma_f32_32x32x16_bf16 v[16:31], v[192:195], v[238:241], v[16:31]
	ds_read_b128 v[238:241], v175 offset:32768
	v_exp_f32_e32 v156, v156
	v_exp_f32_e32 v157, v157
	s_waitcnt lgkmcnt(5)
	v_mfma_f32_32x32x16_bf16 v[16:31], v[196:199], v[242:245], v[16:31]
	ds_read_b128 v[242:245], v175 offset:40960
	v_exp_f32_e32 v158, v158
	v_exp_f32_e32 v159, v159
	s_barrier
	v_mfma_f32_32x32x16_bf16 v[64:79], v[200:203], v[124:127], 0
	ds_read_b128 v[200:203], v176 offset:32768
	v_cvt_pk_bf16_f32 v184, v128, v129
	v_add_f32_e32 v169, v169, v128
	v_add_f32_e32 v219, v219, v129
	v_mfma_f32_32x32x16_bf16 v[80:95], v[204:207], v[124:127], 0
	ds_read_b128 v[204:207], v176 offset:40960
	v_cvt_pk_bf16_f32 v185, v130, v131
	v_add_f32_e32 v222, v222, v130
	v_add_f32_e32 v254, v254, v131
	s_waitcnt lgkmcnt(7)
	v_mfma_f32_32x32x16_bf16 v[64:79], v[208:211], v[120:123], v[64:79]
	ds_read_b128 v[208:211], v177 offset:32768
	v_cvt_pk_bf16_f32 v186, v132, v133
	v_add_f32_e32 v169, v169, v132
	v_add_f32_e32 v219, v219, v133
	s_waitcnt lgkmcnt(7)
	v_mfma_f32_32x32x16_bf16 v[80:95], v[212:215], v[120:123], v[80:95]
	ds_read_b128 v[212:215], v177 offset:40960
	v_cvt_pk_bf16_f32 v187, v134, v135
	v_add_f32_e32 v222, v222, v134
	v_add_f32_e32 v254, v254, v135
	s_waitcnt lgkmcnt(7)
	v_mfma_f32_32x32x16_bf16 v[64:79], v[230:233], v[116:119], v[64:79]
	ds_read_b128 v[230:233], v178 offset:32768
	v_cvt_pk_bf16_f32 v188, v136, v137
	v_add_f32_e32 v169, v169, v136
	v_add_f32_e32 v219, v219, v137
	v_permlane32_swap_b32_e32 v184, v186
	global_load_dwordx4 v[164:167], v183, s[0:1] offset:512
	s_waitcnt lgkmcnt(7)
	v_mfma_f32_32x32x16_bf16 v[80:95], v[234:237], v[116:119], v[80:95]
	ds_read_b128 v[234:237], v178 offset:40960
	v_cvt_pk_bf16_f32 v189, v138, v139
	v_add_f32_e32 v222, v222, v138
	v_add_f32_e32 v254, v254, v139
	v_permlane32_swap_b32_e32 v185, v187
	s_waitcnt lgkmcnt(7)
	v_mfma_f32_32x32x16_bf16 v[64:79], v[238:241], v[112:115], v[64:79]
	ds_read_b128 v[238:241], v179 offset:32768
	v_cvt_pk_bf16_f32 v190, v140, v141
	v_add_f32_e32 v169, v169, v140
	v_add_f32_e32 v219, v219, v141
	global_load_dwordx4 v[160:163], v183, s[4:5] offset:512
	s_add_u32 s0, s0, 0x150000
	s_addc_u32 s1, s1, 0
	s_add_u32 s4, s4, 0x150000
	s_addc_u32 s5, s5, 0
	s_waitcnt lgkmcnt(7)
	v_mfma_f32_32x32x16_bf16 v[80:95], v[242:245], v[112:115], v[80:95]
	ds_read_b128 v[242:245], v179 offset:40960
	v_cvt_pk_bf16_f32 v191, v142, v143
	v_add_f32_e32 v222, v222, v142
	v_add_f32_e32 v254, v254, v143
	s_waitcnt lgkmcnt(7)
	v_mfma_f32_32x32x16_bf16 v[64:79], v[200:203], v[108:111], v[64:79]
	v_cvt_pk_bf16_f32 v192, v144, v145
	v_add_f32_e32 v169, v169, v144
	v_add_f32_e32 v219, v219, v145
	v_permlane32_swap_b32_e32 v188, v190
	s_waitcnt lgkmcnt(6)
	v_mfma_f32_32x32x16_bf16 v[80:95], v[204:207], v[108:111], v[80:95]
	v_cvt_pk_bf16_f32 v193, v146, v147
	v_add_f32_e32 v222, v222, v146
	v_add_f32_e32 v254, v254, v147
	v_permlane32_swap_b32_e32 v189, v191
	s_waitcnt lgkmcnt(5)
; #define SBAR() __builtin_amdgcn_sched_barrier(0)
; __device__ __forceinline__ void qkt(f32x16& p0, f32x16& p1, const bf16* Ks, const bf16x8* qr, int r32, int hi) {
;   p0 = f32x16{}; p1 = f32x16{};
; #pragma unroll
;   for (int d0 = 0; d0 < 8; ++d0) { int cb = (d0 * 16 + hi * 8) * 2;
;     bf16x8 b0 = *reinterpret_cast<const bf16x8*>((const char*)Ks + KSWZ(r32, cb));
;     bf16x8 b1 = *reinterpret_cast<const bf16x8*>((const char*)Ks + KSWZ(32 + r32, cb));
;     p0 = __builtin_amdgcn_mfma_f32_32x32x16_bf16(b0, qr[d0], p0, 0, 0, 0);
;     p1 = __builtin_amdgcn_mfma_f32_32x32x16_bf16(b1, qr[d0], p1, 0, 0, 0); }
; }
; __device__ __forceinline__ int v_st(int k, int c) { const int kk = (k & ~0xC) | ((k & 4) << 1) | ((k & 8) >> 1); return ((kk >> 3) * 4 + (c >> 5)) * 512 + ((kk & 7) * 32 + (c & 31)) * 2; }
; __device__ __forceinline__ int v_rd_base(int lane) { return ((lane & 3) << 3) | (((lane >> 2) & 3) << 6) | (((lane >> 4) & 1) << 5) | (((lane >> 5) & 1) << 8); }
; template <int OFF> __device__ __forceinline__ s16x4 tr_read(int vb) {
;   s16x4 r; asm volatile("ds_read_b64_tr_b16 %0, %1 offset:%2" : "=&v"(r) : "v"(vb), "i"(OFF) : "memory"); return r;
; }
; template <int D0> __device__ __forceinline__ void pv_one(f32x16& od, int vb, bf16x8 pa0, bf16x8 pa1, bf16x8 pa2, bf16x8 pa3) {
;   const s16x4 l0 = tr_read<v_rd_off(D0, 0, 0)>(vb), h0 = tr_read<v_rd_off(D0, 0, 1)>(vb), l1 = tr_read<v_rd_off(D0, 1, 0)>(vb), h1 = tr_read<v_rd_off(D0, 1, 1)>(vb);
;   const s16x4 l2 = tr_read<v_rd_off(D0, 2, 0)>(vb), h2 = tr_read<v_rd_off(D0, 2, 1)>(vb), l3 = tr_read<v_rd_off(D0, 3, 0)>(vb), h3 = tr_read<v_rd_off(D0, 3, 1)>(vb);
;   asm volatile("s_waitcnt lgkmcnt(0)" ::: "memory"); SBAR();
;     ...
;   od = __builtin_amdgcn_mfma_f32_32x32x16_bf16(pa0, PK(l0, h0), od, 0, 0, 0);
;   od = __builtin_amdgcn_mfma_f32_32x32x16_bf16(pa1, PK(l1, h1), od, 0, 0, 0);
;   od = __builtin_amdgcn_mfma_f32_32x32x16_bf16(pa2, PK(l2, h2), od, 0, 0, 0);
;   od = __builtin_amdgcn_mfma_f32_32x32x16_bf16(pa3, PK(l3, h3), od, 0, 0, 0);
;     ...
;   PAIR_FULL(0, 1, NP - 1);
;   { SBAR(); qkt(pB0, pB1, KSUB(1, 1), qr, r32, hi);
;     finishSM(pA0, pA1, alA, l_reg, pa0, pa1, pa2, pa3); SBAR();
;     pv_d0(o, VSUB(1, 0), pa0, pa1, pa2, pa3); partialSM(pB0, pB1, m_reg, mnB, alB);
;     RESC(alB);
;     finishSM(pB0, pB1, alB, l_reg, pa0, pa1, pa2, pa3); SBAR();
;     pv_d0(o, VSUB(1, 1), pa0, pa1, pa2, pa3); }
	v_mfma_f32_32x32x16_bf16 v[64:79], v[208:211], v[104:107], v[64:79]
	v_cvt_pk_bf16_f32 v194, v148, v149
	v_add_f32_e32 v169, v169, v148
	v_add_f32_e32 v219, v219, v149
	s_waitcnt lgkmcnt(4)
	v_mfma_f32_32x32x16_bf16 v[80:95], v[212:215], v[104:107], v[80:95]
	ds_read_b64_tr_b16 v[200:201], v182 offset:16384
	ds_read_b64_tr_b16 v[202:203], v182 offset:18432
	v_cvt_pk_bf16_f32 v195, v150, v151
	v_add_f32_e32 v222, v222, v150
	v_add_f32_e32 v254, v254, v151
	s_waitcnt lgkmcnt(5)
	v_mfma_f32_32x32x16_bf16 v[64:79], v[230:233], v[100:103], v[64:79]
	ds_read_b64_tr_b16 v[204:205], v182 offset:20480
	ds_read_b64_tr_b16 v[206:207], v182 offset:22528
	v_cvt_pk_bf16_f32 v196, v152, v153
	v_add_f32_e32 v169, v169, v152
	v_add_f32_e32 v219, v219, v153
	v_permlane32_swap_b32_e32 v192, v194
	s_waitcnt lgkmcnt(6)
	v_mfma_f32_32x32x16_bf16 v[80:95], v[234:237], v[100:103], v[80:95]
	ds_read_b64_tr_b16 v[208:209], v182 offset:24576
	ds_read_b64_tr_b16 v[210:211], v182 offset:26624
	v_cvt_pk_bf16_f32 v197, v154, v155
	v_add_f32_e32 v222, v222, v154
	v_add_f32_e32 v254, v254, v155
	v_permlane32_swap_b32_e32 v193, v195
	s_waitcnt lgkmcnt(7)
	v_mfma_f32_32x32x16_bf16 v[64:79], v[238:241], v[96:99], v[64:79]
	ds_read_b64_tr_b16 v[212:213], v182 offset:28672
	ds_read_b64_tr_b16 v[214:215], v182 offset:30720
	v_cvt_pk_bf16_f32 v198, v156, v157
	v_add_f32_e32 v169, v169, v156
	v_add_f32_e32 v219, v219, v157
	s_waitcnt lgkmcnt(8)
	v_mfma_f32_32x32x16_bf16 v[80:95], v[242:245], v[96:99], v[80:95]
	ds_read_b64_tr_b16 v[230:231], v182 offset:16896
	ds_read_b64_tr_b16 v[232:233], v182 offset:18944
	v_cvt_pk_bf16_f32 v199, v158, v159
	v_add_f32_e32 v222, v222, v158
	v_add_f32_e32 v254, v254, v159
	v_permlane32_swap_b32_e32 v196, v198
	v_permlane32_swap_b32_e32 v197, v199
	s_waitcnt lgkmcnt(8)
	v_mfma_f32_32x32x16_bf16 v[0:15], v[184:187], v[200:203], v[0:15]
	ds_read_b64_tr_b16 v[234:235], v182 offset:20992
	ds_read_b64_tr_b16 v[236:237], v182 offset:23040
	v_exp_f32_e32 v64, v64
	v_exp_f32_e32 v65, v65
	s_waitcnt lgkmcnt(8)
	v_mfma_f32_32x32x16_bf16 v[0:15], v[188:191], v[204:207], v[0:15]
	ds_read_b64_tr_b16 v[238:239], v182 offset:25088
	ds_read_b64_tr_b16 v[240:241], v182 offset:27136
	v_exp_f32_e32 v66, v66
	v_exp_f32_e32 v67, v67
	s_waitcnt vmcnt(1)
	ds_write_b128 v180, v[164:167] offset:49152
	s_waitcnt lgkmcnt(9)
	v_mfma_f32_32x32x16_bf16 v[0:15], v[192:195], v[208:211], v[0:15]
	ds_read_b64_tr_b16 v[242:243], v182 offset:29184
	ds_read_b64_tr_b16 v[244:245], v182 offset:31232
	v_exp_f32_e32 v68, v68
	v_exp_f32_e32 v69, v69
	s_waitcnt lgkmcnt(9)
	v_mfma_f32_32x32x16_bf16 v[0:15], v[196:199], v[212:215], v[0:15]
	ds_read_b64_tr_b16 v[200:201], v182 offset:17408
	ds_read_b64_tr_b16 v[202:203], v182 offset:19456
	v_exp_f32_e32 v70, v70
	v_exp_f32_e32 v71, v71
	s_waitcnt vmcnt(0)
	ds_write_b128 v180, v[160:163] offset:57344
	s_waitcnt lgkmcnt(10)
	v_mfma_f32_32x32x16_bf16 v[48:63], v[184:187], v[230:233], v[48:63]
	ds_read_b64_tr_b16 v[204:205], v182 offset:21504
	ds_read_b64_tr_b16 v[206:207], v182 offset:23552
	v_exp_f32_e32 v72, v72
	v_exp_f32_e32 v73, v73
	s_waitcnt lgkmcnt(10)
	v_mfma_f32_32x32x16_bf16 v[48:63], v[188:191], v[234:237], v[48:63]
	ds_read_b64_tr_b16 v[208:209], v182 offset:25600
	ds_read_b64_tr_b16 v[210:211], v182 offset:27648
	v_exp_f32_e32 v74, v74
	v_exp_f32_e32 v75, v75
	s_waitcnt lgkmcnt(10)
	v_mfma_f32_32x32x16_bf16 v[48:63], v[192:195], v[238:241], v[48:63]
	ds_read_b64_tr_b16 v[212:213], v182 offset:29696
	ds_read_b64_tr_b16 v[214:215], v182 offset:31744
	v_exp_f32_e32 v76, v76
	v_exp_f32_e32 v77, v77
	s_waitcnt lgkmcnt(9)
	v_mfma_f32_32x32x16_bf16 v[48:63], v[196:199], v[242:245], v[48:63]
	ds_read_b64_tr_b16 v[230:231], v182 offset:17920
	ds_read_b64_tr_b16 v[232:233], v182 offset:19968
	v_exp_f32_e32 v78, v78
	v_exp_f32_e32 v79, v79
	s_waitcnt lgkmcnt(9)
	v_mfma_f32_32x32x16_bf16 v[32:47], v[184:187], v[200:203], v[32:47]
	ds_read_b64_tr_b16 v[234:235], v182 offset:22016
	ds_read_b64_tr_b16 v[236:237], v182 offset:24064
	ds_read_b128 v[200:203], v172 offset:49152
	v_exp_f32_e32 v80, v80
	v_exp_f32_e32 v81, v81
	s_waitcnt lgkmcnt(9)
	v_mfma_f32_32x32x16_bf16 v[32:47], v[188:191], v[204:207], v[32:47]
	ds_read_b64_tr_b16 v[238:239], v182 offset:26112
	ds_read_b64_tr_b16 v[240:241], v182 offset:28160
	ds_read_b128 v[204:207], v172 offset:57344
	v_exp_f32_e32 v82, v82
	v_exp_f32_e32 v83, v83
	s_waitcnt lgkmcnt(10)
	v_mfma_f32_32x32x16_bf16 v[32:47], v[192:195], v[208:211], v[32:47]
	ds_read_b64_tr_b16 v[242:243], v182 offset:30208
	ds_read_b64_tr_b16 v[244:245], v182 offset:32256
	ds_read_b128 v[208:211], v173 offset:49152
	v_exp_f32_e32 v84, v84
	v_exp_f32_e32 v85, v85
	s_waitcnt lgkmcnt(11)
	v_mfma_f32_32x32x16_bf16 v[32:47], v[196:199], v[212:215], v[32:47]
	ds_read_b128 v[212:215], v173 offset:57344
	v_exp_f32_e32 v86, v86
	v_exp_f32_e32 v87, v87
	s_waitcnt lgkmcnt(10)
	v_mfma_f32_32x32x16_bf16 v[16:31], v[184:187], v[230:233], v[16:31]
	ds_read_b128 v[230:233], v174 offset:49152
	v_exp_f32_e32 v88, v88
	v_exp_f32_e32 v89, v89
	s_waitcnt lgkmcnt(9)
	v_mfma_f32_32x32x16_bf16 v[16:31], v[188:191], v[234:237], v[16:31]
	ds_read_b128 v[234:237], v174 offset:57344
	v_exp_f32_e32 v90, v90
	v_exp_f32_e32 v91, v91
	s_waitcnt lgkmcnt(7)
	v_mfma_f32_32x32x16_bf16 v[16:31], v[192:195], v[238:241], v[16:31]
	ds_read_b128 v[238:241], v175 offset:49152
	v_exp_f32_e32 v92, v92
	v_exp_f32_e32 v93, v93
	s_waitcnt lgkmcnt(5)
	v_mfma_f32_32x32x16_bf16 v[16:31], v[196:199], v[242:245], v[16:31]
	ds_read_b128 v[242:245], v175 offset:57344
	v_exp_f32_e32 v94, v94
	v_exp_f32_e32 v95, v95
	s_barrier
; #define SBAR() __builtin_amdgcn_sched_barrier(0)
; __device__ __forceinline__ void qkt(f32x16& p0, f32x16& p1, const bf16* Ks, const bf16x8* qr, int r32, int hi) {
;   p0 = f32x16{}; p1 = f32x16{};
; #pragma unroll
;   for (int d0 = 0; d0 < 8; ++d0) { int cb = (d0 * 16 + hi * 8) * 2;
;     bf16x8 b0 = *reinterpret_cast<const bf16x8*>((const char*)Ks + KSWZ(r32, cb));
;     bf16x8 b1 = *reinterpret_cast<const bf16x8*>((const char*)Ks + KSWZ(32 + r32, cb));
;     p0 = __builtin_amdgcn_mfma_f32_32x32x16_bf16(b0, qr[d0], p0, 0, 0, 0);
;     p1 = __builtin_amdgcn_mfma_f32_32x32x16_bf16(b1, qr[d0], p1, 0, 0, 0); }
; }
; __device__ __forceinline__ int v_st(int k, int c) { const int kk = (k & ~0xC) | ((k & 4) << 1) | ((k & 8) >> 1); return ((kk >> 3) * 4 + (c >> 5)) * 512 + ((kk & 7) * 32 + (c & 31)) * 2; }
; __device__ __forceinline__ int v_rd_base(int lane) { return ((lane & 3) << 3) | (((lane >> 2) & 3) << 6) | (((lane >> 4) & 1) << 5) | (((lane >> 5) & 1) << 8); }
; template <int OFF> __device__ __forceinline__ s16x4 tr_read(int vb) {
;   s16x4 r; asm volatile("ds_read_b64_tr_b16 %0, %1 offset:%2" : "=&v"(r) : "v"(vb), "i"(OFF) : "memory"); return r;
; }
; template <int D0> __device__ __forceinline__ void pv_one(f32x16& od, int vb, bf16x8 pa0, bf16x8 pa1, bf16x8 pa2, bf16x8 pa3) {
;   const s16x4 l0 = tr_read<v_rd_off(D0, 0, 0)>(vb), h0 = tr_read<v_rd_off(D0, 0, 1)>(vb), l1 = tr_read<v_rd_off(D0, 1, 0)>(vb), h1 = tr_read<v_rd_off(D0, 1, 1)>(vb);
;   const s16x4 l2 = tr_read<v_rd_off(D0, 2, 0)>(vb), h2 = tr_read<v_rd_off(D0, 2, 1)>(vb), l3 = tr_read<v_rd_off(D0, 3, 0)>(vb), h3 = tr_read<v_rd_off(D0, 3, 1)>(vb);
;   asm volatile("s_waitcnt lgkmcnt(0)" ::: "memory"); SBAR();
;     ...
;   od = __builtin_amdgcn_mfma_f32_32x32x16_bf16(pa0, PK(l0, h0), od, 0, 0, 0);
;   od = __builtin_amdgcn_mfma_f32_32x32x16_bf16(pa1, PK(l1, h1), od, 0, 0, 0);
;   od = __builtin_amdgcn_mfma_f32_32x32x16_bf16(pa2, PK(l2, h2), od, 0, 0, 0);
;   od = __builtin_amdgcn_mfma_f32_32x32x16_bf16(pa3, PK(l3, h3), od, 0, 0, 0);
;     ...
;   { SBAR(); qkt(pB0, pB1, KSUB(1, 1), qr, r32, hi);
;     finishSM(pA0, pA1, alA, l_reg, pa0, pa1, pa2, pa3); SBAR();
;     pv_d0(o, VSUB(1, 0), pa0, pa1, pa2, pa3); partialSM(pB0, pB1, m_reg, mnB, alB);
;     RESC(alB);
;     finishSM(pB0, pB1, alB, l_reg, pa0, pa1, pa2, pa3); SBAR();
;     pv_d0(o, VSUB(1, 1), pa0, pa1, pa2, pa3); }
	v_mfma_f32_32x32x16_bf16 v[128:143], v[200:203], v[124:127], 0
	ds_read_b128 v[200:203], v176 offset:49152
	v_cvt_pk_bf16_f32 v184, v64, v65
	v_add_f32_e32 v169, v169, v64
	v_add_f32_e32 v219, v219, v65
	v_mfma_f32_32x32x16_bf16 v[144:159], v[204:207], v[124:127], 0
	ds_read_b128 v[204:207], v176 offset:57344
	v_cvt_pk_bf16_f32 v185, v66, v67
	v_add_f32_e32 v222, v222, v66
	v_add_f32_e32 v254, v254, v67
	s_waitcnt lgkmcnt(7)
	v_mfma_f32_32x32x16_bf16 v[128:143], v[208:211], v[120:123], v[128:143]
	ds_read_b128 v[208:211], v177 offset:49152
	v_cvt_pk_bf16_f32 v186, v68, v69
	v_add_f32_e32 v169, v169, v68
	v_add_f32_e32 v219, v219, v69
	s_waitcnt lgkmcnt(7)
	v_mfma_f32_32x32x16_bf16 v[144:159], v[212:215], v[120:123], v[144:159]
	ds_read_b128 v[212:215], v177 offset:57344
	v_cvt_pk_bf16_f32 v187, v70, v71
	v_add_f32_e32 v222, v222, v70
	v_add_f32_e32 v254, v254, v71
	s_waitcnt lgkmcnt(7)
	v_mfma_f32_32x32x16_bf16 v[128:143], v[230:233], v[116:119], v[128:143]
	ds_read_b128 v[230:233], v178 offset:49152
	v_cvt_pk_bf16_f32 v188, v72, v73
	v_add_f32_e32 v169, v169, v72
	v_add_f32_e32 v219, v219, v73
	v_permlane32_swap_b32_e32 v184, v186
	s_waitcnt lgkmcnt(7)
	v_mfma_f32_32x32x16_bf16 v[144:159], v[234:237], v[116:119], v[144:159]
	ds_read_b128 v[234:237], v178 offset:57344
	v_cvt_pk_bf16_f32 v189, v74, v75
	v_add_f32_e32 v222, v222, v74
	v_add_f32_e32 v254, v254, v75
	v_permlane32_swap_b32_e32 v185, v187
	s_waitcnt lgkmcnt(7)
	v_mfma_f32_32x32x16_bf16 v[128:143], v[238:241], v[112:115], v[128:143]
	ds_read_b128 v[238:241], v179 offset:49152
	v_cvt_pk_bf16_f32 v190, v76, v77
	v_add_f32_e32 v169, v169, v76
	v_add_f32_e32 v219, v219, v77
	s_waitcnt lgkmcnt(7)
	v_mfma_f32_32x32x16_bf16 v[144:159], v[242:245], v[112:115], v[144:159]
	ds_read_b128 v[242:245], v179 offset:57344
	v_cvt_pk_bf16_f32 v191, v78, v79
	v_add_f32_e32 v222, v222, v78
	v_add_f32_e32 v254, v254, v79
	s_waitcnt lgkmcnt(7)
	v_mfma_f32_32x32x16_bf16 v[128:143], v[200:203], v[108:111], v[128:143]
	v_cvt_pk_bf16_f32 v192, v80, v81
	v_add_f32_e32 v169, v169, v80
	v_add_f32_e32 v219, v219, v81
	v_permlane32_swap_b32_e32 v188, v190
	s_waitcnt lgkmcnt(6)
	v_mfma_f32_32x32x16_bf16 v[144:159], v[204:207], v[108:111], v[144:159]
	v_cvt_pk_bf16_f32 v193, v82, v83
	v_add_f32_e32 v222, v222, v82
	v_add_f32_e32 v254, v254, v83
	v_permlane32_swap_b32_e32 v189, v191
	s_waitcnt lgkmcnt(5)
	v_mfma_f32_32x32x16_bf16 v[128:143], v[208:211], v[104:107], v[128:143]
	v_cvt_pk_bf16_f32 v194, v84, v85
	v_add_f32_e32 v169, v169, v84
	v_add_f32_e32 v219, v219, v85
	s_waitcnt lgkmcnt(4)
	v_mfma_f32_32x32x16_bf16 v[144:159], v[212:215], v[104:107], v[144:159]
	ds_read_b64_tr_b16 v[200:201], v182 offset:32768
	ds_read_b64_tr_b16 v[202:203], v182 offset:34816
	v_cvt_pk_bf16_f32 v195, v86, v87
	v_add_f32_e32 v222, v222, v86
	v_add_f32_e32 v254, v254, v87
	s_waitcnt lgkmcnt(5)
	v_mfma_f32_32x32x16_bf16 v[128:143], v[230:233], v[100:103], v[128:143]
	ds_read_b64_tr_b16 v[204:205], v182 offset:36864
	ds_read_b64_tr_b16 v[206:207], v182 offset:38912
	v_cvt_pk_bf16_f32 v196, v88, v89
	v_add_f32_e32 v169, v169, v88
	v_add_f32_e32 v219, v219, v89
	v_permlane32_swap_b32_e32 v192, v194
	s_waitcnt lgkmcnt(6)
	v_mfma_f32_32x32x16_bf16 v[144:159], v[234:237], v[100:103], v[144:159]
	ds_read_b64_tr_b16 v[208:209], v182 offset:40960
	ds_read_b64_tr_b16 v[210:211], v182 offset:43008
	v_cvt_pk_bf16_f32 v197, v90, v91
	v_add_f32_e32 v222, v222, v90
	v_add_f32_e32 v254, v254, v91
	v_permlane32_swap_b32_e32 v193, v195
	s_waitcnt lgkmcnt(7)
	v_mfma_f32_32x32x16_bf16 v[128:143], v[238:241], v[96:99], v[128:143]
	ds_read_b64_tr_b16 v[212:213], v182 offset:45056
	ds_read_b64_tr_b16 v[214:215], v182 offset:47104
	v_cvt_pk_bf16_f32 v198, v92, v93
	v_add_f32_e32 v169, v169, v92
	v_add_f32_e32 v219, v219, v93
	s_waitcnt lgkmcnt(8)
	v_mfma_f32_32x32x16_bf16 v[144:159], v[242:245], v[96:99], v[144:159]
	ds_read_b64_tr_b16 v[230:231], v182 offset:33280
	ds_read_b64_tr_b16 v[232:233], v182 offset:35328
	v_cvt_pk_bf16_f32 v199, v94, v95
	v_add_f32_e32 v222, v222, v94
	v_add_f32_e32 v254, v254, v95
	v_permlane32_swap_b32_e32 v196, v198
	v_permlane32_swap_b32_e32 v197, v199
	s_waitcnt lgkmcnt(8)
	v_mfma_f32_32x32x16_bf16 v[0:15], v[184:187], v[200:203], v[0:15]
	ds_read_b64_tr_b16 v[234:235], v182 offset:37376
	ds_read_b64_tr_b16 v[236:237], v182 offset:39424
	v_exp_f32_e32 v128, v128
	v_exp_f32_e32 v129, v129
	s_waitcnt lgkmcnt(8)
	v_mfma_f32_32x32x16_bf16 v[0:15], v[188:191], v[204:207], v[0:15]
	ds_read_b64_tr_b16 v[238:239], v182 offset:41472
	ds_read_b64_tr_b16 v[240:241], v182 offset:43520
	v_exp_f32_e32 v130, v130
	v_exp_f32_e32 v131, v131
	s_waitcnt lgkmcnt(8)
	v_mfma_f32_32x32x16_bf16 v[0:15], v[192:195], v[208:211], v[0:15]
	ds_read_b64_tr_b16 v[242:243], v182 offset:45568
	ds_read_b64_tr_b16 v[244:245], v182 offset:47616
	v_exp_f32_e32 v132, v132
	v_exp_f32_e32 v133, v133
	s_waitcnt lgkmcnt(8)
	v_mfma_f32_32x32x16_bf16 v[0:15], v[196:199], v[212:215], v[0:15]
	ds_read_b64_tr_b16 v[200:201], v182 offset:33792
	ds_read_b64_tr_b16 v[202:203], v182 offset:35840
	v_exp_f32_e32 v134, v134
	v_exp_f32_e32 v135, v135
	s_waitcnt lgkmcnt(8)
	v_mfma_f32_32x32x16_bf16 v[48:63], v[184:187], v[230:233], v[48:63]
	ds_read_b64_tr_b16 v[204:205], v182 offset:37888
	ds_read_b64_tr_b16 v[206:207], v182 offset:39936
	v_exp_f32_e32 v136, v136
	v_exp_f32_e32 v137, v137
	s_waitcnt lgkmcnt(8)
	v_mfma_f32_32x32x16_bf16 v[48:63], v[188:191], v[234:237], v[48:63]
	ds_read_b64_tr_b16 v[208:209], v182 offset:41984
	ds_read_b64_tr_b16 v[210:211], v182 offset:44032
	v_exp_f32_e32 v138, v138
	v_exp_f32_e32 v139, v139
	s_waitcnt lgkmcnt(8)
; #define SBAR() __builtin_amdgcn_sched_barrier(0)
; template <int D0> __device__ __forceinline__ void pv_one(f32x16& od, int vb, bf16x8 pa0, bf16x8 pa1, bf16x8 pa2, bf16x8 pa3) {
;   const s16x4 l0 = tr_read<v_rd_off(D0, 0, 0)>(vb), h0 = tr_read<v_rd_off(D0, 0, 1)>(vb), l1 = tr_read<v_rd_off(D0, 1, 0)>(vb), h1 = tr_read<v_rd_off(D0, 1, 1)>(vb);
;   const s16x4 l2 = tr_read<v_rd_off(D0, 2, 0)>(vb), h2 = tr_read<v_rd_off(D0, 2, 1)>(vb), l3 = tr_read<v_rd_off(D0, 3, 0)>(vb), h3 = tr_read<v_rd_off(D0, 3, 1)>(vb);
;   asm volatile("s_waitcnt lgkmcnt(0)" ::: "memory"); SBAR();
;     ...
;   od = __builtin_amdgcn_mfma_f32_32x32x16_bf16(pa0, PK(l0, h0), od, 0, 0, 0);
;   od = __builtin_amdgcn_mfma_f32_32x32x16_bf16(pa1, PK(l1, h1), od, 0, 0, 0);
;   od = __builtin_amdgcn_mfma_f32_32x32x16_bf16(pa2, PK(l2, h2), od, 0, 0, 0);
;   od = __builtin_amdgcn_mfma_f32_32x32x16_bf16(pa3, PK(l3, h3), od, 0, 0, 0);
	v_mfma_f32_32x32x16_bf16 v[48:63], v[192:195], v[238:241], v[48:63]
	ds_read_b64_tr_b16 v[212:213], v182 offset:46080
	ds_read_b64_tr_b16 v[214:215], v182 offset:48128
	v_exp_f32_e32 v140, v140
	v_exp_f32_e32 v141, v141
	s_waitcnt lgkmcnt(8)
	v_mfma_f32_32x32x16_bf16 v[48:63], v[196:199], v[242:245], v[48:63]
	ds_read_b64_tr_b16 v[230:231], v182 offset:34304
	ds_read_b64_tr_b16 v[232:233], v182 offset:36352
	v_exp_f32_e32 v142, v142
	v_exp_f32_e32 v143, v143
	s_waitcnt lgkmcnt(8)
	v_mfma_f32_32x32x16_bf16 v[32:47], v[184:187], v[200:203], v[32:47]
	ds_read_b64_tr_b16 v[234:235], v182 offset:38400
	ds_read_b64_tr_b16 v[236:237], v182 offset:40448
	v_exp_f32_e32 v144, v144
	v_exp_f32_e32 v145, v145
	s_waitcnt lgkmcnt(8)
	v_mfma_f32_32x32x16_bf16 v[32:47], v[188:191], v[204:207], v[32:47]
	ds_read_b64_tr_b16 v[238:239], v182 offset:42496
	ds_read_b64_tr_b16 v[240:241], v182 offset:44544
	v_exp_f32_e32 v146, v146
	v_exp_f32_e32 v147, v147
	s_waitcnt lgkmcnt(8)
	v_mfma_f32_32x32x16_bf16 v[32:47], v[192:195], v[208:211], v[32:47]
	ds_read_b64_tr_b16 v[242:243], v182 offset:46592
	ds_read_b64_tr_b16 v[244:245], v182 offset:48640
	v_exp_f32_e32 v148, v148
	v_exp_f32_e32 v149, v149
	s_waitcnt lgkmcnt(8)
	v_mfma_f32_32x32x16_bf16 v[32:47], v[196:199], v[212:215], v[32:47]
	v_exp_f32_e32 v150, v150
	v_exp_f32_e32 v151, v151
	s_waitcnt lgkmcnt(6)
	v_mfma_f32_32x32x16_bf16 v[16:31], v[184:187], v[230:233], v[16:31]
	v_exp_f32_e32 v152, v152
	v_exp_f32_e32 v153, v153
	s_waitcnt lgkmcnt(4)
	v_mfma_f32_32x32x16_bf16 v[16:31], v[188:191], v[234:237], v[16:31]
	v_exp_f32_e32 v154, v154
	v_exp_f32_e32 v155, v155
	s_waitcnt lgkmcnt(2)
	v_mfma_f32_32x32x16_bf16 v[16:31], v[192:195], v[238:241], v[16:31]
	v_exp_f32_e32 v156, v156
	v_exp_f32_e32 v157, v157
	s_waitcnt lgkmcnt(0)
	v_mfma_f32_32x32x16_bf16 v[16:31], v[196:199], v[242:245], v[16:31]
	v_exp_f32_e32 v158, v158
	v_exp_f32_e32 v159, v159
	s_waitcnt lgkmcnt(0)
	s_barrier
; __device__ __forceinline__ void finishSM(f32x16& p0, f32x16& p1, float alpha, float& l_reg, bf16x8& pa0, bf16x8& pa1, bf16x8& pa2, bf16x8& pa3) {
; #pragma unroll
;   for (int r = 0; r < 16; ++r) p1[r] = __builtin_amdgcn_exp2f(p1[r]);
;   float ps = 0;
; #pragma unroll
;   for (int r = 0; r < 16; ++r) ps += p0[r];
; #pragma unroll
;   for (int r = 0; r < 16; ++r) ps += p1[r];
;   { auto rr = __builtin_amdgcn_permlane32_swap(__float_as_uint(ps), __float_as_uint(ps), false, false);
;     ps = __uint_as_float(rr[0]) + __uint_as_float(rr[1]); }
;   l_reg = l_reg * alpha + ps;
;     ...
;   PK4(p0, 0, pa0); PK4(p0, 8, pa1); PK4(p1, 0, pa2); PK4(p1, 8, pa3);
;     ...
; }
; __device__ __forceinline__ void qkt(f32x16& p0, f32x16& p1, const bf16* Ks, const bf16x8* qr, int r32, int hi) {
;   p0 = f32x16{}; p1 = f32x16{};
; #pragma unroll
;   for (int d0 = 0; d0 < 8; ++d0) { int cb = (d0 * 16 + hi * 8) * 2;
;     bf16x8 b0 = *reinterpret_cast<const bf16x8*>((const char*)Ks + KSWZ(r32, cb));
;     bf16x8 b1 = *reinterpret_cast<const bf16x8*>((const char*)Ks + KSWZ(32 + r32, cb));
;     p0 = __builtin_amdgcn_mfma_f32_32x32x16_bf16(b0, qr[d0], p0, 0, 0, 0);
;     p1 = __builtin_amdgcn_mfma_f32_32x32x16_bf16(b1, qr[d0], p1, 0, 0, 0); }
; }
; __device__ __forceinline__ int v_st(int k, int c) { const int kk = (k & ~0xC) | ((k & 4) << 1) | ((k & 8) >> 1); return ((kk >> 3) * 4 + (c >> 5)) * 512 + ((kk & 7) * 32 + (c & 31)) * 2; }
; __device__ __forceinline__ int v_rd_base(int lane) { return ((lane & 3) << 3) | (((lane >> 2) & 3) << 6) | (((lane >> 4) & 1) << 5) | (((lane >> 5) & 1) << 8); }
; template <int OFF> __device__ __forceinline__ s16x4 tr_read(int vb) {
;   s16x4 r; asm volatile("ds_read_b64_tr_b16 %0, %1 offset:%2" : "=&v"(r) : "v"(vb), "i"(OFF) : "memory"); return r;
; }
; template <int D0> __device__ __forceinline__ void pv_one(f32x16& od, int vb, bf16x8 pa0, bf16x8 pa1, bf16x8 pa2, bf16x8 pa3) {
;   const s16x4 l0 = tr_read<v_rd_off(D0, 0, 0)>(vb), h0 = tr_read<v_rd_off(D0, 0, 1)>(vb), l1 = tr_read<v_rd_off(D0, 1, 0)>(vb), h1 = tr_read<v_rd_off(D0, 1, 1)>(vb);
;   const s16x4 l2 = tr_read<v_rd_off(D0, 2, 0)>(vb), h2 = tr_read<v_rd_off(D0, 2, 1)>(vb), l3 = tr_read<v_rd_off(D0, 3, 0)>(vb), h3 = tr_read<v_rd_off(D0, 3, 1)>(vb);
;   asm volatile("s_waitcnt lgkmcnt(0)" ::: "memory"); SBAR();
;     ...
;   od = __builtin_amdgcn_mfma_f32_32x32x16_bf16(pa0, PK(l0, h0), od, 0, 0, 0);
	v_cvt_pk_bf16_f32 v184, v128, v129
	v_add_f32_e32 v169, v169, v128
	v_add_f32_e32 v219, v219, v129
	v_cvt_pk_bf16_f32 v185, v130, v131
	v_add_f32_e32 v222, v222, v130
	v_add_f32_e32 v254, v254, v131
	v_cvt_pk_bf16_f32 v186, v132, v133
	v_add_f32_e32 v169, v169, v132
	v_add_f32_e32 v219, v219, v133
	v_cvt_pk_bf16_f32 v187, v134, v135
	v_add_f32_e32 v222, v222, v134
	v_add_f32_e32 v254, v254, v135
	v_cvt_pk_bf16_f32 v188, v136, v137
	v_add_f32_e32 v169, v169, v136
	v_add_f32_e32 v219, v219, v137
	v_permlane32_swap_b32_e32 v184, v186
	v_cvt_pk_bf16_f32 v189, v138, v139
	v_add_f32_e32 v222, v222, v138
	v_add_f32_e32 v254, v254, v139
	v_permlane32_swap_b32_e32 v185, v187
	v_cvt_pk_bf16_f32 v190, v140, v141
	v_add_f32_e32 v169, v169, v140
	v_add_f32_e32 v219, v219, v141
	v_cvt_pk_bf16_f32 v191, v142, v143
	v_add_f32_e32 v222, v222, v142
	v_add_f32_e32 v254, v254, v143
	v_cvt_pk_bf16_f32 v192, v144, v145
	v_add_f32_e32 v169, v169, v144
	v_add_f32_e32 v219, v219, v145
	v_permlane32_swap_b32_e32 v188, v190
	v_cvt_pk_bf16_f32 v193, v146, v147
	v_add_f32_e32 v222, v222, v146
	v_add_f32_e32 v254, v254, v147
	v_permlane32_swap_b32_e32 v189, v191
	v_cvt_pk_bf16_f32 v194, v148, v149
	v_add_f32_e32 v169, v169, v148
	v_add_f32_e32 v219, v219, v149
	ds_read_b64_tr_b16 v[200:201], v182 offset:49152
	ds_read_b64_tr_b16 v[202:203], v182 offset:51200
	v_cvt_pk_bf16_f32 v195, v150, v151
	v_add_f32_e32 v222, v222, v150
	v_add_f32_e32 v254, v254, v151
	ds_read_b64_tr_b16 v[204:205], v182 offset:53248
	ds_read_b64_tr_b16 v[206:207], v182 offset:55296
	v_cvt_pk_bf16_f32 v196, v152, v153
	v_add_f32_e32 v169, v169, v152
	v_add_f32_e32 v219, v219, v153
	v_permlane32_swap_b32_e32 v192, v194
	ds_read_b64_tr_b16 v[208:209], v182 offset:57344
	ds_read_b64_tr_b16 v[210:211], v182 offset:59392
	v_cvt_pk_bf16_f32 v197, v154, v155
	v_add_f32_e32 v222, v222, v154
	v_add_f32_e32 v254, v254, v155
	v_permlane32_swap_b32_e32 v193, v195
	ds_read_b64_tr_b16 v[212:213], v182 offset:61440
	ds_read_b64_tr_b16 v[214:215], v182 offset:63488
	v_cvt_pk_bf16_f32 v198, v156, v157
	v_add_f32_e32 v169, v169, v156
	v_add_f32_e32 v219, v219, v157
	ds_read_b64_tr_b16 v[230:231], v182 offset:49664
	ds_read_b64_tr_b16 v[232:233], v182 offset:51712
	v_cvt_pk_bf16_f32 v199, v158, v159
	v_add_f32_e32 v222, v222, v158
	v_add_f32_e32 v254, v254, v159
	v_permlane32_swap_b32_e32 v196, v198
	v_permlane32_swap_b32_e32 v197, v199
	s_waitcnt lgkmcnt(8)
	v_mfma_f32_32x32x16_bf16 v[0:15], v[184:187], v[200:203], v[0:15]
	ds_read_b64_tr_b16 v[234:235], v182 offset:53760
	ds_read_b64_tr_b16 v[236:237], v182 offset:55808
	s_waitcnt lgkmcnt(8)
	v_mfma_f32_32x32x16_bf16 v[0:15], v[188:191], v[204:207], v[0:15]
	ds_read_b64_tr_b16 v[238:239], v182 offset:57856
	ds_read_b64_tr_b16 v[240:241], v182 offset:59904
	s_waitcnt lgkmcnt(8)
	v_mfma_f32_32x32x16_bf16 v[0:15], v[192:195], v[208:211], v[0:15]
	ds_read_b64_tr_b16 v[242:243], v182 offset:61952
	ds_read_b64_tr_b16 v[244:245], v182 offset:64000
	s_waitcnt lgkmcnt(8)
	v_mfma_f32_32x32x16_bf16 v[0:15], v[196:199], v[212:215], v[0:15]
	ds_read_b64_tr_b16 v[200:201], v182 offset:50176
	ds_read_b64_tr_b16 v[202:203], v182 offset:52224
	s_waitcnt lgkmcnt(8)
	v_mfma_f32_32x32x16_bf16 v[48:63], v[184:187], v[230:233], v[48:63]
	ds_read_b64_tr_b16 v[204:205], v182 offset:54272
	ds_read_b64_tr_b16 v[206:207], v182 offset:56320
	s_waitcnt lgkmcnt(8)
	v_mfma_f32_32x32x16_bf16 v[48:63], v[188:191], v[234:237], v[48:63]
	ds_read_b64_tr_b16 v[208:209], v182 offset:58368
	ds_read_b64_tr_b16 v[210:211], v182 offset:60416
	s_waitcnt lgkmcnt(8)
	v_mfma_f32_32x32x16_bf16 v[48:63], v[192:195], v[238:241], v[48:63]
	ds_read_b64_tr_b16 v[212:213], v182 offset:62464
	ds_read_b64_tr_b16 v[214:215], v182 offset:64512
	s_waitcnt lgkmcnt(8)
	v_mfma_f32_32x32x16_bf16 v[48:63], v[196:199], v[242:245], v[48:63]
	ds_read_b64_tr_b16 v[230:231], v182 offset:50688
	ds_read_b64_tr_b16 v[232:233], v182 offset:52736
	s_waitcnt lgkmcnt(8)
	v_mfma_f32_32x32x16_bf16 v[32:47], v[184:187], v[200:203], v[32:47]
	ds_read_b64_tr_b16 v[234:235], v182 offset:54784
	ds_read_b64_tr_b16 v[236:237], v182 offset:56832
	s_waitcnt lgkmcnt(8)
	v_mfma_f32_32x32x16_bf16 v[32:47], v[188:191], v[204:207], v[32:47]
	ds_read_b64_tr_b16 v[238:239], v182 offset:58880
	ds_read_b64_tr_b16 v[240:241], v182 offset:60928
	s_waitcnt lgkmcnt(8)
	v_mfma_f32_32x32x16_bf16 v[32:47], v[192:195], v[208:211], v[32:47]
	ds_read_b64_tr_b16 v[242:243], v182 offset:62976
	ds_read_b64_tr_b16 v[244:245], v182 offset:65024
	s_waitcnt lgkmcnt(8)
	v_mfma_f32_32x32x16_bf16 v[32:47], v[196:199], v[212:215], v[32:47]
	s_waitcnt lgkmcnt(6)
	v_mfma_f32_32x32x16_bf16 v[16:31], v[184:187], v[230:233], v[16:31]
	s_waitcnt lgkmcnt(4)
	v_mfma_f32_32x32x16_bf16 v[16:31], v[188:191], v[234:237], v[16:31]
	s_waitcnt lgkmcnt(2)
	v_mfma_f32_32x32x16_bf16 v[16:31], v[192:195], v[238:241], v[16:31]
	s_waitcnt lgkmcnt(0)
	v_mfma_f32_32x32x16_bf16 v[16:31], v[196:199], v[242:245], v[16:31]
	s_waitcnt lgkmcnt(0)
	s_barrier
	v_add_f32_e32 v169, v169, v219
	v_add_f32_e32 v222, v222, v254
	v_add_f32_e32 v169, v169, v222
	v_mov_b32_e32 v219, v169
	s_nop 1
	v_permlane32_swap_b32_e32 v169, v219
	v_add_f32_e32 v64, v169, v219
	v_lshlrev_b32_e32 v164, 4, v229
	v_mov_b32_e32 v165, 0
	s_and_saveexec_b64 s[0:1], s[2:3]
	ds_write_b32 v168, v64
	s_branch .LBB0_477

; __global__ void __launch_bounds__(NWAVES * 64, 2) mk_fwd(Args args) {
	.amdhsa_kernel _Z6mk_fwd4Args
		.amdhsa_group_segment_fixed_size 0
		.amdhsa_private_segment_fixed_size 0
		.amdhsa_kernarg_size 456
		.amdhsa_user_sgpr_count 2
		.amdhsa_user_sgpr_dispatch_ptr 0
		.amdhsa_user_sgpr_queue_ptr 0
		.amdhsa_user_sgpr_kernarg_segment_ptr 1
		.amdhsa_user_sgpr_dispatch_id 0
		.amdhsa_user_sgpr_kernarg_preload_length 0
		.amdhsa_user_sgpr_kernarg_preload_offset 0
		.amdhsa_user_sgpr_private_segment_size 0
		.amdhsa_uses_dynamic_stack 0
		.amdhsa_enable_private_segment 0
		.amdhsa_system_sgpr_workgroup_id_x 1
		.amdhsa_system_sgpr_workgroup_id_y 0
		.amdhsa_system_sgpr_workgroup_id_z 0
		.amdhsa_system_sgpr_workgroup_info 0
		.amdhsa_system_vgpr_workitem_id 2
		.amdhsa_next_free_vgpr 256
		.amdhsa_next_free_sgpr 102
		.amdhsa_accum_offset 256
		.amdhsa_reserve_vcc 1
		.amdhsa_float_round_mode_32 0
		.amdhsa_float_round_mode_16_64 0
		.amdhsa_float_denorm_mode_32 3
		.amdhsa_float_denorm_mode_16_64 3
		.amdhsa_dx10_clamp 1
		.amdhsa_ieee_mode 1
		.amdhsa_fp16_overflow 0
		.amdhsa_tg_split 0
		.amdhsa_exception_fp_ieee_invalid_op 0
		.amdhsa_exception_fp_denorm_src 0
		.amdhsa_exception_fp_ieee_div_zero 0
		.amdhsa_exception_fp_ieee_overflow 0
		.amdhsa_exception_fp_ieee_underflow 0
		.amdhsa_exception_fp_ieee_inexact 0
		.amdhsa_exception_int_div_zero 0
	.end_amdhsa_kernel

; __global__ void __launch_bounds__(NWAVES * 64, 2) mk_fwd(Args args) {
amdhsa.kernels:
  - .agpr_count:     0
    .args:
      - .offset:         0
        .size:           200
        .value_kind:     by_value
      - .offset:         200
        .size:           4
        .value_kind:     hidden_block_count_x
      - .offset:         204
        .size:           4
        .value_kind:     hidden_block_count_y
      - .offset:         208
        .size:           4
        .value_kind:     hidden_block_count_z
      - .offset:         212
        .size:           2
        .value_kind:     hidden_group_size_x
      - .offset:         214
        .size:           2
        .value_kind:     hidden_group_size_y
      - .offset:         216
        .size:           2
        .value_kind:     hidden_group_size_z
      - .offset:         218
        .size:           2
        .value_kind:     hidden_remainder_x
      - .offset:         220
        .size:           2
        .value_kind:     hidden_remainder_y
      - .offset:         222
        .size:           2
        .value_kind:     hidden_remainder_z
      - .offset:         240
        .size:           8
        .value_kind:     hidden_global_offset_x
      - .offset:         248
        .size:           8
        .value_kind:     hidden_global_offset_y
      - .offset:         256
        .size:           8
        .value_kind:     hidden_global_offset_z
      - .offset:         264
        .size:           2
        .value_kind:     hidden_grid_dims
      - .offset:         288
        .size:           8
        .value_kind:     hidden_multigrid_sync_arg
      - .offset:         320
        .size:           4
        .value_kind:     hidden_dynamic_lds_size
    .group_segment_fixed_size: 0
    .kernarg_segment_align: 8
    .kernarg_segment_size: 456
    .language:       OpenCL C
    .language_version:
      - 2
      - 0
    .max_flat_workgroup_size: 512
    .name:           _Z6mk_fwd4Args
    .private_segment_fixed_size: 0
    .sgpr_count:     108
    .sgpr_spill_count: 2
    .symbol:         _Z6mk_fwd4Args.kd
    .uniform_work_group_size: 1
    .uses_dynamic_stack: false
    .vgpr_count:     256
    .vgpr_spill_count: 0
    .wavefront_size: 64
